# DSA attention: per-token LDS table of selected-row byte offsets, shared by the 32 key and 32 value gathers (one ds_read_b32 + add per gather instead of recomputing from sel)
# speedup vs baseline: 1.0211x; 1.0071x over previous
;   __device__ __forceinline__ half_t* mm() const { return (half_t*)(ws() + OFF_mm); }
; __device__ __forceinline__ void dsa_item(const KP& p, int b, int tile, char* smem) {
;     ...
;     const int nsel = min(cnt[tk], 256);
;     const half_t* urow = ub + (size_t)t * NU;
;     const int col = lane & 15;
;     h8 q0, q1;
; #pragma unroll
;     for (int e = 0; e < 8; ++e) { q0[e] = (half_t)0.f; q1[e] = (half_t)0.f; }
;     if (col < 8) {
;       q0 = *(const h8*)(urow + C_BQ + col * 64 + hq * 8);
;       q1 = *(const h8*)(urow + C_BQ + col * 64 + 32 + hq * 8);
;     }
;     float mx = NEGF;
; #pragma unroll 1
;     for (int mg = 0; mg < 2; ++mg) {
; #pragma unroll
;       for (int mm = 0; mm < 8; ++mm) {
;         const int m = mg * 8 + mm;
;         const int pos = m * 16 + col;
;         const int s = (pos < nsel) ? (int)sel[tk * 256 + pos] : 0;
;         const half_t* kp = ub + (size_t)s * NU + C_BK + hq * 8;
;         const h8 a0 = *(const h8*)kp, a1 = *(const h8*)(kp + 32);
;         f32x4 d = {0.f, 0.f, 0.f, 0.f};
;         d = __builtin_amdgcn_mfma_f32_16x16x32_f16(a0, q0, d, 0, 0, 0);
;         d = __builtin_amdgcn_mfma_f32_16x16x32_f16(a1, q1, d, 0, 0, 0);
.LBB0_1427:
	s_or_b64 exec, exec, s[2:3]
	s_waitcnt lgkmcnt(0)
	v_min_i32_e32 v85, 0x100, v11
	v_lshlrev_b32_e32 v14, 9, v10
	v_mov_b32_e32 v15, 0xf149f2ca
	s_add_u32 s14, s78, 0x3800
	s_addc_u32 s15, s79, 0
	v_add_u32_e32 v203, v126, v157
	v_lshl_add_u32 v80, v203, 1, v14
	ds_read_u16 v172, v80 offset:32768
	ds_read_u16 v173, v80 offset:32896
	ds_read_u16 v174, v80 offset:33024
	ds_read_u16 v175, v80 offset:33152
	v_and_b32_e32 v200, 7, v157
	v_lshlrev_b32_e32 v200, 4, v200
	v_mul_u32_u24_e32 v201, 0x240, v159
	v_add_u32_e32 v201, 0xa800, v201
	v_mul_u32_u24_e32 v198, 0x90, v165
	v_add3_u32 v198, v198, v200, v201
	v_mul_u32_u24_e32 v199, 0x90, v157
	v_add3_u32 v199, v199, v126, v201
	v_lshlrev_b32_e32 v202, 8, v159
	v_add_u32_e32 v202, 0xcc00, v202
	v_lshl_add_u32 v81, v203, 2, v202
	v_add_u32_e32 v171, -1, v85
	v_add_u32_e32 v156, -2, v85
	v_add_u32_e32 v158, -3, v85
	v_cmp_lt_i32_e32 vcc, v203, v85
	s_waitcnt lgkmcnt(3)
	s_nop 0
	v_cndmask_b32_e32 v172, 0, v172, vcc
	v_mul_u32_u24_e32 v172, 0x3a00, v172
	ds_write_b32 v81, v172
	v_add_u32_e32 v201, 64, v203
	v_cmp_lt_i32_e32 vcc, v201, v85
	s_waitcnt lgkmcnt(2)
	s_nop 0
	v_cndmask_b32_e32 v173, 0, v173, vcc
	v_mul_u32_u24_e32 v173, 0x3a00, v173
	ds_write_b32 v81, v173 offset:256
	v_add_u32_e32 v201, 0x80, v203
	v_cmp_lt_i32_e32 vcc, v201, v85
	s_waitcnt lgkmcnt(1)
	s_nop 0
	v_cndmask_b32_e32 v174, 0, v174, vcc
	v_mul_u32_u24_e32 v174, 0x3a00, v174
	ds_write_b32 v81, v174 offset:512
	v_add_u32_e32 v201, 0xc0, v203
	v_cmp_lt_i32_e32 vcc, v201, v85
	s_waitcnt lgkmcnt(0)
	s_nop 0
	v_cndmask_b32_e32 v175, 0, v175, vcc
	v_mul_u32_u24_e32 v175, 0x3a00, v175
	ds_write_b32 v81, v175 offset:768
	v_lshl_add_u32 v202, v165, 2, v202
	ds_read_b32 v172, v202
	ds_read_b32 v173, v202 offset:64
	ds_read_b32 v174, v202 offset:128
	ds_read_b32 v175, v202 offset:192
	ds_read_b32 v176, v202 offset:256
	ds_read_b32 v177, v202 offset:320
	ds_read_b32 v178, v202 offset:384
	ds_read_b32 v179, v202 offset:448
	ds_read_b32 v180, v202 offset:512
	ds_read_b32 v181, v202 offset:576
	ds_read_b32 v188, v202 offset:640
	ds_read_b32 v189, v202 offset:704
	ds_read_b32 v190, v202 offset:768
	ds_read_b32 v191, v202 offset:832
	ds_read_b32 v192, v202 offset:896
	ds_read_b32 v193, v202 offset:960
	s_waitcnt lgkmcnt(15)
	v_add_u32_e32 v172, v172, v200
	global_load_dwordx4 v[16:19], v172, s[14:15]
	s_waitcnt lgkmcnt(14)
	v_add_u32_e32 v173, v173, v200
	global_load_dwordx4 v[24:27], v173, s[14:15]
	s_waitcnt lgkmcnt(13)
	v_add_u32_e32 v174, v174, v200
	global_load_dwordx4 v[32:35], v174, s[14:15]
	s_waitcnt lgkmcnt(12)
	v_add_u32_e32 v175, v175, v200
	global_load_dwordx4 v[40:43], v175, s[14:15]
	s_waitcnt lgkmcnt(11)
	v_add_u32_e32 v176, v176, v200
	global_load_dwordx4 v[48:51], v176, s[14:15]
	s_waitcnt lgkmcnt(10)
	v_add_u32_e32 v177, v177, v200
	global_load_dwordx4 v[56:59], v177, s[14:15]
	s_waitcnt lgkmcnt(9)
	v_add_u32_e32 v178, v178, v200
	global_load_dwordx4 v[64:67], v178, s[14:15]
	s_waitcnt lgkmcnt(8)
	v_add_u32_e32 v179, v179, v200
	global_load_dwordx4 v[72:75], v179, s[14:15]
	s_waitcnt lgkmcnt(7)
	v_add_u32_e32 v180, v180, v200
	global_load_dwordx4 v[90:93], v180, s[14:15]
	s_waitcnt lgkmcnt(6)
	v_add_u32_e32 v181, v181, v200
	global_load_dwordx4 v[98:101], v181, s[14:15]
	s_waitcnt lgkmcnt(5)
	v_add_u32_e32 v188, v188, v200
	global_load_dwordx4 v[106:109], v188, s[14:15]
	s_waitcnt lgkmcnt(4)
	v_add_u32_e32 v189, v189, v200
	global_load_dwordx4 v[114:117], v189, s[14:15]
	s_waitcnt lgkmcnt(3)
	v_add_u32_e32 v190, v190, v200
	global_load_dwordx4 v[122:125], v190, s[14:15]
	s_waitcnt lgkmcnt(2)
	v_add_u32_e32 v191, v191, v200
	global_load_dwordx4 v[132:135], v191, s[14:15]
	s_waitcnt lgkmcnt(1)
	v_add_u32_e32 v192, v192, v200
	global_load_dwordx4 v[140:143], v192, s[14:15]
	s_waitcnt lgkmcnt(0)
	v_add_u32_e32 v193, v193, v200
	global_load_dwordx4 v[148:151], v193, s[14:15]
	ds_read_b32 v172, v202 offset:32
	ds_read_b32 v173, v202 offset:96
	ds_read_b32 v174, v202 offset:160
	ds_read_b32 v175, v202 offset:224
	ds_read_b32 v176, v202 offset:288
	ds_read_b32 v177, v202 offset:352
	ds_read_b32 v178, v202 offset:416
	ds_read_b32 v179, v202 offset:480
	ds_read_b32 v180, v202 offset:544
	ds_read_b32 v181, v202 offset:608
	ds_read_b32 v188, v202 offset:672
	ds_read_b32 v189, v202 offset:736
	ds_read_b32 v190, v202 offset:800
	ds_read_b32 v191, v202 offset:864
	ds_read_b32 v192, v202 offset:928
	ds_read_b32 v193, v202 offset:992
	s_waitcnt lgkmcnt(15)
	v_add_u32_e32 v172, v172, v200
	global_load_dwordx4 v[20:23], v172, s[14:15]
	s_waitcnt lgkmcnt(14)
	v_add_u32_e32 v173, v173, v200
	global_load_dwordx4 v[28:31], v173, s[14:15]
	s_waitcnt lgkmcnt(13)
	v_add_u32_e32 v174, v174, v200
	global_load_dwordx4 v[36:39], v174, s[14:15]
	s_waitcnt lgkmcnt(12)
	v_add_u32_e32 v175, v175, v200
	global_load_dwordx4 v[44:47], v175, s[14:15]
	s_waitcnt lgkmcnt(11)
	v_add_u32_e32 v176, v176, v200
	global_load_dwordx4 v[52:55], v176, s[14:15]
	s_waitcnt lgkmcnt(10)
	v_add_u32_e32 v177, v177, v200
	global_load_dwordx4 v[60:63], v177, s[14:15]
	s_waitcnt lgkmcnt(9)
	v_add_u32_e32 v178, v178, v200
	global_load_dwordx4 v[68:71], v178, s[14:15]
	s_waitcnt lgkmcnt(8)
	v_add_u32_e32 v179, v179, v200
	global_load_dwordx4 v[76:79], v179, s[14:15]
	s_waitcnt lgkmcnt(7)
	v_add_u32_e32 v180, v180, v200
	global_load_dwordx4 v[94:97], v180, s[14:15]
	s_waitcnt lgkmcnt(6)
	v_add_u32_e32 v181, v181, v200
	global_load_dwordx4 v[102:105], v181, s[14:15]
	s_waitcnt lgkmcnt(5)
	v_add_u32_e32 v188, v188, v200
	global_load_dwordx4 v[110:113], v188, s[14:15]
	s_waitcnt lgkmcnt(4)
	v_add_u32_e32 v189, v189, v200
	global_load_dwordx4 v[118:121], v189, s[14:15]
	s_waitcnt lgkmcnt(3)
;   __device__ __forceinline__ half_t* mm() const { return (half_t*)(ws() + OFF_mm); }
; __device__ __forceinline__ void dsa_item(const KP& p, int b, int tile, char* smem) {
;     ...
;       for (int mm = 0; mm < 8; ++mm) {
;         const int m = mg * 8 + mm;
;         const int pos = m * 16 + col;
;         const int s = (pos < nsel) ? (int)sel[tk * 256 + pos] : 0;
;         const half_t* kp = ub + (size_t)s * NU + C_BK + hq * 8;
;         const h8 a0 = *(const h8*)kp, a1 = *(const h8*)(kp + 32);
;         f32x4 d = {0.f, 0.f, 0.f, 0.f};
;         d = __builtin_amdgcn_mfma_f32_16x16x32_f16(a0, q0, d, 0, 0, 0);
;         d = __builtin_amdgcn_mfma_f32_16x16x32_f16(a1, q1, d, 0, 0, 0);
; #pragma unroll
;         for (int r = 0; r < 4; ++r) {
;           const int pp = m * 16 + hq * 4 + r;
;           const float v = (pp < nsel) ? d[r] * 0.125f : NEGF;
;           mx = fmaxf(mx, v);
;           if (col < 8) pbuf[pp * 8 + col] = v;
;         }
;       }
	v_add_u32_e32 v190, v190, v200
	global_load_dwordx4 v[128:131], v190, s[14:15]
	s_waitcnt lgkmcnt(2)
	v_add_u32_e32 v191, v191, v200
	global_load_dwordx4 v[136:139], v191, s[14:15]
	s_waitcnt lgkmcnt(1)
	v_add_u32_e32 v192, v192, v200
	global_load_dwordx4 v[144:147], v192, s[14:15]
	s_waitcnt lgkmcnt(0)
	v_add_u32_e32 v193, v193, v200
	global_load_dwordx4 v[152:155], v193, s[14:15]
	s_waitcnt vmcnt(15)
	ds_write_b128 v198, v[16:19]
	ds_write_b128 v198, v[20:23] offset:1152
	ds_read_b128 v[16:19], v199
	ds_read_b128 v[20:23], v199 offset:64
	s_waitcnt vmcnt(14)
	ds_write_b128 v198, v[24:27]
	ds_write_b128 v198, v[28:31] offset:1152
	ds_read_b128 v[24:27], v199
	ds_read_b128 v[28:31], v199 offset:64
	s_waitcnt lgkmcnt(4)
	v_mfma_f32_16x16x32_f16 v[10:13], v[16:19], v[6:9], 0
	v_mfma_f32_16x16x32_f16 v[10:13], v[20:23], v[2:5], v[10:13]
	s_nop 4
	s_waitcnt vmcnt(13)
	ds_write_b128 v198, v[32:35]
	ds_write_b128 v198, v[36:39] offset:1152
	ds_read_b128 v[32:35], v199
	ds_read_b128 v[36:39], v199 offset:64
	s_waitcnt lgkmcnt(4)
	v_mfma_f32_16x16x32_f16 v[194:197], v[24:27], v[6:9], 0
	v_mfma_f32_16x16x32_f16 v[194:197], v[28:31], v[2:5], v[194:197]
	v_or_b32_e32 v80, 0, v160
	v_mul_f32_e32 v10, 0x3e000000, v10
	v_mul_f32_e32 v11, 0x3e000000, v11
	v_mul_f32_e32 v12, 0x3e000000, v12
	v_mul_f32_e32 v13, 0x3e000000, v13
	v_cmp_lt_i32_e32 vcc, v80, v85
	v_cmp_lt_i32_e64 s[46:47], v80, v171
	v_lshl_add_u32 v81, v80, 5, v167
	s_nop 0
	v_cndmask_b32_e32 v10, v242, v10, vcc
	v_cndmask_b32_e64 v11, v242, v11, s[46:47]
	v_cmp_lt_i32_e32 vcc, v80, v156
	v_cmp_lt_i32_e64 s[46:47], v80, v158
	v_max3_f32 v15, v15, v10, v11
	s_nop 0
	v_cndmask_b32_e32 v12, v242, v12, vcc
	v_cndmask_b32_e64 v13, v242, v13, s[46:47]
	v_max3_f32 v15, v15, v12, v13
	s_and_saveexec_b64 s[2:3], s[38:39]
	ds_write_b32 v81, v10
	ds_write_b32 v81, v11 offset:32
	ds_write_b32 v81, v12 offset:64
	ds_write_b32 v81, v13 offset:96
	s_or_b64 exec, exec, s[2:3]
	s_waitcnt vmcnt(12)
	ds_write_b128 v198, v[40:43]
	ds_write_b128 v198, v[44:47] offset:1152
	ds_read_b128 v[40:43], v199
	ds_read_b128 v[44:47], v199 offset:64
	s_waitcnt lgkmcnt(8)
	v_mfma_f32_16x16x32_f16 v[10:13], v[32:35], v[6:9], 0
	v_mfma_f32_16x16x32_f16 v[10:13], v[36:39], v[2:5], v[10:13]
	v_or_b32_e32 v80, 16, v160
	v_mul_f32_e32 v194, 0x3e000000, v194
	v_mul_f32_e32 v195, 0x3e000000, v195
	v_mul_f32_e32 v196, 0x3e000000, v196
	v_mul_f32_e32 v197, 0x3e000000, v197
	v_cmp_lt_i32_e32 vcc, v80, v85
	v_cmp_lt_i32_e64 s[46:47], v80, v171
	v_lshl_add_u32 v81, v80, 5, v167
	s_nop 0
	v_cndmask_b32_e32 v194, v242, v194, vcc
	v_cndmask_b32_e64 v195, v242, v195, s[46:47]
	v_cmp_lt_i32_e32 vcc, v80, v156
	v_cmp_lt_i32_e64 s[46:47], v80, v158
	v_max3_f32 v15, v15, v194, v195
	s_nop 0
	v_cndmask_b32_e32 v196, v242, v196, vcc
	v_cndmask_b32_e64 v197, v242, v197, s[46:47]
	v_max3_f32 v15, v15, v196, v197
	s_and_saveexec_b64 s[2:3], s[38:39]
	ds_write_b32 v81, v194
	ds_write_b32 v81, v195 offset:32
	ds_write_b32 v81, v196 offset:64
	ds_write_b32 v81, v197 offset:96
	s_or_b64 exec, exec, s[2:3]
	s_waitcnt vmcnt(11)
	ds_write_b128 v198, v[48:51]
	ds_write_b128 v198, v[52:55] offset:1152
	ds_read_b128 v[48:51], v199
	ds_read_b128 v[52:55], v199 offset:64
	s_waitcnt lgkmcnt(8)
	v_mfma_f32_16x16x32_f16 v[194:197], v[40:43], v[6:9], 0
	v_mfma_f32_16x16x32_f16 v[194:197], v[44:47], v[2:5], v[194:197]
	v_or_b32_e32 v80, 32, v160
	v_mul_f32_e32 v10, 0x3e000000, v10
	v_mul_f32_e32 v11, 0x3e000000, v11
	v_mul_f32_e32 v12, 0x3e000000, v12
	v_mul_f32_e32 v13, 0x3e000000, v13
	v_cmp_lt_i32_e32 vcc, v80, v85
	v_cmp_lt_i32_e64 s[46:47], v80, v171
	v_lshl_add_u32 v81, v80, 5, v167
	s_nop 0
	v_cndmask_b32_e32 v10, v242, v10, vcc
	v_cndmask_b32_e64 v11, v242, v11, s[46:47]
	v_cmp_lt_i32_e32 vcc, v80, v156
	v_cmp_lt_i32_e64 s[46:47], v80, v158
	v_max3_f32 v15, v15, v10, v11
	s_nop 0
	v_cndmask_b32_e32 v12, v242, v12, vcc
	v_cndmask_b32_e64 v13, v242, v13, s[46:47]
	v_max3_f32 v15, v15, v12, v13
	s_and_saveexec_b64 s[2:3], s[38:39]
	ds_write_b32 v81, v10
	ds_write_b32 v81, v11 offset:32
	ds_write_b32 v81, v12 offset:64
	ds_write_b32 v81, v13 offset:96
	s_or_b64 exec, exec, s[2:3]
	s_waitcnt vmcnt(10)
	ds_write_b128 v198, v[56:59]
	ds_write_b128 v198, v[60:63] offset:1152
	ds_read_b128 v[56:59], v199
	ds_read_b128 v[60:63], v199 offset:64
	s_waitcnt lgkmcnt(8)
	v_mfma_f32_16x16x32_f16 v[10:13], v[48:51], v[6:9], 0
	v_mfma_f32_16x16x32_f16 v[10:13], v[52:55], v[2:5], v[10:13]
	v_or_b32_e32 v80, 48, v160
	v_mul_f32_e32 v194, 0x3e000000, v194
	v_mul_f32_e32 v195, 0x3e000000, v195
	v_mul_f32_e32 v196, 0x3e000000, v196
	v_mul_f32_e32 v197, 0x3e000000, v197
	v_cmp_lt_i32_e32 vcc, v80, v85
	v_cmp_lt_i32_e64 s[46:47], v80, v171
	v_lshl_add_u32 v81, v80, 5, v167
	s_nop 0
	v_cndmask_b32_e32 v194, v242, v194, vcc
	v_cndmask_b32_e64 v195, v242, v195, s[46:47]
	v_cmp_lt_i32_e32 vcc, v80, v156
	v_cmp_lt_i32_e64 s[46:47], v80, v158
	v_max3_f32 v15, v15, v194, v195
	s_nop 0
	v_cndmask_b32_e32 v196, v242, v196, vcc
	v_cndmask_b32_e64 v197, v242, v197, s[46:47]
	v_max3_f32 v15, v15, v196, v197
	s_and_saveexec_b64 s[2:3], s[38:39]
	ds_write_b32 v81, v194
	ds_write_b32 v81, v195 offset:32
	ds_write_b32 v81, v196 offset:64
	ds_write_b32 v81, v197 offset:96
	s_or_b64 exec, exec, s[2:3]
	s_waitcnt vmcnt(9)
	ds_write_b128 v198, v[64:67]
	ds_write_b128 v198, v[68:71] offset:1152
	ds_read_b128 v[64:67], v199
	ds_read_b128 v[68:71], v199 offset:64
	s_waitcnt lgkmcnt(8)
;   __device__ __forceinline__ half_t* mm() const { return (half_t*)(ws() + OFF_mm); }
; __device__ __forceinline__ void dsa_item(const KP& p, int b, int tile, char* smem) {
;     ...
;       for (int mm = 0; mm < 8; ++mm) {
;         const int m = mg * 8 + mm;
;         const int pos = m * 16 + col;
;         const int s = (pos < nsel) ? (int)sel[tk * 256 + pos] : 0;
;         const half_t* kp = ub + (size_t)s * NU + C_BK + hq * 8;
;         const h8 a0 = *(const h8*)kp, a1 = *(const h8*)(kp + 32);
;         f32x4 d = {0.f, 0.f, 0.f, 0.f};
;         d = __builtin_amdgcn_mfma_f32_16x16x32_f16(a0, q0, d, 0, 0, 0);
;         d = __builtin_amdgcn_mfma_f32_16x16x32_f16(a1, q1, d, 0, 0, 0);
; #pragma unroll
;         for (int r = 0; r < 4; ++r) {
;           const int pp = m * 16 + hq * 4 + r;
;           const float v = (pp < nsel) ? d[r] * 0.125f : NEGF;
;           mx = fmaxf(mx, v);
;           if (col < 8) pbuf[pp * 8 + col] = v;
;         }
;       }
	v_mfma_f32_16x16x32_f16 v[194:197], v[56:59], v[6:9], 0
	v_mfma_f32_16x16x32_f16 v[194:197], v[60:63], v[2:5], v[194:197]
	v_or_b32_e32 v80, 64, v160
	v_mul_f32_e32 v10, 0x3e000000, v10
	v_mul_f32_e32 v11, 0x3e000000, v11
	v_mul_f32_e32 v12, 0x3e000000, v12
	v_mul_f32_e32 v13, 0x3e000000, v13
	v_cmp_lt_i32_e32 vcc, v80, v85
	v_cmp_lt_i32_e64 s[46:47], v80, v171
	v_lshl_add_u32 v81, v80, 5, v167
	s_nop 0
	v_cndmask_b32_e32 v10, v242, v10, vcc
	v_cndmask_b32_e64 v11, v242, v11, s[46:47]
	v_cmp_lt_i32_e32 vcc, v80, v156
	v_cmp_lt_i32_e64 s[46:47], v80, v158
	v_max3_f32 v15, v15, v10, v11
	s_nop 0
	v_cndmask_b32_e32 v12, v242, v12, vcc
	v_cndmask_b32_e64 v13, v242, v13, s[46:47]
	v_max3_f32 v15, v15, v12, v13
	s_and_saveexec_b64 s[2:3], s[38:39]
	ds_write_b32 v81, v10
	ds_write_b32 v81, v11 offset:32
	ds_write_b32 v81, v12 offset:64
	ds_write_b32 v81, v13 offset:96
	s_or_b64 exec, exec, s[2:3]
	s_waitcnt vmcnt(8)
	ds_write_b128 v198, v[72:75]
	ds_write_b128 v198, v[76:79] offset:1152
	ds_read_b128 v[72:75], v199
	ds_read_b128 v[76:79], v199 offset:64
	s_waitcnt lgkmcnt(8)
	v_mfma_f32_16x16x32_f16 v[10:13], v[64:67], v[6:9], 0
	v_mfma_f32_16x16x32_f16 v[10:13], v[68:71], v[2:5], v[10:13]
	v_or_b32_e32 v80, 0x50, v160
	v_mul_f32_e32 v194, 0x3e000000, v194
	v_mul_f32_e32 v195, 0x3e000000, v195
	v_mul_f32_e32 v196, 0x3e000000, v196
	v_mul_f32_e32 v197, 0x3e000000, v197
	v_cmp_lt_i32_e32 vcc, v80, v85
	v_cmp_lt_i32_e64 s[46:47], v80, v171
	v_lshl_add_u32 v81, v80, 5, v167
	s_nop 0
	v_cndmask_b32_e32 v194, v242, v194, vcc
	v_cndmask_b32_e64 v195, v242, v195, s[46:47]
	v_cmp_lt_i32_e32 vcc, v80, v156
	v_cmp_lt_i32_e64 s[46:47], v80, v158
	v_max3_f32 v15, v15, v194, v195
	s_nop 0
	v_cndmask_b32_e32 v196, v242, v196, vcc
	v_cndmask_b32_e64 v197, v242, v197, s[46:47]
	v_max3_f32 v15, v15, v196, v197
	s_and_saveexec_b64 s[2:3], s[38:39]
	ds_write_b32 v81, v194
	ds_write_b32 v81, v195 offset:32
	ds_write_b32 v81, v196 offset:64
	ds_write_b32 v81, v197 offset:96
	s_or_b64 exec, exec, s[2:3]
	s_waitcnt vmcnt(7)
	ds_write_b128 v198, v[90:93]
	ds_write_b128 v198, v[94:97] offset:1152
	ds_read_b128 v[90:93], v199
	ds_read_b128 v[94:97], v199 offset:64
	s_waitcnt lgkmcnt(8)
	v_mfma_f32_16x16x32_f16 v[194:197], v[72:75], v[6:9], 0
	v_mfma_f32_16x16x32_f16 v[194:197], v[76:79], v[2:5], v[194:197]
	v_or_b32_e32 v80, 0x60, v160
	v_mul_f32_e32 v10, 0x3e000000, v10
	v_mul_f32_e32 v11, 0x3e000000, v11
	v_mul_f32_e32 v12, 0x3e000000, v12
	v_mul_f32_e32 v13, 0x3e000000, v13
	v_cmp_lt_i32_e32 vcc, v80, v85
	v_cmp_lt_i32_e64 s[46:47], v80, v171
	v_lshl_add_u32 v81, v80, 5, v167
	s_nop 0
	v_cndmask_b32_e32 v10, v242, v10, vcc
	v_cndmask_b32_e64 v11, v242, v11, s[46:47]
	v_cmp_lt_i32_e32 vcc, v80, v156
	v_cmp_lt_i32_e64 s[46:47], v80, v158
	v_max3_f32 v15, v15, v10, v11
	s_nop 0
	v_cndmask_b32_e32 v12, v242, v12, vcc
	v_cndmask_b32_e64 v13, v242, v13, s[46:47]
	v_max3_f32 v15, v15, v12, v13
	s_and_saveexec_b64 s[2:3], s[38:39]
	ds_write_b32 v81, v10
	ds_write_b32 v81, v11 offset:32
	ds_write_b32 v81, v12 offset:64
	ds_write_b32 v81, v13 offset:96
	s_or_b64 exec, exec, s[2:3]
	s_waitcnt vmcnt(6)
	ds_write_b128 v198, v[98:101]
	ds_write_b128 v198, v[102:105] offset:1152
	ds_read_b128 v[98:101], v199
	ds_read_b128 v[102:105], v199 offset:64
	s_waitcnt lgkmcnt(8)
	v_mfma_f32_16x16x32_f16 v[10:13], v[90:93], v[6:9], 0
	v_mfma_f32_16x16x32_f16 v[10:13], v[94:97], v[2:5], v[10:13]
	v_or_b32_e32 v80, 0x70, v160
	v_mul_f32_e32 v194, 0x3e000000, v194
	v_mul_f32_e32 v195, 0x3e000000, v195
	v_mul_f32_e32 v196, 0x3e000000, v196
	v_mul_f32_e32 v197, 0x3e000000, v197
	v_cmp_lt_i32_e32 vcc, v80, v85
	v_cmp_lt_i32_e64 s[46:47], v80, v171
	v_lshl_add_u32 v81, v80, 5, v167
	s_nop 0
	v_cndmask_b32_e32 v194, v242, v194, vcc
	v_cndmask_b32_e64 v195, v242, v195, s[46:47]
	v_cmp_lt_i32_e32 vcc, v80, v156
	v_cmp_lt_i32_e64 s[46:47], v80, v158
	v_max3_f32 v15, v15, v194, v195
	s_nop 0
	v_cndmask_b32_e32 v196, v242, v196, vcc
	v_cndmask_b32_e64 v197, v242, v197, s[46:47]
	v_max3_f32 v15, v15, v196, v197
	s_and_saveexec_b64 s[2:3], s[38:39]
	ds_write_b32 v81, v194
	ds_write_b32 v81, v195 offset:32
	ds_write_b32 v81, v196 offset:64
	ds_write_b32 v81, v197 offset:96
	s_or_b64 exec, exec, s[2:3]
	s_waitcnt vmcnt(5)
	ds_write_b128 v198, v[106:109]
	ds_write_b128 v198, v[110:113] offset:1152
	ds_read_b128 v[106:109], v199
	ds_read_b128 v[110:113], v199 offset:64
	s_waitcnt lgkmcnt(8)
	v_mfma_f32_16x16x32_f16 v[194:197], v[98:101], v[6:9], 0
	v_mfma_f32_16x16x32_f16 v[194:197], v[102:105], v[2:5], v[194:197]
	v_or_b32_e32 v80, 0x80, v160
	v_mul_f32_e32 v10, 0x3e000000, v10
	v_mul_f32_e32 v11, 0x3e000000, v11
	v_mul_f32_e32 v12, 0x3e000000, v12
	v_mul_f32_e32 v13, 0x3e000000, v13
	v_cmp_lt_i32_e32 vcc, v80, v85
	v_cmp_lt_i32_e64 s[46:47], v80, v171
	v_lshl_add_u32 v81, v80, 5, v167
	s_nop 0
	v_cndmask_b32_e32 v10, v242, v10, vcc
	v_cndmask_b32_e64 v11, v242, v11, s[46:47]
	v_cmp_lt_i32_e32 vcc, v80, v156
	v_cmp_lt_i32_e64 s[46:47], v80, v158
	v_max3_f32 v15, v15, v10, v11
	s_nop 0
	v_cndmask_b32_e32 v12, v242, v12, vcc
	v_cndmask_b32_e64 v13, v242, v13, s[46:47]
	v_max3_f32 v15, v15, v12, v13
	s_and_saveexec_b64 s[2:3], s[38:39]
	ds_write_b32 v81, v10
	ds_write_b32 v81, v11 offset:32
	ds_write_b32 v81, v12 offset:64
	ds_write_b32 v81, v13 offset:96
	s_or_b64 exec, exec, s[2:3]
	s_waitcnt vmcnt(4)
	ds_write_b128 v198, v[114:117]
	ds_write_b128 v198, v[118:121] offset:1152
	ds_read_b128 v[114:117], v199
	ds_read_b128 v[118:121], v199 offset:64
	s_waitcnt lgkmcnt(8)
;   __device__ __forceinline__ half_t* mm() const { return (half_t*)(ws() + OFF_mm); }
; __device__ __forceinline__ void dsa_item(const KP& p, int b, int tile, char* smem) {
;     ...
;       for (int mm = 0; mm < 8; ++mm) {
;         const int m = mg * 8 + mm;
;         const int pos = m * 16 + col;
;         const int s = (pos < nsel) ? (int)sel[tk * 256 + pos] : 0;
;         const half_t* kp = ub + (size_t)s * NU + C_BK + hq * 8;
;         const h8 a0 = *(const h8*)kp, a1 = *(const h8*)(kp + 32);
;         f32x4 d = {0.f, 0.f, 0.f, 0.f};
;         d = __builtin_amdgcn_mfma_f32_16x16x32_f16(a0, q0, d, 0, 0, 0);
;         d = __builtin_amdgcn_mfma_f32_16x16x32_f16(a1, q1, d, 0, 0, 0);
; #pragma unroll
;         for (int r = 0; r < 4; ++r) {
;           const int pp = m * 16 + hq * 4 + r;
;           const float v = (pp < nsel) ? d[r] * 0.125f : NEGF;
;           mx = fmaxf(mx, v);
;           if (col < 8) pbuf[pp * 8 + col] = v;
;         }
;       }
	v_mfma_f32_16x16x32_f16 v[10:13], v[106:109], v[6:9], 0
	v_mfma_f32_16x16x32_f16 v[10:13], v[110:113], v[2:5], v[10:13]
	v_or_b32_e32 v80, 0x90, v160
	v_mul_f32_e32 v194, 0x3e000000, v194
	v_mul_f32_e32 v195, 0x3e000000, v195
	v_mul_f32_e32 v196, 0x3e000000, v196
	v_mul_f32_e32 v197, 0x3e000000, v197
	v_cmp_lt_i32_e32 vcc, v80, v85
	v_cmp_lt_i32_e64 s[46:47], v80, v171
	v_lshl_add_u32 v81, v80, 5, v167
	s_nop 0
	v_cndmask_b32_e32 v194, v242, v194, vcc
	v_cndmask_b32_e64 v195, v242, v195, s[46:47]
	v_cmp_lt_i32_e32 vcc, v80, v156
	v_cmp_lt_i32_e64 s[46:47], v80, v158
	v_max3_f32 v15, v15, v194, v195
	s_nop 0
	v_cndmask_b32_e32 v196, v242, v196, vcc
	v_cndmask_b32_e64 v197, v242, v197, s[46:47]
	v_max3_f32 v15, v15, v196, v197
	s_and_saveexec_b64 s[2:3], s[38:39]
	ds_write_b32 v81, v194
	ds_write_b32 v81, v195 offset:32
	ds_write_b32 v81, v196 offset:64
	ds_write_b32 v81, v197 offset:96
	s_or_b64 exec, exec, s[2:3]
	s_waitcnt vmcnt(3)
	ds_write_b128 v198, v[122:125]
	ds_write_b128 v198, v[128:131] offset:1152
	ds_read_b128 v[122:125], v199
	ds_read_b128 v[128:131], v199 offset:64
	s_waitcnt lgkmcnt(8)
	v_mfma_f32_16x16x32_f16 v[194:197], v[114:117], v[6:9], 0
	v_mfma_f32_16x16x32_f16 v[194:197], v[118:121], v[2:5], v[194:197]
	v_or_b32_e32 v80, 0xa0, v160
	v_mul_f32_e32 v10, 0x3e000000, v10
	v_mul_f32_e32 v11, 0x3e000000, v11
	v_mul_f32_e32 v12, 0x3e000000, v12
	v_mul_f32_e32 v13, 0x3e000000, v13
	v_cmp_lt_i32_e32 vcc, v80, v85
	v_cmp_lt_i32_e64 s[46:47], v80, v171
	v_lshl_add_u32 v81, v80, 5, v167
	s_nop 0
	v_cndmask_b32_e32 v10, v242, v10, vcc
	v_cndmask_b32_e64 v11, v242, v11, s[46:47]
	v_cmp_lt_i32_e32 vcc, v80, v156
	v_cmp_lt_i32_e64 s[46:47], v80, v158
	v_max3_f32 v15, v15, v10, v11
	s_nop 0
	v_cndmask_b32_e32 v12, v242, v12, vcc
	v_cndmask_b32_e64 v13, v242, v13, s[46:47]
	v_max3_f32 v15, v15, v12, v13
	s_and_saveexec_b64 s[2:3], s[38:39]
	ds_write_b32 v81, v10
	ds_write_b32 v81, v11 offset:32
	ds_write_b32 v81, v12 offset:64
	ds_write_b32 v81, v13 offset:96
	s_or_b64 exec, exec, s[2:3]
	s_waitcnt vmcnt(2)
	ds_write_b128 v198, v[132:135]
	ds_write_b128 v198, v[136:139] offset:1152
	ds_read_b128 v[132:135], v199
	ds_read_b128 v[136:139], v199 offset:64
	s_waitcnt lgkmcnt(8)
	v_mfma_f32_16x16x32_f16 v[10:13], v[122:125], v[6:9], 0
	v_mfma_f32_16x16x32_f16 v[10:13], v[128:131], v[2:5], v[10:13]
	v_or_b32_e32 v80, 0xb0, v160
	v_mul_f32_e32 v194, 0x3e000000, v194
	v_mul_f32_e32 v195, 0x3e000000, v195
	v_mul_f32_e32 v196, 0x3e000000, v196
	v_mul_f32_e32 v197, 0x3e000000, v197
	v_cmp_lt_i32_e32 vcc, v80, v85
	v_cmp_lt_i32_e64 s[46:47], v80, v171
	v_lshl_add_u32 v81, v80, 5, v167
	s_nop 0
	v_cndmask_b32_e32 v194, v242, v194, vcc
	v_cndmask_b32_e64 v195, v242, v195, s[46:47]
	v_cmp_lt_i32_e32 vcc, v80, v156
	v_cmp_lt_i32_e64 s[46:47], v80, v158
	v_max3_f32 v15, v15, v194, v195
	s_nop 0
	v_cndmask_b32_e32 v196, v242, v196, vcc
	v_cndmask_b32_e64 v197, v242, v197, s[46:47]
	v_max3_f32 v15, v15, v196, v197
	s_and_saveexec_b64 s[2:3], s[38:39]
	ds_write_b32 v81, v194
	ds_write_b32 v81, v195 offset:32
	ds_write_b32 v81, v196 offset:64
	ds_write_b32 v81, v197 offset:96
	s_or_b64 exec, exec, s[2:3]
	s_waitcnt vmcnt(1)
	ds_write_b128 v198, v[140:143]
	ds_write_b128 v198, v[144:147] offset:1152
	ds_read_b128 v[140:143], v199
	ds_read_b128 v[144:147], v199 offset:64
	s_waitcnt lgkmcnt(8)
;   __device__ __forceinline__ half_t* mm() const { return (half_t*)(ws() + OFF_mm); }
; __device__ __forceinline__ void dsa_item(const KP& p, int b, int tile, char* smem) {
;     ...
;       for (int mm = 0; mm < 8; ++mm) {
;         const int m = mg * 8 + mm;
;         const int pos = m * 16 + col;
;         const int s = (pos < nsel) ? (int)sel[tk * 256 + pos] : 0;
;         const half_t* kp = ub + (size_t)s * NU + C_BK + hq * 8;
;         const h8 a0 = *(const h8*)kp, a1 = *(const h8*)(kp + 32);
;         f32x4 d = {0.f, 0.f, 0.f, 0.f};
;         d = __builtin_amdgcn_mfma_f32_16x16x32_f16(a0, q0, d, 0, 0, 0);
;         d = __builtin_amdgcn_mfma_f32_16x16x32_f16(a1, q1, d, 0, 0, 0);
; #pragma unroll
;         for (int r = 0; r < 4; ++r) {
;           const int pp = m * 16 + hq * 4 + r;
;           const float v = (pp < nsel) ? d[r] * 0.125f : NEGF;
;           mx = fmaxf(mx, v);
;           if (col < 8) pbuf[pp * 8 + col] = v;
;         }
;       }
	v_mfma_f32_16x16x32_f16 v[194:197], v[132:135], v[6:9], 0
	v_mfma_f32_16x16x32_f16 v[194:197], v[136:139], v[2:5], v[194:197]
	v_or_b32_e32 v80, 0xc0, v160
	v_mul_f32_e32 v10, 0x3e000000, v10
	v_mul_f32_e32 v11, 0x3e000000, v11
	v_mul_f32_e32 v12, 0x3e000000, v12
	v_mul_f32_e32 v13, 0x3e000000, v13
	v_cmp_lt_i32_e32 vcc, v80, v85
	v_cmp_lt_i32_e64 s[46:47], v80, v171
	v_lshl_add_u32 v81, v80, 5, v167
	s_nop 0
	v_cndmask_b32_e32 v10, v242, v10, vcc
	v_cndmask_b32_e64 v11, v242, v11, s[46:47]
	v_cmp_lt_i32_e32 vcc, v80, v156
	v_cmp_lt_i32_e64 s[46:47], v80, v158
	v_max3_f32 v15, v15, v10, v11
	s_nop 0
	v_cndmask_b32_e32 v12, v242, v12, vcc
	v_cndmask_b32_e64 v13, v242, v13, s[46:47]
	v_max3_f32 v15, v15, v12, v13
	s_and_saveexec_b64 s[2:3], s[38:39]
	ds_write_b32 v81, v10
	ds_write_b32 v81, v11 offset:32
	ds_write_b32 v81, v12 offset:64
	ds_write_b32 v81, v13 offset:96
	s_or_b64 exec, exec, s[2:3]
	s_waitcnt vmcnt(0)
	ds_write_b128 v198, v[148:151]
	ds_write_b128 v198, v[152:155] offset:1152
	ds_read_b128 v[148:151], v199
	ds_read_b128 v[152:155], v199 offset:64
	s_waitcnt lgkmcnt(8)
	v_mfma_f32_16x16x32_f16 v[10:13], v[140:143], v[6:9], 0
	v_mfma_f32_16x16x32_f16 v[10:13], v[144:147], v[2:5], v[10:13]
	v_or_b32_e32 v80, 0xd0, v160
	v_mul_f32_e32 v194, 0x3e000000, v194
	v_mul_f32_e32 v195, 0x3e000000, v195
	v_mul_f32_e32 v196, 0x3e000000, v196
	v_mul_f32_e32 v197, 0x3e000000, v197
	v_cmp_lt_i32_e32 vcc, v80, v85
	v_cmp_lt_i32_e64 s[46:47], v80, v171
	v_lshl_add_u32 v81, v80, 5, v167
	s_nop 0
	v_cndmask_b32_e32 v194, v242, v194, vcc
	v_cndmask_b32_e64 v195, v242, v195, s[46:47]
	v_cmp_lt_i32_e32 vcc, v80, v156
	v_cmp_lt_i32_e64 s[46:47], v80, v158
	v_max3_f32 v15, v15, v194, v195
	s_nop 0
	v_cndmask_b32_e32 v196, v242, v196, vcc
	v_cndmask_b32_e64 v197, v242, v197, s[46:47]
	v_max3_f32 v15, v15, v196, v197
	s_and_saveexec_b64 s[2:3], s[38:39]
	ds_write_b32 v81, v194
	ds_write_b32 v81, v195 offset:32
	ds_write_b32 v81, v196 offset:64
	ds_write_b32 v81, v197 offset:96
	s_or_b64 exec, exec, s[2:3]
	s_waitcnt lgkmcnt(4)
	v_mfma_f32_16x16x32_f16 v[194:197], v[148:151], v[6:9], 0
	v_mfma_f32_16x16x32_f16 v[194:197], v[152:155], v[2:5], v[194:197]
	v_or_b32_e32 v80, 0xe0, v160
	v_mul_f32_e32 v10, 0x3e000000, v10
	v_mul_f32_e32 v11, 0x3e000000, v11
	v_mul_f32_e32 v12, 0x3e000000, v12
	v_mul_f32_e32 v13, 0x3e000000, v13
	v_cmp_lt_i32_e32 vcc, v80, v85
	v_cmp_lt_i32_e64 s[46:47], v80, v171
	v_lshl_add_u32 v81, v80, 5, v167
	s_nop 0
	v_cndmask_b32_e32 v10, v242, v10, vcc
	v_cndmask_b32_e64 v11, v242, v11, s[46:47]
	v_cmp_lt_i32_e32 vcc, v80, v156
	v_cmp_lt_i32_e64 s[46:47], v80, v158
	v_max3_f32 v15, v15, v10, v11
	s_nop 0
	v_cndmask_b32_e32 v12, v242, v12, vcc
	v_cndmask_b32_e64 v13, v242, v13, s[46:47]
	v_max3_f32 v15, v15, v12, v13
	s_and_saveexec_b64 s[2:3], s[38:39]
	ds_write_b32 v81, v10
	ds_write_b32 v81, v11 offset:32
	ds_write_b32 v81, v12 offset:64
	ds_write_b32 v81, v13 offset:96
	s_or_b64 exec, exec, s[2:3]
	s_nop 7
	v_or_b32_e32 v80, 0xf0, v160
	v_mul_f32_e32 v194, 0x3e000000, v194
	v_mul_f32_e32 v195, 0x3e000000, v195
	v_mul_f32_e32 v196, 0x3e000000, v196
	v_mul_f32_e32 v197, 0x3e000000, v197
	v_cmp_lt_i32_e32 vcc, v80, v85
	v_cmp_lt_i32_e64 s[46:47], v80, v171
	v_lshl_add_u32 v81, v80, 5, v167
	s_nop 0
	v_cndmask_b32_e32 v194, v242, v194, vcc
	v_cndmask_b32_e64 v195, v242, v195, s[46:47]
	v_cmp_lt_i32_e32 vcc, v80, v156
	v_cmp_lt_i32_e64 s[46:47], v80, v158
	v_max3_f32 v15, v15, v194, v195
	s_nop 0
	v_cndmask_b32_e32 v196, v242, v196, vcc
	v_cndmask_b32_e64 v197, v242, v197, s[46:47]
	v_max3_f32 v15, v15, v196, v197
	s_and_saveexec_b64 s[2:3], s[38:39]
	ds_write_b32 v81, v194
	ds_write_b32 v81, v195 offset:32
	ds_write_b32 v81, v196 offset:64
	ds_write_b32 v81, v197 offset:96
	s_or_b64 exec, exec, s[2:3]

; __device__ __forceinline__ void dsa_item(const KP& p, int b, int tile, char* smem) {
;     ...
; #pragma unroll 1
;       for (int g8 = 0; g8 < 4; ++g8) {
;         h8 vv[8];
; #pragma unroll
;         for (int i = 0; i < 8; ++i) {
;           const int pos = (g8 * 8 + i) * 8 + rs;
;           const int s = (pos < nsel) ? (int)sel[tk * 256 + pos] : 0;
;           vv[i] = *(const h8*)(ub + (size_t)s * NU + C_BV + dc * 8);
;         }
; #pragma unroll
;         for (int i = 0; i < 8; ++i) {
;           const int pos = (g8 * 8 + i) * 8 + rs;
;           const f32x4 pa = *(const f32x4*)&pbuf[pos * 8];
;           const f32x4 pb = *(const f32x4*)&pbuf[pos * 8 + 4];
;           float vf[8];
; #pragma unroll
;           for (int e = 0; e < 8; ++e) vf[e] = (float)vv[i][e];
; #pragma unroll
;           for (int e = 0; e < 8; ++e) {
;             acc[0][e] += pa[0] * vf[e]; acc[1][e] += pa[1] * vf[e]; acc[2][e] += pa[2] * vf[e]; acc[3][e] += pa[3] * vf[e];
;             acc[4][e] += pb[0] * vf[e]; acc[5][e] += pb[1] * vf[e]; acc[6][e] += pb[2] * vf[e]; acc[7][e] += pb[3] * vf[e];
;           }
;         }
.LBB0_1513:
	s_add_u32 s2, s78, 0x3880
	s_addc_u32 s3, s79, 0
	v_lshlrev_b32_e32 v35, 8, v159
	v_lshl_add_u32 v35, v165, 2, v35
	v_add_u32_e32 v35, 0xcc00, v35
	ds_read_b32 v2, v35
	ds_read_b32 v6, v35 offset:32
	ds_read_b32 v10, v35 offset:64
	ds_read_b32 v14, v35 offset:96
	ds_read_b32 v22, v35 offset:128
	ds_read_b32 v26, v35 offset:160
	ds_read_b32 v18, v35 offset:192
	ds_read_b32 v30, v35 offset:224
	s_waitcnt lgkmcnt(7)
	v_add_u32_e32 v2, v2, v0
	global_load_dwordx4 v[2:5], v2, s[2:3]
	s_waitcnt lgkmcnt(6)
	v_add_u32_e32 v6, v6, v0
	global_load_dwordx4 v[6:9], v6, s[2:3]
	s_waitcnt lgkmcnt(5)
	v_add_u32_e32 v10, v10, v0
	global_load_dwordx4 v[10:13], v10, s[2:3]
	s_waitcnt lgkmcnt(4)
	v_add_u32_e32 v14, v14, v0
	global_load_dwordx4 v[14:17], v14, s[2:3]
	s_waitcnt lgkmcnt(3)
	v_add_u32_e32 v22, v22, v0
	global_load_dwordx4 v[22:25], v22, s[2:3]
	s_waitcnt lgkmcnt(2)
	v_add_u32_e32 v26, v26, v0
	global_load_dwordx4 v[26:29], v26, s[2:3]
	s_waitcnt lgkmcnt(1)
	v_add_u32_e32 v18, v18, v0
	global_load_dwordx4 v[18:21], v18, s[2:3]
	s_waitcnt lgkmcnt(0)
	v_add_u32_e32 v30, v30, v0
	global_load_dwordx4 v[30:33], v30, s[2:3]
	v_lshlrev_b32_e32 v35, 8, v159
	v_lshl_add_u32 v35, v165, 2, v35
	v_add_u32_e32 v35, 0xcc00, v35
	ds_read_b32 v204, v35 offset:256
	ds_read_b32 v208, v35 offset:288
	ds_read_b32 v212, v35 offset:320
	ds_read_b32 v216, v35 offset:352
	ds_read_b32 v224, v35 offset:384
	ds_read_b32 v228, v35 offset:416
	ds_read_b32 v220, v35 offset:448
	ds_read_b32 v232, v35 offset:480
	s_waitcnt lgkmcnt(7)
	v_add_u32_e32 v204, v204, v0
	global_load_dwordx4 v[204:207], v204, s[2:3]
	s_waitcnt lgkmcnt(6)
	v_add_u32_e32 v208, v208, v0
	global_load_dwordx4 v[208:211], v208, s[2:3]
	s_waitcnt lgkmcnt(5)
	v_add_u32_e32 v212, v212, v0
	global_load_dwordx4 v[212:215], v212, s[2:3]
	s_waitcnt lgkmcnt(4)
	v_add_u32_e32 v216, v216, v0
	global_load_dwordx4 v[216:219], v216, s[2:3]
	s_waitcnt lgkmcnt(3)
	v_add_u32_e32 v224, v224, v0
	global_load_dwordx4 v[224:227], v224, s[2:3]
	s_waitcnt lgkmcnt(2)
	v_add_u32_e32 v228, v228, v0
	global_load_dwordx4 v[228:231], v228, s[2:3]
	s_waitcnt lgkmcnt(1)
	v_add_u32_e32 v220, v220, v0
	global_load_dwordx4 v[220:223], v220, s[2:3]
	s_waitcnt lgkmcnt(0)
	v_add_u32_e32 v232, v232, v0
	global_load_dwordx4 v[232:235], v232, s[2:3]
	s_waitcnt vmcnt(15)
	v_cvt_f32_f16_sdwa v175, v2 dst_sel:DWORD dst_unused:UNUSED_PAD src0_sel:WORD_1
	v_cvt_f32_f16_e32 v174, v2
	s_waitcnt vmcnt(14)
	v_cvt_f32_f16_sdwa v177, v6 dst_sel:DWORD dst_unused:UNUSED_PAD src0_sel:WORD_1
	v_cvt_f32_f16_e32 v176, v6
	ds_read_b128 v[58:61], v172
	ds_read_b128 v[34:37], v172 offset:16
	ds_read_b128 v[62:65], v172 offset:256
	ds_read_b128 v[38:41], v172 offset:272
	ds_read_b128 v[66:69], v172 offset:512
	ds_read_b128 v[42:45], v172 offset:528
	ds_read_b128 v[70:73], v172 offset:768
	ds_read_b128 v[46:49], v172 offset:784
	ds_read_b128 v[74:77], v172 offset:1024
	ds_read_b128 v[50:53], v172 offset:1040
	s_waitcnt vmcnt(13)
	v_cvt_f32_f16_sdwa v179, v10 dst_sel:DWORD dst_unused:UNUSED_PAD src0_sel:WORD_1
	v_cvt_f32_f16_e32 v178, v10
	s_waitcnt lgkmcnt(8)
	v_mov_b32_e32 v156, v37
	s_waitcnt vmcnt(12)
	v_cvt_f32_f16_sdwa v181, v14 dst_sel:DWORD dst_unused:UNUSED_PAD src0_sel:WORD_1
	v_cvt_f32_f16_e32 v180, v14
	v_pk_fma_f32 v[148:149], v[156:157], v[174:175], v[148:149] op_sel_hi:[0,1,1]
	s_waitcnt lgkmcnt(6)
	v_mov_b32_e32 v6, v41
	s_waitcnt vmcnt(11)
	v_cvt_f32_f16_sdwa v189, v22 dst_sel:DWORD dst_unused:UNUSED_PAD src0_sel:WORD_1
	v_cvt_f32_f16_e32 v188, v22
	v_pk_fma_f32 v[148:149], v[6:7], v[176:177], v[148:149] op_sel_hi:[0,1,1]
	s_waitcnt lgkmcnt(4)
	v_mov_b32_e32 v10, v45
	v_pk_fma_f32 v[148:149], v[10:11], v[178:179], v[148:149] op_sel_hi:[0,1,1]
	s_waitcnt lgkmcnt(2)
	v_mov_b32_e32 v22, v49
	v_pk_fma_f32 v[148:149], v[22:23], v[180:181], v[148:149] op_sel_hi:[0,1,1]
	s_waitcnt lgkmcnt(0)
	v_mov_b32_e32 v158, v53
	ds_read_b128 v[78:81], v172 offset:1280
	ds_read_b128 v[54:57], v172 offset:1296
	v_pk_fma_f32 v[190:191], v[158:159], v[188:189], v[148:149] op_sel_hi:[0,1,1]
	v_pk_fma_f32 v[148:149], v[58:59], v[174:175], v[154:155] op_sel_hi:[0,1,1]
	v_mov_b32_e32 v154, v61
	v_pk_fma_f32 v[152:153], v[58:59], v[174:175], v[152:153] op_sel:[1,0,0]
	v_pk_fma_f32 v[146:147], v[60:61], v[174:175], v[146:147] op_sel_hi:[0,1,1]
	v_pk_fma_f32 v[140:141], v[154:155], v[174:175], v[140:141] op_sel_hi:[0,1,1]
	v_mov_b32_e32 v194, v65
	v_pk_fma_f32 v[150:151], v[34:35], v[174:175], v[150:151] op_sel_hi:[0,1,1]
	v_pk_fma_f32 v[144:145], v[34:35], v[174:175], v[144:145] op_sel:[1,0,0]
	v_pk_fma_f32 v[138:139], v[36:37], v[174:175], v[138:139] op_sel_hi:[0,1,1]
	s_waitcnt vmcnt(10)
; __device__ __forceinline__ void dsa_item(const KP& p, int b, int tile, char* smem) {
;     ...
; #pragma unroll
;         for (int i = 0; i < 8; ++i) {
;           const int pos = (g8 * 8 + i) * 8 + rs;
;           const f32x4 pa = *(const f32x4*)&pbuf[pos * 8];
;           const f32x4 pb = *(const f32x4*)&pbuf[pos * 8 + 4];
;           float vf[8];
; #pragma unroll
;           for (int e = 0; e < 8; ++e) vf[e] = (float)vv[i][e];
; #pragma unroll
;           for (int e = 0; e < 8; ++e) {
;             acc[0][e] += pa[0] * vf[e]; acc[1][e] += pa[1] * vf[e]; acc[2][e] += pa[2] * vf[e]; acc[3][e] += pa[3] * vf[e];
;             acc[4][e] += pb[0] * vf[e]; acc[5][e] += pb[1] * vf[e]; acc[6][e] += pb[2] * vf[e]; acc[7][e] += pb[3] * vf[e];
;           }
	v_cvt_f32_f16_sdwa v193, v26 dst_sel:DWORD dst_unused:UNUSED_PAD src0_sel:WORD_1
	v_cvt_f32_f16_e32 v192, v26
	v_pk_fma_f32 v[148:149], v[62:63], v[176:177], v[148:149] op_sel_hi:[0,1,1]
	v_pk_fma_f32 v[152:153], v[62:63], v[176:177], v[152:153] op_sel:[1,0,0]
	v_pk_fma_f32 v[146:147], v[64:65], v[176:177], v[146:147] op_sel_hi:[0,1,1]
	v_pk_fma_f32 v[140:141], v[194:195], v[176:177], v[140:141] op_sel_hi:[0,1,1]
	v_mov_b32_e32 v196, v69
	v_pk_fma_f32 v[150:151], v[38:39], v[176:177], v[150:151] op_sel_hi:[0,1,1]
	v_pk_fma_f32 v[144:145], v[38:39], v[176:177], v[144:145] op_sel:[1,0,0]
	v_pk_fma_f32 v[138:139], v[40:41], v[176:177], v[138:139] op_sel_hi:[0,1,1]
	v_cvt_f32_f16_sdwa v175, v3 dst_sel:DWORD dst_unused:UNUSED_PAD src0_sel:WORD_1
	v_cvt_f32_f16_e32 v174, v3
	v_pk_fma_f32 v[148:149], v[66:67], v[178:179], v[148:149] op_sel_hi:[0,1,1]
	v_pk_fma_f32 v[152:153], v[66:67], v[178:179], v[152:153] op_sel:[1,0,0]
	v_pk_fma_f32 v[146:147], v[68:69], v[178:179], v[146:147] op_sel_hi:[0,1,1]
	v_pk_fma_f32 v[140:141], v[196:197], v[178:179], v[140:141] op_sel_hi:[0,1,1]
	v_mov_b32_e32 v198, v73
	v_pk_fma_f32 v[150:151], v[42:43], v[178:179], v[150:151] op_sel_hi:[0,1,1]
	v_pk_fma_f32 v[144:145], v[42:43], v[178:179], v[144:145] op_sel:[1,0,0]
	v_pk_fma_f32 v[138:139], v[44:45], v[178:179], v[138:139] op_sel_hi:[0,1,1]
	v_cvt_f32_f16_sdwa v179, v7 dst_sel:DWORD dst_unused:UNUSED_PAD src0_sel:WORD_1
	v_cvt_f32_f16_e32 v178, v7
	v_pk_fma_f32 v[148:149], v[70:71], v[180:181], v[148:149] op_sel_hi:[0,1,1]
	v_pk_fma_f32 v[152:153], v[70:71], v[180:181], v[152:153] op_sel:[1,0,0]
	v_pk_fma_f32 v[146:147], v[72:73], v[180:181], v[146:147] op_sel_hi:[0,1,1]
	v_pk_fma_f32 v[140:141], v[198:199], v[180:181], v[140:141] op_sel_hi:[0,1,1]
	v_mov_b32_e32 v200, v77
	v_pk_fma_f32 v[150:151], v[46:47], v[180:181], v[150:151] op_sel_hi:[0,1,1]
	v_pk_fma_f32 v[144:145], v[46:47], v[180:181], v[144:145] op_sel:[1,0,0]
	v_pk_fma_f32 v[138:139], v[48:49], v[180:181], v[138:139] op_sel_hi:[0,1,1]
	v_cvt_f32_f16_sdwa v181, v11 dst_sel:DWORD dst_unused:UNUSED_PAD src0_sel:WORD_1
	v_cvt_f32_f16_e32 v180, v11
	v_pk_fma_f32 v[148:149], v[74:75], v[188:189], v[148:149] op_sel_hi:[0,1,1]
	v_pk_fma_f32 v[152:153], v[74:75], v[188:189], v[152:153] op_sel:[1,0,0]
	v_pk_fma_f32 v[146:147], v[76:77], v[188:189], v[146:147] op_sel_hi:[0,1,1]
	v_pk_fma_f32 v[140:141], v[200:201], v[188:189], v[140:141] op_sel_hi:[0,1,1]
	v_pk_fma_f32 v[150:151], v[50:51], v[188:189], v[150:151] op_sel_hi:[0,1,1]
	v_pk_fma_f32 v[144:145], v[50:51], v[188:189], v[144:145] op_sel:[1,0,0]
	v_pk_fma_f32 v[138:139], v[52:53], v[188:189], v[138:139] op_sel_hi:[0,1,1]
	s_waitcnt lgkmcnt(0)
	v_mov_b32_e32 v176, v57
	v_cvt_f32_f16_sdwa v189, v15 dst_sel:DWORD dst_unused:UNUSED_PAD src0_sel:WORD_1
	v_cvt_f32_f16_e32 v188, v15
	v_pk_fma_f32 v[2:3], v[56:57], v[192:193], v[138:139] op_sel_hi:[0,1,1]
	v_pk_fma_f32 v[138:139], v[176:177], v[192:193], v[190:191] op_sel_hi:[0,1,1]
	v_pk_fma_f32 v[132:133], v[156:157], v[174:175], v[132:133] op_sel_hi:[0,1,1]
	v_cvt_f32_f16_sdwa v191, v23 dst_sel:DWORD dst_unused:UNUSED_PAD src0_sel:WORD_1
	v_cvt_f32_f16_e32 v190, v23
	v_pk_fma_f32 v[14:15], v[6:7], v[178:179], v[132:133] op_sel_hi:[0,1,1]
	v_mov_b32_e32 v202, v81
	v_pk_fma_f32 v[14:15], v[10:11], v[180:181], v[14:15] op_sel_hi:[0,1,1]
	v_pk_fma_f32 v[148:149], v[78:79], v[192:193], v[148:149] op_sel_hi:[0,1,1]
	v_pk_fma_f32 v[152:153], v[78:79], v[192:193], v[152:153] op_sel:[1,0,0]
	v_pk_fma_f32 v[146:147], v[80:81], v[192:193], v[146:147] op_sel_hi:[0,1,1]
	v_pk_fma_f32 v[140:141], v[202:203], v[192:193], v[140:141] op_sel_hi:[0,1,1]
	v_pk_fma_f32 v[150:151], v[54:55], v[192:193], v[150:151] op_sel_hi:[0,1,1]
	v_pk_fma_f32 v[144:145], v[54:55], v[192:193], v[144:145] op_sel:[1,0,0]
	v_pk_fma_f32 v[14:15], v[22:23], v[188:189], v[14:15] op_sel_hi:[0,1,1]
	v_cvt_f32_f16_sdwa v193, v27 dst_sel:DWORD dst_unused:UNUSED_PAD src0_sel:WORD_1
	v_cvt_f32_f16_e32 v192, v27
	v_pk_fma_f32 v[26:27], v[58:59], v[174:175], v[134:135] op_sel:[1,0,0]
	v_pk_fma_f32 v[134:135], v[34:35], v[174:175], v[136:137] op_sel_hi:[0,1,1]
	v_cvt_f32_f16_sdwa v137, v4 dst_sel:DWORD dst_unused:UNUSED_PAD src0_sel:WORD_1
	v_cvt_f32_f16_e32 v136, v4
	v_pk_fma_f32 v[132:133], v[158:159], v[190:191], v[14:15] op_sel_hi:[0,1,1]
	v_pk_fma_f32 v[14:15], v[58:59], v[174:175], v[142:143] op_sel_hi:[0,1,1]
	v_cvt_f32_f16_sdwa v143, v8 dst_sel:DWORD dst_unused:UNUSED_PAD src0_sel:WORD_1
	v_cvt_f32_f16_e32 v142, v8
	v_pk_fma_f32 v[128:129], v[60:61], v[174:175], v[128:129] op_sel_hi:[0,1,1]
	v_pk_fma_f32 v[120:121], v[154:155], v[174:175], v[120:121] op_sel_hi:[0,1,1]
	v_pk_fma_f32 v[130:131], v[34:35], v[174:175], v[130:131] op_sel:[1,0,0]
	v_pk_fma_f32 v[122:123], v[36:37], v[174:175], v[122:123] op_sel_hi:[0,1,1]
	v_cvt_f32_f16_sdwa v175, v12 dst_sel:DWORD dst_unused:UNUSED_PAD src0_sel:WORD_1
	v_cvt_f32_f16_e32 v174, v12
	v_pk_fma_f32 v[14:15], v[62:63], v[178:179], v[14:15] op_sel_hi:[0,1,1]
	v_pk_fma_f32 v[26:27], v[62:63], v[178:179], v[26:27] op_sel:[1,0,0]
	v_pk_fma_f32 v[128:129], v[64:65], v[178:179], v[128:129] op_sel_hi:[0,1,1]
	v_pk_fma_f32 v[120:121], v[194:195], v[178:179], v[120:121] op_sel_hi:[0,1,1]
	v_pk_fma_f32 v[134:135], v[38:39], v[178:179], v[134:135] op_sel_hi:[0,1,1]
	v_pk_fma_f32 v[130:131], v[38:39], v[178:179], v[130:131] op_sel:[1,0,0]
	v_pk_fma_f32 v[122:123], v[40:41], v[178:179], v[122:123] op_sel_hi:[0,1,1]
	v_cvt_f32_f16_sdwa v179, v16 dst_sel:DWORD dst_unused:UNUSED_PAD src0_sel:WORD_1
	v_cvt_f32_f16_e32 v178, v16
	v_pk_fma_f32 v[14:15], v[66:67], v[180:181], v[14:15] op_sel_hi:[0,1,1]
; __device__ __forceinline__ void dsa_item(const KP& p, int b, int tile, char* smem) {
;     ...
; #pragma unroll
;         for (int i = 0; i < 8; ++i) {
;           const int pos = (g8 * 8 + i) * 8 + rs;
;           const f32x4 pa = *(const f32x4*)&pbuf[pos * 8];
;           const f32x4 pb = *(const f32x4*)&pbuf[pos * 8 + 4];
;           float vf[8];
; #pragma unroll
;           for (int e = 0; e < 8; ++e) vf[e] = (float)vv[i][e];
; #pragma unroll
;           for (int e = 0; e < 8; ++e) {
;             acc[0][e] += pa[0] * vf[e]; acc[1][e] += pa[1] * vf[e]; acc[2][e] += pa[2] * vf[e]; acc[3][e] += pa[3] * vf[e];
;             acc[4][e] += pb[0] * vf[e]; acc[5][e] += pb[1] * vf[e]; acc[6][e] += pb[2] * vf[e]; acc[7][e] += pb[3] * vf[e];
;           }
	v_pk_fma_f32 v[26:27], v[66:67], v[180:181], v[26:27] op_sel:[1,0,0]
	v_pk_fma_f32 v[128:129], v[68:69], v[180:181], v[128:129] op_sel_hi:[0,1,1]
	v_pk_fma_f32 v[120:121], v[196:197], v[180:181], v[120:121] op_sel_hi:[0,1,1]
	v_pk_fma_f32 v[134:135], v[42:43], v[180:181], v[134:135] op_sel_hi:[0,1,1]
	v_pk_fma_f32 v[130:131], v[42:43], v[180:181], v[130:131] op_sel:[1,0,0]
	v_pk_fma_f32 v[122:123], v[44:45], v[180:181], v[122:123] op_sel_hi:[0,1,1]
	v_cvt_f32_f16_sdwa v181, v24 dst_sel:DWORD dst_unused:UNUSED_PAD src0_sel:WORD_1
	v_cvt_f32_f16_e32 v180, v24
	v_pk_fma_f32 v[106:107], v[36:37], v[136:137], v[106:107] op_sel_hi:[0,1,1]
	v_pk_fma_f32 v[14:15], v[70:71], v[188:189], v[14:15] op_sel_hi:[0,1,1]
	v_pk_fma_f32 v[26:27], v[70:71], v[188:189], v[26:27] op_sel:[1,0,0]
	v_pk_fma_f32 v[128:129], v[72:73], v[188:189], v[128:129] op_sel_hi:[0,1,1]
	v_pk_fma_f32 v[120:121], v[198:199], v[188:189], v[120:121] op_sel_hi:[0,1,1]
	v_pk_fma_f32 v[134:135], v[46:47], v[188:189], v[134:135] op_sel_hi:[0,1,1]
	v_pk_fma_f32 v[130:131], v[46:47], v[188:189], v[130:131] op_sel:[1,0,0]
	v_pk_fma_f32 v[122:123], v[48:49], v[188:189], v[122:123] op_sel_hi:[0,1,1]
	v_pk_fma_f32 v[114:115], v[156:157], v[136:137], v[114:115] op_sel_hi:[0,1,1]
	v_cvt_f32_f16_sdwa v189, v28 dst_sel:DWORD dst_unused:UNUSED_PAD src0_sel:WORD_1
	v_cvt_f32_f16_e32 v188, v28
	v_pk_fma_f32 v[124:125], v[58:59], v[136:137], v[124:125] op_sel_hi:[0,1,1]
	v_pk_fma_f32 v[116:117], v[58:59], v[136:137], v[116:117] op_sel:[1,0,0]
	v_pk_fma_f32 v[110:111], v[60:61], v[136:137], v[110:111] op_sel_hi:[0,1,1]
	v_pk_fma_f32 v[104:105], v[154:155], v[136:137], v[104:105] op_sel_hi:[0,1,1]
	v_pk_fma_f32 v[118:119], v[34:35], v[136:137], v[118:119] op_sel_hi:[0,1,1]
	v_pk_fma_f32 v[112:113], v[34:35], v[136:137], v[112:113] op_sel:[1,0,0]
	v_pk_fma_f32 v[106:107], v[40:41], v[142:143], v[106:107] op_sel_hi:[0,1,1]
	v_cvt_f32_f16_sdwa v137, v5 dst_sel:DWORD dst_unused:UNUSED_PAD src0_sel:WORD_1
	v_cvt_f32_f16_e32 v136, v5
	v_pk_fma_f32 v[106:107], v[44:45], v[174:175], v[106:107] op_sel_hi:[0,1,1]
	v_pk_fma_f32 v[106:107], v[48:49], v[178:179], v[106:107] op_sel_hi:[0,1,1]
	v_pk_fma_f32 v[4:5], v[52:53], v[180:181], v[106:107] op_sel_hi:[0,1,1]
	v_pk_fma_f32 v[106:107], v[56:57], v[188:189], v[4:5] op_sel_hi:[0,1,1]
	v_pk_fma_f32 v[4:5], v[156:157], v[136:137], v[98:99] op_sel_hi:[0,1,1]
	v_cvt_f32_f16_sdwa v99, v9 dst_sel:DWORD dst_unused:UNUSED_PAD src0_sel:WORD_1
	v_cvt_f32_f16_e32 v98, v9
	v_cvt_f32_f16_sdwa v9, v13 dst_sel:DWORD dst_unused:UNUSED_PAD src0_sel:WORD_1
	v_cvt_f32_f16_e32 v8, v13
	v_cvt_f32_f16_sdwa v13, v17 dst_sel:DWORD dst_unused:UNUSED_PAD src0_sel:WORD_1
	v_cvt_f32_f16_e32 v12, v17
	v_cvt_f32_f16_sdwa v17, v25 dst_sel:DWORD dst_unused:UNUSED_PAD src0_sel:WORD_1
	v_cvt_f32_f16_e32 v16, v25
	v_pk_fma_f32 v[4:5], v[6:7], v[98:99], v[4:5] op_sel_hi:[0,1,1]
	v_pk_fma_f32 v[114:115], v[6:7], v[142:143], v[114:115] op_sel_hi:[0,1,1]
	v_pk_fma_f32 v[4:5], v[10:11], v[8:9], v[4:5] op_sel_hi:[0,1,1]
	v_pk_fma_f32 v[114:115], v[10:11], v[174:175], v[114:115] op_sel_hi:[0,1,1]
	v_pk_fma_f32 v[4:5], v[22:23], v[12:13], v[4:5] op_sel_hi:[0,1,1]
	v_pk_fma_f32 v[114:115], v[22:23], v[178:179], v[114:115] op_sel_hi:[0,1,1]
	v_pk_fma_f32 v[22:23], v[158:159], v[16:17], v[4:5] op_sel_hi:[0,1,1]
	v_pk_fma_f32 v[4:5], v[58:59], v[136:137], v[108:109] op_sel_hi:[0,1,1]
	v_cvt_f32_f16_sdwa v25, v29 dst_sel:DWORD dst_unused:UNUSED_PAD src0_sel:WORD_1
	v_cvt_f32_f16_e32 v24, v29
	v_pk_fma_f32 v[4:5], v[62:63], v[98:99], v[4:5] op_sel_hi:[0,1,1]
	v_pk_fma_f32 v[4:5], v[66:67], v[8:9], v[4:5] op_sel_hi:[0,1,1]
	v_pk_fma_f32 v[4:5], v[70:71], v[12:13], v[4:5] op_sel_hi:[0,1,1]
	v_pk_fma_f32 v[4:5], v[74:75], v[16:17], v[4:5] op_sel_hi:[0,1,1]
	v_pk_fma_f32 v[28:29], v[78:79], v[24:25], v[4:5] op_sel_hi:[0,1,1]
	v_pk_fma_f32 v[4:5], v[58:59], v[136:137], v[100:101] op_sel:[1,0,0]
	v_pk_fma_f32 v[124:125], v[62:63], v[142:143], v[124:125] op_sel_hi:[0,1,1]
	v_pk_fma_f32 v[4:5], v[62:63], v[98:99], v[4:5] op_sel:[1,0,0]
	v_pk_fma_f32 v[116:117], v[62:63], v[142:143], v[116:117] op_sel:[1,0,0]
	v_pk_fma_f32 v[4:5], v[66:67], v[8:9], v[4:5] op_sel:[1,0,0]
	v_pk_fma_f32 v[110:111], v[64:65], v[142:143], v[110:111] op_sel_hi:[0,1,1]
	v_pk_fma_f32 v[4:5], v[70:71], v[12:13], v[4:5] op_sel:[1,0,0]
	v_pk_fma_f32 v[118:119], v[38:39], v[142:143], v[118:119] op_sel_hi:[0,1,1]
	v_pk_fma_f32 v[4:5], v[74:75], v[16:17], v[4:5] op_sel:[1,0,0]
	v_pk_fma_f32 v[112:113], v[38:39], v[142:143], v[112:113] op_sel:[1,0,0]
	v_pk_fma_f32 v[58:59], v[78:79], v[24:25], v[4:5] op_sel:[1,0,0]
	v_pk_fma_f32 v[4:5], v[60:61], v[136:137], v[94:95] op_sel_hi:[0,1,1]
	v_pk_fma_f32 v[4:5], v[64:65], v[98:99], v[4:5] op_sel_hi:[0,1,1]
	v_pk_fma_f32 v[4:5], v[68:69], v[8:9], v[4:5] op_sel_hi:[0,1,1]
	v_pk_fma_f32 v[4:5], v[72:73], v[12:13], v[4:5] op_sel_hi:[0,1,1]
	v_pk_fma_f32 v[4:5], v[76:77], v[16:17], v[4:5] op_sel_hi:[0,1,1]
	v_pk_fma_f32 v[60:61], v[80:81], v[24:25], v[4:5] op_sel_hi:[0,1,1]
	v_pk_fma_f32 v[4:5], v[154:155], v[136:137], v[90:91] op_sel_hi:[0,1,1]
	v_pk_fma_f32 v[4:5], v[194:195], v[98:99], v[4:5] op_sel_hi:[0,1,1]
	v_pk_fma_f32 v[4:5], v[196:197], v[8:9], v[4:5] op_sel_hi:[0,1,1]
	v_pk_fma_f32 v[4:5], v[198:199], v[12:13], v[4:5] op_sel_hi:[0,1,1]
	v_pk_fma_f32 v[4:5], v[200:201], v[16:17], v[4:5] op_sel_hi:[0,1,1]
	v_pk_fma_f32 v[62:63], v[202:203], v[24:25], v[4:5] op_sel_hi:[0,1,1]
	v_pk_fma_f32 v[4:5], v[34:35], v[136:137], v[102:103] op_sel_hi:[0,1,1]
	v_pk_fma_f32 v[4:5], v[38:39], v[98:99], v[4:5] op_sel_hi:[0,1,1]
	v_pk_fma_f32 v[4:5], v[42:43], v[8:9], v[4:5] op_sel_hi:[0,1,1]
	v_pk_fma_f32 v[4:5], v[46:47], v[12:13], v[4:5] op_sel_hi:[0,1,1]
	v_pk_fma_f32 v[4:5], v[50:51], v[16:17], v[4:5] op_sel_hi:[0,1,1]
	v_pk_fma_f32 v[64:65], v[54:55], v[24:25], v[4:5] op_sel_hi:[0,1,1]
	v_pk_fma_f32 v[4:5], v[34:35], v[136:137], v[96:97] op_sel:[1,0,0]
	v_pk_fma_f32 v[118:119], v[42:43], v[174:175], v[118:119] op_sel_hi:[0,1,1]
	v_pk_fma_f32 v[4:5], v[38:39], v[98:99], v[4:5] op_sel:[1,0,0]
	v_pk_fma_f32 v[112:113], v[42:43], v[174:175], v[112:113] op_sel:[1,0,0]
	v_pk_fma_f32 v[4:5], v[42:43], v[8:9], v[4:5] op_sel:[1,0,0]
	v_pk_fma_f32 v[118:119], v[46:47], v[178:179], v[118:119] op_sel_hi:[0,1,1]
	v_pk_fma_f32 v[4:5], v[46:47], v[12:13], v[4:5] op_sel:[1,0,0]
	v_pk_fma_f32 v[112:113], v[46:47], v[178:179], v[112:113] op_sel:[1,0,0]
	v_pk_fma_f32 v[4:5], v[50:51], v[16:17], v[4:5] op_sel:[1,0,0]
	s_waitcnt vmcnt(9)
; __device__ __forceinline__ void dsa_item(const KP& p, int b, int tile, char* smem) {
;     ...
; #pragma unroll
;         for (int i = 0; i < 8; ++i) {
;           const int pos = (g8 * 8 + i) * 8 + rs;
;           const f32x4 pa = *(const f32x4*)&pbuf[pos * 8];
;           const f32x4 pb = *(const f32x4*)&pbuf[pos * 8 + 4];
;           float vf[8];
; #pragma unroll
;           for (int e = 0; e < 8; ++e) vf[e] = (float)vv[i][e];
; #pragma unroll
;           for (int e = 0; e < 8; ++e) {
;             acc[0][e] += pa[0] * vf[e]; acc[1][e] += pa[1] * vf[e]; acc[2][e] += pa[2] * vf[e]; acc[3][e] += pa[3] * vf[e];
;             acc[4][e] += pb[0] * vf[e]; acc[5][e] += pb[1] * vf[e]; acc[6][e] += pb[2] * vf[e]; acc[7][e] += pb[3] * vf[e];
;           }
	v_cvt_f32_f16_sdwa v43, v19 dst_sel:DWORD dst_unused:UNUSED_PAD src0_sel:WORD_1
	v_pk_fma_f32 v[34:35], v[54:55], v[24:25], v[4:5] op_sel:[1,0,0]
	v_pk_fma_f32 v[4:5], v[36:37], v[136:137], v[92:93] op_sel_hi:[0,1,1]
	v_pk_fma_f32 v[4:5], v[40:41], v[98:99], v[4:5] op_sel_hi:[0,1,1]
	v_pk_fma_f32 v[4:5], v[44:45], v[8:9], v[4:5] op_sel_hi:[0,1,1]
	v_pk_fma_f32 v[4:5], v[48:49], v[12:13], v[4:5] op_sel_hi:[0,1,1]
	v_pk_fma_f32 v[4:5], v[52:53], v[16:17], v[4:5] op_sel_hi:[0,1,1]
	v_pk_fma_f32 v[12:13], v[56:57], v[24:25], v[4:5] op_sel_hi:[0,1,1]
	ds_read_b128 v[4:7], v172 offset:1536
	ds_read_b128 v[8:11], v172 offset:1552
	v_pk_fma_f32 v[24:25], v[176:177], v[24:25], v[22:23] op_sel_hi:[0,1,1]
	v_cvt_f32_f16_sdwa v37, v18 dst_sel:DWORD dst_unused:UNUSED_PAD src0_sel:WORD_1
	v_cvt_f32_f16_e32 v36, v18
	v_cvt_f32_f16_e32 v42, v19
	v_cvt_f32_f16_sdwa v45, v20 dst_sel:DWORD dst_unused:UNUSED_PAD src0_sel:WORD_1
	v_cvt_f32_f16_e32 v44, v20
	v_cvt_f32_f16_sdwa v47, v21 dst_sel:DWORD dst_unused:UNUSED_PAD src0_sel:WORD_1
	v_cvt_f32_f16_e32 v46, v21
	ds_read_b128 v[16:19], v172 offset:1792
	ds_read_b128 v[20:23], v172 offset:1808
	s_waitcnt vmcnt(8)
	v_cvt_f32_f16_e32 v48, v30
	v_cvt_f32_f16_sdwa v49, v30 dst_sel:DWORD dst_unused:UNUSED_PAD src0_sel:WORD_1
	v_pk_fma_f32 v[124:125], v[66:67], v[174:175], v[124:125] op_sel_hi:[0,1,1]
	v_pk_fma_f32 v[116:117], v[66:67], v[174:175], v[116:117] op_sel:[1,0,0]
	v_pk_fma_f32 v[110:111], v[68:69], v[174:175], v[110:111] op_sel_hi:[0,1,1]
	v_pk_fma_f32 v[104:105], v[194:195], v[142:143], v[104:105] op_sel_hi:[0,1,1]
	v_cvt_f32_f16_e32 v30, v31
	v_cvt_f32_f16_sdwa v31, v31 dst_sel:DWORD dst_unused:UNUSED_PAD src0_sel:WORD_1
	v_pk_fma_f32 v[14:15], v[74:75], v[190:191], v[14:15] op_sel_hi:[0,1,1]
	v_pk_fma_f32 v[26:27], v[74:75], v[190:191], v[26:27] op_sel:[1,0,0]
	v_pk_fma_f32 v[128:129], v[76:77], v[190:191], v[128:129] op_sel_hi:[0,1,1]
	v_pk_fma_f32 v[134:135], v[50:51], v[190:191], v[134:135] op_sel_hi:[0,1,1]
	v_pk_fma_f32 v[130:131], v[50:51], v[190:191], v[130:131] op_sel:[1,0,0]
	v_pk_fma_f32 v[124:125], v[70:71], v[178:179], v[124:125] op_sel_hi:[0,1,1]
	v_pk_fma_f32 v[116:117], v[70:71], v[178:179], v[116:117] op_sel:[1,0,0]
	v_pk_fma_f32 v[110:111], v[72:73], v[178:179], v[110:111] op_sel_hi:[0,1,1]
	v_pk_fma_f32 v[104:105], v[196:197], v[174:175], v[104:105] op_sel_hi:[0,1,1]
	v_pk_fma_f32 v[118:119], v[50:51], v[180:181], v[118:119] op_sel_hi:[0,1,1]
	v_pk_fma_f32 v[112:113], v[50:51], v[180:181], v[112:113] op_sel:[1,0,0]
	v_cvt_f32_f16_e32 v50, v32
	v_cvt_f32_f16_sdwa v51, v32 dst_sel:DWORD dst_unused:UNUSED_PAD src0_sel:WORD_1
	v_pk_fma_f32 v[14:15], v[78:79], v[192:193], v[14:15] op_sel_hi:[0,1,1]
	v_pk_fma_f32 v[26:27], v[78:79], v[192:193], v[26:27] op_sel:[1,0,0]
	v_pk_fma_f32 v[128:129], v[80:81], v[192:193], v[128:129] op_sel_hi:[0,1,1]
	v_pk_fma_f32 v[120:121], v[200:201], v[190:191], v[120:121] op_sel_hi:[0,1,1]
	v_pk_fma_f32 v[122:123], v[52:53], v[190:191], v[122:123] op_sel_hi:[0,1,1]
	v_pk_fma_f32 v[124:125], v[74:75], v[180:181], v[124:125] op_sel_hi:[0,1,1]
	v_pk_fma_f32 v[116:117], v[74:75], v[180:181], v[116:117] op_sel:[1,0,0]
	v_pk_fma_f32 v[110:111], v[76:77], v[180:181], v[110:111] op_sel_hi:[0,1,1]
	v_pk_fma_f32 v[104:105], v[198:199], v[178:179], v[104:105] op_sel_hi:[0,1,1]
	s_waitcnt lgkmcnt(3)
	v_mov_b32_e32 v38, v7
	s_waitcnt lgkmcnt(2)
	v_mov_b32_e32 v40, v11
	v_cvt_f32_f16_e32 v32, v33
	v_cvt_f32_f16_sdwa v33, v33 dst_sel:DWORD dst_unused:UNUSED_PAD src0_sel:WORD_1
	v_pk_fma_f32 v[2:3], v[10:11], v[36:37], v[2:3] op_sel_hi:[0,1,1]
	v_pk_fma_f32 v[120:121], v[202:203], v[192:193], v[120:121] op_sel_hi:[0,1,1]
	v_pk_fma_f32 v[134:135], v[54:55], v[192:193], v[134:135] op_sel_hi:[0,1,1]
	v_pk_fma_f32 v[130:131], v[54:55], v[192:193], v[130:131] op_sel:[1,0,0]
	v_pk_fma_f32 v[122:123], v[56:57], v[192:193], v[122:123] op_sel_hi:[0,1,1]
	v_pk_fma_f32 v[132:133], v[176:177], v[192:193], v[132:133] op_sel_hi:[0,1,1]
	v_pk_fma_f32 v[114:115], v[158:159], v[180:181], v[114:115] op_sel_hi:[0,1,1]
	v_pk_fma_f32 v[124:125], v[78:79], v[188:189], v[124:125] op_sel_hi:[0,1,1]
	v_pk_fma_f32 v[116:117], v[78:79], v[188:189], v[116:117] op_sel:[1,0,0]
	v_pk_fma_f32 v[110:111], v[80:81], v[188:189], v[110:111] op_sel_hi:[0,1,1]
	v_pk_fma_f32 v[104:105], v[200:201], v[180:181], v[104:105] op_sel_hi:[0,1,1]
	v_pk_fma_f32 v[118:119], v[54:55], v[188:189], v[118:119] op_sel_hi:[0,1,1]
	v_pk_fma_f32 v[112:113], v[54:55], v[188:189], v[112:113] op_sel:[1,0,0]
	v_pk_fma_f32 v[52:53], v[4:5], v[36:37], v[148:149] op_sel_hi:[0,1,1]
	v_pk_fma_f32 v[54:55], v[4:5], v[36:37], v[152:153] op_sel:[1,0,0]
	v_pk_fma_f32 v[56:57], v[6:7], v[36:37], v[146:147] op_sel_hi:[0,1,1]
	v_pk_fma_f32 v[66:67], v[38:39], v[36:37], v[140:141] op_sel_hi:[0,1,1]
	v_pk_fma_f32 v[68:69], v[8:9], v[36:37], v[150:151] op_sel_hi:[0,1,1]
	v_pk_fma_f32 v[70:71], v[8:9], v[36:37], v[144:145] op_sel:[1,0,0]
	v_pk_fma_f32 v[36:37], v[40:41], v[36:37], v[138:139] op_sel_hi:[0,1,1]
	s_waitcnt lgkmcnt(1)
	v_mov_b32_e32 v72, v19
	s_waitcnt lgkmcnt(0)
; __device__ __forceinline__ void dsa_item(const KP& p, int b, int tile, char* smem) {
;     ...
;         for (int i = 0; i < 8; ++i) {
;           const int pos = (g8 * 8 + i) * 8 + rs;
;           const int s = (pos < nsel) ? (int)sel[tk * 256 + pos] : 0;
;           vv[i] = *(const h8*)(ub + (size_t)s * NU + C_BV + dc * 8);
;         }
; #pragma unroll
;         for (int i = 0; i < 8; ++i) {
;           const int pos = (g8 * 8 + i) * 8 + rs;
;           const f32x4 pa = *(const f32x4*)&pbuf[pos * 8];
;           const f32x4 pb = *(const f32x4*)&pbuf[pos * 8 + 4];
;           float vf[8];
; #pragma unroll
;           for (int e = 0; e < 8; ++e) vf[e] = (float)vv[i][e];
; #pragma unroll
;           for (int e = 0; e < 8; ++e) {
;             acc[0][e] += pa[0] * vf[e]; acc[1][e] += pa[1] * vf[e]; acc[2][e] += pa[2] * vf[e]; acc[3][e] += pa[3] * vf[e];
;             acc[4][e] += pb[0] * vf[e]; acc[5][e] += pb[1] * vf[e]; acc[6][e] += pb[2] * vf[e]; acc[7][e] += pb[3] * vf[e];
;           }
	v_mov_b32_e32 v74, v23
	v_pk_fma_f32 v[138:139], v[22:23], v[48:49], v[2:3] op_sel_hi:[0,1,1]
	v_pk_fma_f32 v[2:3], v[4:5], v[42:43], v[14:15] op_sel_hi:[0,1,1]
	v_pk_fma_f32 v[14:15], v[4:5], v[42:43], v[26:27] op_sel:[1,0,0]
	v_pk_fma_f32 v[26:27], v[6:7], v[42:43], v[128:129] op_sel_hi:[0,1,1]
	v_pk_fma_f32 v[104:105], v[202:203], v[188:189], v[104:105] op_sel_hi:[0,1,1]
	v_pk_fma_f32 v[114:115], v[176:177], v[188:189], v[114:115] op_sel_hi:[0,1,1]
	v_pk_fma_f32 v[154:155], v[16:17], v[48:49], v[52:53] op_sel_hi:[0,1,1]
	v_pk_fma_f32 v[152:153], v[16:17], v[48:49], v[54:55] op_sel:[1,0,0]
	v_pk_fma_f32 v[146:147], v[18:19], v[48:49], v[56:57] op_sel_hi:[0,1,1]
	v_pk_fma_f32 v[140:141], v[72:73], v[48:49], v[66:67] op_sel_hi:[0,1,1]
	v_pk_fma_f32 v[150:151], v[20:21], v[48:49], v[68:69] op_sel_hi:[0,1,1]
	v_pk_fma_f32 v[144:145], v[20:21], v[48:49], v[70:71] op_sel:[1,0,0]
	v_pk_fma_f32 v[148:149], v[74:75], v[48:49], v[36:37] op_sel_hi:[0,1,1]
	v_pk_fma_f32 v[36:37], v[38:39], v[42:43], v[120:121] op_sel_hi:[0,1,1]
	v_pk_fma_f32 v[48:49], v[8:9], v[42:43], v[134:135] op_sel_hi:[0,1,1]
	v_pk_fma_f32 v[52:53], v[8:9], v[42:43], v[130:131] op_sel:[1,0,0]
	v_pk_fma_f32 v[54:55], v[10:11], v[42:43], v[122:123] op_sel_hi:[0,1,1]
	v_pk_fma_f32 v[42:43], v[40:41], v[42:43], v[132:133] op_sel_hi:[0,1,1]
	v_pk_fma_f32 v[142:143], v[16:17], v[30:31], v[2:3] op_sel_hi:[0,1,1]
	v_pk_fma_f32 v[134:135], v[16:17], v[30:31], v[14:15] op_sel:[1,0,0]
	v_pk_fma_f32 v[128:129], v[18:19], v[30:31], v[26:27] op_sel_hi:[0,1,1]
	v_pk_fma_f32 v[2:3], v[4:5], v[44:45], v[124:125] op_sel_hi:[0,1,1]
	v_pk_fma_f32 v[14:15], v[4:5], v[44:45], v[116:117] op_sel:[1,0,0]
	v_pk_fma_f32 v[26:27], v[6:7], v[44:45], v[110:111] op_sel_hi:[0,1,1]
	v_pk_fma_f32 v[120:121], v[72:73], v[30:31], v[36:37] op_sel_hi:[0,1,1]
	v_pk_fma_f32 v[136:137], v[20:21], v[30:31], v[48:49] op_sel_hi:[0,1,1]
	v_pk_fma_f32 v[130:131], v[20:21], v[30:31], v[52:53] op_sel:[1,0,0]
	v_pk_fma_f32 v[122:123], v[22:23], v[30:31], v[54:55] op_sel_hi:[0,1,1]
	v_pk_fma_f32 v[132:133], v[74:75], v[30:31], v[42:43] op_sel_hi:[0,1,1]
	v_pk_fma_f32 v[30:31], v[38:39], v[44:45], v[104:105] op_sel_hi:[0,1,1]
	v_pk_fma_f32 v[36:37], v[8:9], v[44:45], v[118:119] op_sel_hi:[0,1,1]
	v_pk_fma_f32 v[42:43], v[8:9], v[44:45], v[112:113] op_sel:[1,0,0]
	v_pk_fma_f32 v[48:49], v[10:11], v[44:45], v[106:107] op_sel_hi:[0,1,1]
	v_pk_fma_f32 v[44:45], v[40:41], v[44:45], v[114:115] op_sel_hi:[0,1,1]
	v_pk_fma_f32 v[124:125], v[16:17], v[50:51], v[2:3] op_sel_hi:[0,1,1]
	v_pk_fma_f32 v[116:117], v[16:17], v[50:51], v[14:15] op_sel:[1,0,0]
	v_pk_fma_f32 v[110:111], v[18:19], v[50:51], v[26:27] op_sel_hi:[0,1,1]
	v_pk_fma_f32 v[2:3], v[4:5], v[46:47], v[28:29] op_sel_hi:[0,1,1]
	v_pk_fma_f32 v[4:5], v[4:5], v[46:47], v[58:59] op_sel:[1,0,0]
	v_pk_fma_f32 v[6:7], v[6:7], v[46:47], v[60:61] op_sel_hi:[0,1,1]
	v_pk_fma_f32 v[14:15], v[38:39], v[46:47], v[62:63] op_sel_hi:[0,1,1]
	v_pk_fma_f32 v[26:27], v[8:9], v[46:47], v[64:65] op_sel_hi:[0,1,1]
	v_pk_fma_f32 v[8:9], v[8:9], v[46:47], v[34:35] op_sel:[1,0,0]
	v_pk_fma_f32 v[10:11], v[10:11], v[46:47], v[12:13] op_sel_hi:[0,1,1]
	v_pk_fma_f32 v[12:13], v[40:41], v[46:47], v[24:25] op_sel_hi:[0,1,1]
	v_pk_fma_f32 v[104:105], v[72:73], v[50:51], v[30:31] op_sel_hi:[0,1,1]
	v_pk_fma_f32 v[118:119], v[20:21], v[50:51], v[36:37] op_sel_hi:[0,1,1]
	v_pk_fma_f32 v[112:113], v[20:21], v[50:51], v[42:43] op_sel:[1,0,0]
	v_pk_fma_f32 v[106:107], v[22:23], v[50:51], v[48:49] op_sel_hi:[0,1,1]
	v_pk_fma_f32 v[114:115], v[74:75], v[50:51], v[44:45] op_sel_hi:[0,1,1]
	v_pk_fma_f32 v[108:109], v[16:17], v[32:33], v[2:3] op_sel_hi:[0,1,1]
	v_pk_fma_f32 v[100:101], v[16:17], v[32:33], v[4:5] op_sel:[1,0,0]
	v_pk_fma_f32 v[94:95], v[18:19], v[32:33], v[6:7] op_sel_hi:[0,1,1]
	v_pk_fma_f32 v[90:91], v[72:73], v[32:33], v[14:15] op_sel_hi:[0,1,1]
	v_pk_fma_f32 v[102:103], v[20:21], v[32:33], v[26:27] op_sel_hi:[0,1,1]
	v_pk_fma_f32 v[96:97], v[20:21], v[32:33], v[8:9] op_sel:[1,0,0]
	v_pk_fma_f32 v[92:93], v[22:23], v[32:33], v[10:11] op_sel_hi:[0,1,1]
	v_pk_fma_f32 v[98:99], v[74:75], v[32:33], v[12:13] op_sel_hi:[0,1,1]
	v_add_u32_e32 v172, 0x800, v172
	v_lshlrev_b32_e32 v35, 8, v159
	v_lshl_add_u32 v35, v165, 2, v35
	v_add_u32_e32 v35, 0xcc00, v35
	ds_read_b32 v2, v35 offset:512
	ds_read_b32 v6, v35 offset:544
	ds_read_b32 v10, v35 offset:576
	ds_read_b32 v14, v35 offset:608
	ds_read_b32 v22, v35 offset:640
	ds_read_b32 v26, v35 offset:672
	ds_read_b32 v18, v35 offset:704
	ds_read_b32 v30, v35 offset:736
	s_waitcnt lgkmcnt(7)
	v_add_u32_e32 v2, v2, v0
	global_load_dwordx4 v[2:5], v2, s[2:3]
	s_waitcnt lgkmcnt(6)
	v_add_u32_e32 v6, v6, v0
	global_load_dwordx4 v[6:9], v6, s[2:3]
	s_waitcnt lgkmcnt(5)
	v_add_u32_e32 v10, v10, v0
	global_load_dwordx4 v[10:13], v10, s[2:3]
	s_waitcnt lgkmcnt(4)
	v_add_u32_e32 v14, v14, v0
	global_load_dwordx4 v[14:17], v14, s[2:3]
	s_waitcnt lgkmcnt(3)
	v_add_u32_e32 v22, v22, v0
	global_load_dwordx4 v[22:25], v22, s[2:3]
	s_waitcnt lgkmcnt(2)
	v_add_u32_e32 v26, v26, v0
	global_load_dwordx4 v[26:29], v26, s[2:3]
	s_waitcnt lgkmcnt(1)
	v_add_u32_e32 v18, v18, v0
	global_load_dwordx4 v[18:21], v18, s[2:3]
	s_waitcnt lgkmcnt(0)
	v_add_u32_e32 v30, v30, v0
	global_load_dwordx4 v[30:33], v30, s[2:3]
	s_waitcnt vmcnt(15)
	v_cvt_f32_f16_sdwa v175, v204 dst_sel:DWORD dst_unused:UNUSED_PAD src0_sel:WORD_1
	v_cvt_f32_f16_e32 v174, v204
	s_waitcnt vmcnt(14)
; __device__ __forceinline__ void dsa_item(const KP& p, int b, int tile, char* smem) {
;     ...
; #pragma unroll
;         for (int i = 0; i < 8; ++i) {
;           const int pos = (g8 * 8 + i) * 8 + rs;
;           const f32x4 pa = *(const f32x4*)&pbuf[pos * 8];
;           const f32x4 pb = *(const f32x4*)&pbuf[pos * 8 + 4];
;           float vf[8];
; #pragma unroll
;           for (int e = 0; e < 8; ++e) vf[e] = (float)vv[i][e];
; #pragma unroll
;           for (int e = 0; e < 8; ++e) {
;             acc[0][e] += pa[0] * vf[e]; acc[1][e] += pa[1] * vf[e]; acc[2][e] += pa[2] * vf[e]; acc[3][e] += pa[3] * vf[e];
;             acc[4][e] += pb[0] * vf[e]; acc[5][e] += pb[1] * vf[e]; acc[6][e] += pb[2] * vf[e]; acc[7][e] += pb[3] * vf[e];
;           }
	v_cvt_f32_f16_sdwa v177, v208 dst_sel:DWORD dst_unused:UNUSED_PAD src0_sel:WORD_1
	v_cvt_f32_f16_e32 v176, v208
	ds_read_b128 v[58:61], v172
	ds_read_b128 v[34:37], v172 offset:16
	ds_read_b128 v[62:65], v172 offset:256
	ds_read_b128 v[38:41], v172 offset:272
	ds_read_b128 v[66:69], v172 offset:512
	ds_read_b128 v[42:45], v172 offset:528
	ds_read_b128 v[70:73], v172 offset:768
	ds_read_b128 v[46:49], v172 offset:784
	ds_read_b128 v[74:77], v172 offset:1024
	ds_read_b128 v[50:53], v172 offset:1040
	s_waitcnt vmcnt(13)
	v_cvt_f32_f16_sdwa v179, v212 dst_sel:DWORD dst_unused:UNUSED_PAD src0_sel:WORD_1
	v_cvt_f32_f16_e32 v178, v212
	s_waitcnt lgkmcnt(8)
	v_mov_b32_e32 v156, v37
	s_waitcnt vmcnt(12)
	v_cvt_f32_f16_sdwa v181, v216 dst_sel:DWORD dst_unused:UNUSED_PAD src0_sel:WORD_1
	v_cvt_f32_f16_e32 v180, v216
	v_pk_fma_f32 v[148:149], v[156:157], v[174:175], v[148:149] op_sel_hi:[0,1,1]
	s_waitcnt lgkmcnt(6)
	v_mov_b32_e32 v208, v41
	s_waitcnt vmcnt(11)
	v_cvt_f32_f16_sdwa v189, v224 dst_sel:DWORD dst_unused:UNUSED_PAD src0_sel:WORD_1
	v_cvt_f32_f16_e32 v188, v224
	v_pk_fma_f32 v[148:149], v[208:209], v[176:177], v[148:149] op_sel_hi:[0,1,1]
	s_waitcnt lgkmcnt(4)
	v_mov_b32_e32 v212, v45
	v_pk_fma_f32 v[148:149], v[212:213], v[178:179], v[148:149] op_sel_hi:[0,1,1]
	s_waitcnt lgkmcnt(2)
	v_mov_b32_e32 v224, v49
	v_pk_fma_f32 v[148:149], v[224:225], v[180:181], v[148:149] op_sel_hi:[0,1,1]
	s_waitcnt lgkmcnt(0)
	v_mov_b32_e32 v158, v53
	ds_read_b128 v[78:81], v172 offset:1280
	ds_read_b128 v[54:57], v172 offset:1296
	v_pk_fma_f32 v[190:191], v[158:159], v[188:189], v[148:149] op_sel_hi:[0,1,1]
	v_pk_fma_f32 v[148:149], v[58:59], v[174:175], v[154:155] op_sel_hi:[0,1,1]
	v_mov_b32_e32 v154, v61
	v_pk_fma_f32 v[152:153], v[58:59], v[174:175], v[152:153] op_sel:[1,0,0]
	v_pk_fma_f32 v[146:147], v[60:61], v[174:175], v[146:147] op_sel_hi:[0,1,1]
	v_pk_fma_f32 v[140:141], v[154:155], v[174:175], v[140:141] op_sel_hi:[0,1,1]
	v_mov_b32_e32 v194, v65
	v_pk_fma_f32 v[150:151], v[34:35], v[174:175], v[150:151] op_sel_hi:[0,1,1]
	v_pk_fma_f32 v[144:145], v[34:35], v[174:175], v[144:145] op_sel:[1,0,0]
	v_pk_fma_f32 v[138:139], v[36:37], v[174:175], v[138:139] op_sel_hi:[0,1,1]
	s_waitcnt vmcnt(10)
	v_cvt_f32_f16_sdwa v193, v228 dst_sel:DWORD dst_unused:UNUSED_PAD src0_sel:WORD_1
	v_cvt_f32_f16_e32 v192, v228
	v_pk_fma_f32 v[148:149], v[62:63], v[176:177], v[148:149] op_sel_hi:[0,1,1]
	v_pk_fma_f32 v[152:153], v[62:63], v[176:177], v[152:153] op_sel:[1,0,0]
	v_pk_fma_f32 v[146:147], v[64:65], v[176:177], v[146:147] op_sel_hi:[0,1,1]
	v_pk_fma_f32 v[140:141], v[194:195], v[176:177], v[140:141] op_sel_hi:[0,1,1]
	v_mov_b32_e32 v196, v69
	v_pk_fma_f32 v[150:151], v[38:39], v[176:177], v[150:151] op_sel_hi:[0,1,1]
	v_pk_fma_f32 v[144:145], v[38:39], v[176:177], v[144:145] op_sel:[1,0,0]
	v_pk_fma_f32 v[138:139], v[40:41], v[176:177], v[138:139] op_sel_hi:[0,1,1]
	v_cvt_f32_f16_sdwa v175, v205 dst_sel:DWORD dst_unused:UNUSED_PAD src0_sel:WORD_1
	v_cvt_f32_f16_e32 v174, v205
	v_pk_fma_f32 v[148:149], v[66:67], v[178:179], v[148:149] op_sel_hi:[0,1,1]
	v_pk_fma_f32 v[152:153], v[66:67], v[178:179], v[152:153] op_sel:[1,0,0]
	v_pk_fma_f32 v[146:147], v[68:69], v[178:179], v[146:147] op_sel_hi:[0,1,1]
	v_pk_fma_f32 v[140:141], v[196:197], v[178:179], v[140:141] op_sel_hi:[0,1,1]
	v_mov_b32_e32 v198, v73
	v_pk_fma_f32 v[150:151], v[42:43], v[178:179], v[150:151] op_sel_hi:[0,1,1]
	v_pk_fma_f32 v[144:145], v[42:43], v[178:179], v[144:145] op_sel:[1,0,0]
	v_pk_fma_f32 v[138:139], v[44:45], v[178:179], v[138:139] op_sel_hi:[0,1,1]
	v_cvt_f32_f16_sdwa v179, v209 dst_sel:DWORD dst_unused:UNUSED_PAD src0_sel:WORD_1
	v_cvt_f32_f16_e32 v178, v209
	v_pk_fma_f32 v[148:149], v[70:71], v[180:181], v[148:149] op_sel_hi:[0,1,1]
	v_pk_fma_f32 v[152:153], v[70:71], v[180:181], v[152:153] op_sel:[1,0,0]
	v_pk_fma_f32 v[146:147], v[72:73], v[180:181], v[146:147] op_sel_hi:[0,1,1]
	v_pk_fma_f32 v[140:141], v[198:199], v[180:181], v[140:141] op_sel_hi:[0,1,1]
	v_mov_b32_e32 v200, v77
	v_pk_fma_f32 v[150:151], v[46:47], v[180:181], v[150:151] op_sel_hi:[0,1,1]
	v_pk_fma_f32 v[144:145], v[46:47], v[180:181], v[144:145] op_sel:[1,0,0]
	v_pk_fma_f32 v[138:139], v[48:49], v[180:181], v[138:139] op_sel_hi:[0,1,1]
	v_cvt_f32_f16_sdwa v181, v213 dst_sel:DWORD dst_unused:UNUSED_PAD src0_sel:WORD_1
	v_cvt_f32_f16_e32 v180, v213
	v_pk_fma_f32 v[148:149], v[74:75], v[188:189], v[148:149] op_sel_hi:[0,1,1]
	v_pk_fma_f32 v[152:153], v[74:75], v[188:189], v[152:153] op_sel:[1,0,0]
	v_pk_fma_f32 v[146:147], v[76:77], v[188:189], v[146:147] op_sel_hi:[0,1,1]
	v_pk_fma_f32 v[140:141], v[200:201], v[188:189], v[140:141] op_sel_hi:[0,1,1]
	v_pk_fma_f32 v[150:151], v[50:51], v[188:189], v[150:151] op_sel_hi:[0,1,1]
	v_pk_fma_f32 v[144:145], v[50:51], v[188:189], v[144:145] op_sel:[1,0,0]
	v_pk_fma_f32 v[138:139], v[52:53], v[188:189], v[138:139] op_sel_hi:[0,1,1]
	s_waitcnt lgkmcnt(0)
; __device__ __forceinline__ void dsa_item(const KP& p, int b, int tile, char* smem) {
;     ...
; #pragma unroll
;         for (int i = 0; i < 8; ++i) {
;           const int pos = (g8 * 8 + i) * 8 + rs;
;           const f32x4 pa = *(const f32x4*)&pbuf[pos * 8];
;           const f32x4 pb = *(const f32x4*)&pbuf[pos * 8 + 4];
;           float vf[8];
; #pragma unroll
;           for (int e = 0; e < 8; ++e) vf[e] = (float)vv[i][e];
; #pragma unroll
;           for (int e = 0; e < 8; ++e) {
;             acc[0][e] += pa[0] * vf[e]; acc[1][e] += pa[1] * vf[e]; acc[2][e] += pa[2] * vf[e]; acc[3][e] += pa[3] * vf[e];
;             acc[4][e] += pb[0] * vf[e]; acc[5][e] += pb[1] * vf[e]; acc[6][e] += pb[2] * vf[e]; acc[7][e] += pb[3] * vf[e];
;           }
	v_mov_b32_e32 v176, v57
	v_cvt_f32_f16_sdwa v189, v217 dst_sel:DWORD dst_unused:UNUSED_PAD src0_sel:WORD_1
	v_cvt_f32_f16_e32 v188, v217
	v_pk_fma_f32 v[204:205], v[56:57], v[192:193], v[138:139] op_sel_hi:[0,1,1]
	v_pk_fma_f32 v[138:139], v[176:177], v[192:193], v[190:191] op_sel_hi:[0,1,1]
	v_pk_fma_f32 v[132:133], v[156:157], v[174:175], v[132:133] op_sel_hi:[0,1,1]
	v_cvt_f32_f16_sdwa v191, v225 dst_sel:DWORD dst_unused:UNUSED_PAD src0_sel:WORD_1
	v_cvt_f32_f16_e32 v190, v225
	v_pk_fma_f32 v[216:217], v[208:209], v[178:179], v[132:133] op_sel_hi:[0,1,1]
	v_mov_b32_e32 v202, v81
	v_pk_fma_f32 v[216:217], v[212:213], v[180:181], v[216:217] op_sel_hi:[0,1,1]
	v_pk_fma_f32 v[148:149], v[78:79], v[192:193], v[148:149] op_sel_hi:[0,1,1]
	v_pk_fma_f32 v[152:153], v[78:79], v[192:193], v[152:153] op_sel:[1,0,0]
	v_pk_fma_f32 v[146:147], v[80:81], v[192:193], v[146:147] op_sel_hi:[0,1,1]
	v_pk_fma_f32 v[140:141], v[202:203], v[192:193], v[140:141] op_sel_hi:[0,1,1]
	v_pk_fma_f32 v[150:151], v[54:55], v[192:193], v[150:151] op_sel_hi:[0,1,1]
	v_pk_fma_f32 v[144:145], v[54:55], v[192:193], v[144:145] op_sel:[1,0,0]
	v_pk_fma_f32 v[216:217], v[224:225], v[188:189], v[216:217] op_sel_hi:[0,1,1]
	v_cvt_f32_f16_sdwa v193, v229 dst_sel:DWORD dst_unused:UNUSED_PAD src0_sel:WORD_1
	v_cvt_f32_f16_e32 v192, v229
	v_pk_fma_f32 v[228:229], v[58:59], v[174:175], v[134:135] op_sel:[1,0,0]
	v_pk_fma_f32 v[134:135], v[34:35], v[174:175], v[136:137] op_sel_hi:[0,1,1]
	v_cvt_f32_f16_sdwa v137, v206 dst_sel:DWORD dst_unused:UNUSED_PAD src0_sel:WORD_1
	v_cvt_f32_f16_e32 v136, v206
	v_pk_fma_f32 v[132:133], v[158:159], v[190:191], v[216:217] op_sel_hi:[0,1,1]
	v_pk_fma_f32 v[216:217], v[58:59], v[174:175], v[142:143] op_sel_hi:[0,1,1]
	v_cvt_f32_f16_sdwa v143, v210 dst_sel:DWORD dst_unused:UNUSED_PAD src0_sel:WORD_1
	v_cvt_f32_f16_e32 v142, v210
	v_pk_fma_f32 v[128:129], v[60:61], v[174:175], v[128:129] op_sel_hi:[0,1,1]
	v_pk_fma_f32 v[120:121], v[154:155], v[174:175], v[120:121] op_sel_hi:[0,1,1]
	v_pk_fma_f32 v[130:131], v[34:35], v[174:175], v[130:131] op_sel:[1,0,0]
	v_pk_fma_f32 v[122:123], v[36:37], v[174:175], v[122:123] op_sel_hi:[0,1,1]
	v_cvt_f32_f16_sdwa v175, v214 dst_sel:DWORD dst_unused:UNUSED_PAD src0_sel:WORD_1
	v_cvt_f32_f16_e32 v174, v214
	v_pk_fma_f32 v[216:217], v[62:63], v[178:179], v[216:217] op_sel_hi:[0,1,1]
	v_pk_fma_f32 v[228:229], v[62:63], v[178:179], v[228:229] op_sel:[1,0,0]
	v_pk_fma_f32 v[128:129], v[64:65], v[178:179], v[128:129] op_sel_hi:[0,1,1]
	v_pk_fma_f32 v[120:121], v[194:195], v[178:179], v[120:121] op_sel_hi:[0,1,1]
	v_pk_fma_f32 v[134:135], v[38:39], v[178:179], v[134:135] op_sel_hi:[0,1,1]
	v_pk_fma_f32 v[130:131], v[38:39], v[178:179], v[130:131] op_sel:[1,0,0]
	v_pk_fma_f32 v[122:123], v[40:41], v[178:179], v[122:123] op_sel_hi:[0,1,1]
	v_cvt_f32_f16_sdwa v179, v218 dst_sel:DWORD dst_unused:UNUSED_PAD src0_sel:WORD_1
	v_cvt_f32_f16_e32 v178, v218
	v_pk_fma_f32 v[216:217], v[66:67], v[180:181], v[216:217] op_sel_hi:[0,1,1]
	v_pk_fma_f32 v[228:229], v[66:67], v[180:181], v[228:229] op_sel:[1,0,0]
	v_pk_fma_f32 v[128:129], v[68:69], v[180:181], v[128:129] op_sel_hi:[0,1,1]
	v_pk_fma_f32 v[120:121], v[196:197], v[180:181], v[120:121] op_sel_hi:[0,1,1]
	v_pk_fma_f32 v[134:135], v[42:43], v[180:181], v[134:135] op_sel_hi:[0,1,1]
	v_pk_fma_f32 v[130:131], v[42:43], v[180:181], v[130:131] op_sel:[1,0,0]
	v_pk_fma_f32 v[122:123], v[44:45], v[180:181], v[122:123] op_sel_hi:[0,1,1]
	v_cvt_f32_f16_sdwa v181, v226 dst_sel:DWORD dst_unused:UNUSED_PAD src0_sel:WORD_1
	v_cvt_f32_f16_e32 v180, v226
	v_pk_fma_f32 v[106:107], v[36:37], v[136:137], v[106:107] op_sel_hi:[0,1,1]
	v_pk_fma_f32 v[216:217], v[70:71], v[188:189], v[216:217] op_sel_hi:[0,1,1]
	v_pk_fma_f32 v[228:229], v[70:71], v[188:189], v[228:229] op_sel:[1,0,0]
	v_pk_fma_f32 v[128:129], v[72:73], v[188:189], v[128:129] op_sel_hi:[0,1,1]
	v_pk_fma_f32 v[120:121], v[198:199], v[188:189], v[120:121] op_sel_hi:[0,1,1]
	v_pk_fma_f32 v[134:135], v[46:47], v[188:189], v[134:135] op_sel_hi:[0,1,1]
	v_pk_fma_f32 v[130:131], v[46:47], v[188:189], v[130:131] op_sel:[1,0,0]
	v_pk_fma_f32 v[122:123], v[48:49], v[188:189], v[122:123] op_sel_hi:[0,1,1]
	v_pk_fma_f32 v[114:115], v[156:157], v[136:137], v[114:115] op_sel_hi:[0,1,1]
	v_cvt_f32_f16_sdwa v189, v230 dst_sel:DWORD dst_unused:UNUSED_PAD src0_sel:WORD_1
	v_cvt_f32_f16_e32 v188, v230
	v_pk_fma_f32 v[124:125], v[58:59], v[136:137], v[124:125] op_sel_hi:[0,1,1]
	v_pk_fma_f32 v[116:117], v[58:59], v[136:137], v[116:117] op_sel:[1,0,0]
	v_pk_fma_f32 v[110:111], v[60:61], v[136:137], v[110:111] op_sel_hi:[0,1,1]
	v_pk_fma_f32 v[104:105], v[154:155], v[136:137], v[104:105] op_sel_hi:[0,1,1]
	v_pk_fma_f32 v[118:119], v[34:35], v[136:137], v[118:119] op_sel_hi:[0,1,1]
	v_pk_fma_f32 v[112:113], v[34:35], v[136:137], v[112:113] op_sel:[1,0,0]
	v_pk_fma_f32 v[106:107], v[40:41], v[142:143], v[106:107] op_sel_hi:[0,1,1]
	v_cvt_f32_f16_sdwa v137, v207 dst_sel:DWORD dst_unused:UNUSED_PAD src0_sel:WORD_1
	v_cvt_f32_f16_e32 v136, v207
	v_pk_fma_f32 v[106:107], v[44:45], v[174:175], v[106:107] op_sel_hi:[0,1,1]
	v_pk_fma_f32 v[106:107], v[48:49], v[178:179], v[106:107] op_sel_hi:[0,1,1]
	v_pk_fma_f32 v[206:207], v[52:53], v[180:181], v[106:107] op_sel_hi:[0,1,1]
	v_pk_fma_f32 v[106:107], v[56:57], v[188:189], v[206:207] op_sel_hi:[0,1,1]
	v_pk_fma_f32 v[206:207], v[156:157], v[136:137], v[98:99] op_sel_hi:[0,1,1]
	v_cvt_f32_f16_sdwa v99, v211 dst_sel:DWORD dst_unused:UNUSED_PAD src0_sel:WORD_1
	v_cvt_f32_f16_e32 v98, v211
	v_cvt_f32_f16_sdwa v211, v215 dst_sel:DWORD dst_unused:UNUSED_PAD src0_sel:WORD_1
	v_cvt_f32_f16_e32 v210, v215
; __device__ __forceinline__ void dsa_item(const KP& p, int b, int tile, char* smem) {
;     ...
; #pragma unroll
;         for (int i = 0; i < 8; ++i) {
;           const int pos = (g8 * 8 + i) * 8 + rs;
;           const f32x4 pa = *(const f32x4*)&pbuf[pos * 8];
;           const f32x4 pb = *(const f32x4*)&pbuf[pos * 8 + 4];
;           float vf[8];
; #pragma unroll
;           for (int e = 0; e < 8; ++e) vf[e] = (float)vv[i][e];
; #pragma unroll
;           for (int e = 0; e < 8; ++e) {
;             acc[0][e] += pa[0] * vf[e]; acc[1][e] += pa[1] * vf[e]; acc[2][e] += pa[2] * vf[e]; acc[3][e] += pa[3] * vf[e];
;             acc[4][e] += pb[0] * vf[e]; acc[5][e] += pb[1] * vf[e]; acc[6][e] += pb[2] * vf[e]; acc[7][e] += pb[3] * vf[e];
;           }
	v_cvt_f32_f16_sdwa v215, v219 dst_sel:DWORD dst_unused:UNUSED_PAD src0_sel:WORD_1
	v_cvt_f32_f16_e32 v214, v219
	v_cvt_f32_f16_sdwa v219, v227 dst_sel:DWORD dst_unused:UNUSED_PAD src0_sel:WORD_1
	v_cvt_f32_f16_e32 v218, v227
	v_pk_fma_f32 v[206:207], v[208:209], v[98:99], v[206:207] op_sel_hi:[0,1,1]
	v_pk_fma_f32 v[114:115], v[208:209], v[142:143], v[114:115] op_sel_hi:[0,1,1]
	v_pk_fma_f32 v[206:207], v[212:213], v[210:211], v[206:207] op_sel_hi:[0,1,1]
	v_pk_fma_f32 v[114:115], v[212:213], v[174:175], v[114:115] op_sel_hi:[0,1,1]
	v_pk_fma_f32 v[206:207], v[224:225], v[214:215], v[206:207] op_sel_hi:[0,1,1]
	v_pk_fma_f32 v[114:115], v[224:225], v[178:179], v[114:115] op_sel_hi:[0,1,1]
	v_pk_fma_f32 v[224:225], v[158:159], v[218:219], v[206:207] op_sel_hi:[0,1,1]
	v_pk_fma_f32 v[206:207], v[58:59], v[136:137], v[108:109] op_sel_hi:[0,1,1]
	v_cvt_f32_f16_sdwa v227, v231 dst_sel:DWORD dst_unused:UNUSED_PAD src0_sel:WORD_1
	v_cvt_f32_f16_e32 v226, v231
	v_pk_fma_f32 v[206:207], v[62:63], v[98:99], v[206:207] op_sel_hi:[0,1,1]
	v_pk_fma_f32 v[206:207], v[66:67], v[210:211], v[206:207] op_sel_hi:[0,1,1]
	v_pk_fma_f32 v[206:207], v[70:71], v[214:215], v[206:207] op_sel_hi:[0,1,1]
	v_pk_fma_f32 v[206:207], v[74:75], v[218:219], v[206:207] op_sel_hi:[0,1,1]
	v_pk_fma_f32 v[230:231], v[78:79], v[226:227], v[206:207] op_sel_hi:[0,1,1]
	v_pk_fma_f32 v[206:207], v[58:59], v[136:137], v[100:101] op_sel:[1,0,0]
	v_pk_fma_f32 v[124:125], v[62:63], v[142:143], v[124:125] op_sel_hi:[0,1,1]
	v_pk_fma_f32 v[206:207], v[62:63], v[98:99], v[206:207] op_sel:[1,0,0]
	v_pk_fma_f32 v[116:117], v[62:63], v[142:143], v[116:117] op_sel:[1,0,0]
	v_pk_fma_f32 v[206:207], v[66:67], v[210:211], v[206:207] op_sel:[1,0,0]
	v_pk_fma_f32 v[110:111], v[64:65], v[142:143], v[110:111] op_sel_hi:[0,1,1]
	v_pk_fma_f32 v[206:207], v[70:71], v[214:215], v[206:207] op_sel:[1,0,0]
	v_pk_fma_f32 v[118:119], v[38:39], v[142:143], v[118:119] op_sel_hi:[0,1,1]
	v_pk_fma_f32 v[206:207], v[74:75], v[218:219], v[206:207] op_sel:[1,0,0]
	v_pk_fma_f32 v[112:113], v[38:39], v[142:143], v[112:113] op_sel:[1,0,0]
	v_pk_fma_f32 v[58:59], v[78:79], v[226:227], v[206:207] op_sel:[1,0,0]
	v_pk_fma_f32 v[206:207], v[60:61], v[136:137], v[94:95] op_sel_hi:[0,1,1]
	v_pk_fma_f32 v[206:207], v[64:65], v[98:99], v[206:207] op_sel_hi:[0,1,1]
	v_pk_fma_f32 v[206:207], v[68:69], v[210:211], v[206:207] op_sel_hi:[0,1,1]
	v_pk_fma_f32 v[206:207], v[72:73], v[214:215], v[206:207] op_sel_hi:[0,1,1]
	v_pk_fma_f32 v[206:207], v[76:77], v[218:219], v[206:207] op_sel_hi:[0,1,1]
	v_pk_fma_f32 v[60:61], v[80:81], v[226:227], v[206:207] op_sel_hi:[0,1,1]
	v_pk_fma_f32 v[206:207], v[154:155], v[136:137], v[90:91] op_sel_hi:[0,1,1]
	v_pk_fma_f32 v[206:207], v[194:195], v[98:99], v[206:207] op_sel_hi:[0,1,1]
	v_pk_fma_f32 v[206:207], v[196:197], v[210:211], v[206:207] op_sel_hi:[0,1,1]
	v_pk_fma_f32 v[206:207], v[198:199], v[214:215], v[206:207] op_sel_hi:[0,1,1]
	v_pk_fma_f32 v[206:207], v[200:201], v[218:219], v[206:207] op_sel_hi:[0,1,1]
	v_pk_fma_f32 v[62:63], v[202:203], v[226:227], v[206:207] op_sel_hi:[0,1,1]
	v_pk_fma_f32 v[206:207], v[34:35], v[136:137], v[102:103] op_sel_hi:[0,1,1]
	v_pk_fma_f32 v[206:207], v[38:39], v[98:99], v[206:207] op_sel_hi:[0,1,1]
	v_pk_fma_f32 v[206:207], v[42:43], v[210:211], v[206:207] op_sel_hi:[0,1,1]
	v_pk_fma_f32 v[206:207], v[46:47], v[214:215], v[206:207] op_sel_hi:[0,1,1]
	v_pk_fma_f32 v[206:207], v[50:51], v[218:219], v[206:207] op_sel_hi:[0,1,1]
	v_pk_fma_f32 v[64:65], v[54:55], v[226:227], v[206:207] op_sel_hi:[0,1,1]
	v_pk_fma_f32 v[206:207], v[34:35], v[136:137], v[96:97] op_sel:[1,0,0]
	v_pk_fma_f32 v[118:119], v[42:43], v[174:175], v[118:119] op_sel_hi:[0,1,1]
	v_pk_fma_f32 v[206:207], v[38:39], v[98:99], v[206:207] op_sel:[1,0,0]
	v_pk_fma_f32 v[112:113], v[42:43], v[174:175], v[112:113] op_sel:[1,0,0]
	v_pk_fma_f32 v[206:207], v[42:43], v[210:211], v[206:207] op_sel:[1,0,0]
	v_pk_fma_f32 v[118:119], v[46:47], v[178:179], v[118:119] op_sel_hi:[0,1,1]
	v_pk_fma_f32 v[206:207], v[46:47], v[214:215], v[206:207] op_sel:[1,0,0]
	v_pk_fma_f32 v[112:113], v[46:47], v[178:179], v[112:113] op_sel:[1,0,0]
	v_pk_fma_f32 v[206:207], v[50:51], v[218:219], v[206:207] op_sel:[1,0,0]
	s_waitcnt vmcnt(9)
	v_cvt_f32_f16_sdwa v43, v221 dst_sel:DWORD dst_unused:UNUSED_PAD src0_sel:WORD_1
	v_pk_fma_f32 v[34:35], v[54:55], v[226:227], v[206:207] op_sel:[1,0,0]
	v_pk_fma_f32 v[206:207], v[36:37], v[136:137], v[92:93] op_sel_hi:[0,1,1]
	v_pk_fma_f32 v[206:207], v[40:41], v[98:99], v[206:207] op_sel_hi:[0,1,1]
	v_pk_fma_f32 v[206:207], v[44:45], v[210:211], v[206:207] op_sel_hi:[0,1,1]
	v_pk_fma_f32 v[206:207], v[48:49], v[214:215], v[206:207] op_sel_hi:[0,1,1]
	v_pk_fma_f32 v[206:207], v[52:53], v[218:219], v[206:207] op_sel_hi:[0,1,1]
	v_pk_fma_f32 v[214:215], v[56:57], v[226:227], v[206:207] op_sel_hi:[0,1,1]
	ds_read_b128 v[206:209], v172 offset:1536
	ds_read_b128 v[210:213], v172 offset:1552
	v_pk_fma_f32 v[226:227], v[176:177], v[226:227], v[224:225] op_sel_hi:[0,1,1]
	v_cvt_f32_f16_sdwa v37, v220 dst_sel:DWORD dst_unused:UNUSED_PAD src0_sel:WORD_1
	v_cvt_f32_f16_e32 v36, v220
	v_cvt_f32_f16_e32 v42, v221
	v_cvt_f32_f16_sdwa v45, v222 dst_sel:DWORD dst_unused:UNUSED_PAD src0_sel:WORD_1
	v_cvt_f32_f16_e32 v44, v222
	v_cvt_f32_f16_sdwa v47, v223 dst_sel:DWORD dst_unused:UNUSED_PAD src0_sel:WORD_1
	v_cvt_f32_f16_e32 v46, v223
	ds_read_b128 v[218:221], v172 offset:1792
	ds_read_b128 v[222:225], v172 offset:1808
	s_waitcnt vmcnt(8)
; __device__ __forceinline__ void dsa_item(const KP& p, int b, int tile, char* smem) {
;     ...
; #pragma unroll
;         for (int i = 0; i < 8; ++i) {
;           const int pos = (g8 * 8 + i) * 8 + rs;
;           const f32x4 pa = *(const f32x4*)&pbuf[pos * 8];
;           const f32x4 pb = *(const f32x4*)&pbuf[pos * 8 + 4];
;           float vf[8];
; #pragma unroll
;           for (int e = 0; e < 8; ++e) vf[e] = (float)vv[i][e];
; #pragma unroll
;           for (int e = 0; e < 8; ++e) {
;             acc[0][e] += pa[0] * vf[e]; acc[1][e] += pa[1] * vf[e]; acc[2][e] += pa[2] * vf[e]; acc[3][e] += pa[3] * vf[e];
;             acc[4][e] += pb[0] * vf[e]; acc[5][e] += pb[1] * vf[e]; acc[6][e] += pb[2] * vf[e]; acc[7][e] += pb[3] * vf[e];
;           }
	v_cvt_f32_f16_e32 v48, v232
	v_cvt_f32_f16_sdwa v49, v232 dst_sel:DWORD dst_unused:UNUSED_PAD src0_sel:WORD_1
	v_pk_fma_f32 v[124:125], v[66:67], v[174:175], v[124:125] op_sel_hi:[0,1,1]
	v_pk_fma_f32 v[116:117], v[66:67], v[174:175], v[116:117] op_sel:[1,0,0]
	v_pk_fma_f32 v[110:111], v[68:69], v[174:175], v[110:111] op_sel_hi:[0,1,1]
	v_pk_fma_f32 v[104:105], v[194:195], v[142:143], v[104:105] op_sel_hi:[0,1,1]
	v_cvt_f32_f16_e32 v232, v233
	v_cvt_f32_f16_sdwa v233, v233 dst_sel:DWORD dst_unused:UNUSED_PAD src0_sel:WORD_1
	v_pk_fma_f32 v[216:217], v[74:75], v[190:191], v[216:217] op_sel_hi:[0,1,1]
	v_pk_fma_f32 v[228:229], v[74:75], v[190:191], v[228:229] op_sel:[1,0,0]
	v_pk_fma_f32 v[128:129], v[76:77], v[190:191], v[128:129] op_sel_hi:[0,1,1]
	v_pk_fma_f32 v[134:135], v[50:51], v[190:191], v[134:135] op_sel_hi:[0,1,1]
	v_pk_fma_f32 v[130:131], v[50:51], v[190:191], v[130:131] op_sel:[1,0,0]
	v_pk_fma_f32 v[124:125], v[70:71], v[178:179], v[124:125] op_sel_hi:[0,1,1]
	v_pk_fma_f32 v[116:117], v[70:71], v[178:179], v[116:117] op_sel:[1,0,0]
	v_pk_fma_f32 v[110:111], v[72:73], v[178:179], v[110:111] op_sel_hi:[0,1,1]
	v_pk_fma_f32 v[104:105], v[196:197], v[174:175], v[104:105] op_sel_hi:[0,1,1]
	v_pk_fma_f32 v[118:119], v[50:51], v[180:181], v[118:119] op_sel_hi:[0,1,1]
	v_pk_fma_f32 v[112:113], v[50:51], v[180:181], v[112:113] op_sel:[1,0,0]
	v_cvt_f32_f16_e32 v50, v234
	v_cvt_f32_f16_sdwa v51, v234 dst_sel:DWORD dst_unused:UNUSED_PAD src0_sel:WORD_1
	v_pk_fma_f32 v[216:217], v[78:79], v[192:193], v[216:217] op_sel_hi:[0,1,1]
	v_pk_fma_f32 v[228:229], v[78:79], v[192:193], v[228:229] op_sel:[1,0,0]
	v_pk_fma_f32 v[128:129], v[80:81], v[192:193], v[128:129] op_sel_hi:[0,1,1]
	v_pk_fma_f32 v[120:121], v[200:201], v[190:191], v[120:121] op_sel_hi:[0,1,1]
	v_pk_fma_f32 v[122:123], v[52:53], v[190:191], v[122:123] op_sel_hi:[0,1,1]
	v_pk_fma_f32 v[124:125], v[74:75], v[180:181], v[124:125] op_sel_hi:[0,1,1]
	v_pk_fma_f32 v[116:117], v[74:75], v[180:181], v[116:117] op_sel:[1,0,0]
	v_pk_fma_f32 v[110:111], v[76:77], v[180:181], v[110:111] op_sel_hi:[0,1,1]
	v_pk_fma_f32 v[104:105], v[198:199], v[178:179], v[104:105] op_sel_hi:[0,1,1]
	s_waitcnt lgkmcnt(3)
	v_mov_b32_e32 v38, v209
	s_waitcnt lgkmcnt(2)
	v_mov_b32_e32 v40, v213
	v_cvt_f32_f16_e32 v234, v235
	v_cvt_f32_f16_sdwa v235, v235 dst_sel:DWORD dst_unused:UNUSED_PAD src0_sel:WORD_1
	v_pk_fma_f32 v[204:205], v[212:213], v[36:37], v[204:205] op_sel_hi:[0,1,1]
	v_pk_fma_f32 v[120:121], v[202:203], v[192:193], v[120:121] op_sel_hi:[0,1,1]
	v_pk_fma_f32 v[134:135], v[54:55], v[192:193], v[134:135] op_sel_hi:[0,1,1]
	v_pk_fma_f32 v[130:131], v[54:55], v[192:193], v[130:131] op_sel:[1,0,0]
	v_pk_fma_f32 v[122:123], v[56:57], v[192:193], v[122:123] op_sel_hi:[0,1,1]
	v_pk_fma_f32 v[132:133], v[176:177], v[192:193], v[132:133] op_sel_hi:[0,1,1]
	v_pk_fma_f32 v[114:115], v[158:159], v[180:181], v[114:115] op_sel_hi:[0,1,1]
	v_pk_fma_f32 v[124:125], v[78:79], v[188:189], v[124:125] op_sel_hi:[0,1,1]
	v_pk_fma_f32 v[116:117], v[78:79], v[188:189], v[116:117] op_sel:[1,0,0]
	v_pk_fma_f32 v[110:111], v[80:81], v[188:189], v[110:111] op_sel_hi:[0,1,1]
	v_pk_fma_f32 v[104:105], v[200:201], v[180:181], v[104:105] op_sel_hi:[0,1,1]
	v_pk_fma_f32 v[118:119], v[54:55], v[188:189], v[118:119] op_sel_hi:[0,1,1]
	v_pk_fma_f32 v[112:113], v[54:55], v[188:189], v[112:113] op_sel:[1,0,0]
	v_pk_fma_f32 v[52:53], v[206:207], v[36:37], v[148:149] op_sel_hi:[0,1,1]
	v_pk_fma_f32 v[54:55], v[206:207], v[36:37], v[152:153] op_sel:[1,0,0]
	v_pk_fma_f32 v[56:57], v[208:209], v[36:37], v[146:147] op_sel_hi:[0,1,1]
	v_pk_fma_f32 v[66:67], v[38:39], v[36:37], v[140:141] op_sel_hi:[0,1,1]
	v_pk_fma_f32 v[68:69], v[210:211], v[36:37], v[150:151] op_sel_hi:[0,1,1]
	v_pk_fma_f32 v[70:71], v[210:211], v[36:37], v[144:145] op_sel:[1,0,0]
	v_pk_fma_f32 v[36:37], v[40:41], v[36:37], v[138:139] op_sel_hi:[0,1,1]
	s_waitcnt lgkmcnt(1)
	v_mov_b32_e32 v72, v221
	s_waitcnt lgkmcnt(0)
	v_mov_b32_e32 v74, v225
	v_pk_fma_f32 v[138:139], v[224:225], v[48:49], v[204:205] op_sel_hi:[0,1,1]
	v_pk_fma_f32 v[204:205], v[206:207], v[42:43], v[216:217] op_sel_hi:[0,1,1]
	v_pk_fma_f32 v[216:217], v[206:207], v[42:43], v[228:229] op_sel:[1,0,0]
	v_pk_fma_f32 v[228:229], v[208:209], v[42:43], v[128:129] op_sel_hi:[0,1,1]
	v_pk_fma_f32 v[104:105], v[202:203], v[188:189], v[104:105] op_sel_hi:[0,1,1]
	v_pk_fma_f32 v[114:115], v[176:177], v[188:189], v[114:115] op_sel_hi:[0,1,1]
	v_pk_fma_f32 v[154:155], v[218:219], v[48:49], v[52:53] op_sel_hi:[0,1,1]
	v_pk_fma_f32 v[152:153], v[218:219], v[48:49], v[54:55] op_sel:[1,0,0]
	v_pk_fma_f32 v[146:147], v[220:221], v[48:49], v[56:57] op_sel_hi:[0,1,1]
	v_pk_fma_f32 v[140:141], v[72:73], v[48:49], v[66:67] op_sel_hi:[0,1,1]
	v_pk_fma_f32 v[150:151], v[222:223], v[48:49], v[68:69] op_sel_hi:[0,1,1]
	v_pk_fma_f32 v[144:145], v[222:223], v[48:49], v[70:71] op_sel:[1,0,0]
	v_pk_fma_f32 v[148:149], v[74:75], v[48:49], v[36:37] op_sel_hi:[0,1,1]
	v_pk_fma_f32 v[36:37], v[38:39], v[42:43], v[120:121] op_sel_hi:[0,1,1]
	v_pk_fma_f32 v[48:49], v[210:211], v[42:43], v[134:135] op_sel_hi:[0,1,1]
	v_pk_fma_f32 v[52:53], v[210:211], v[42:43], v[130:131] op_sel:[1,0,0]
	v_pk_fma_f32 v[54:55], v[212:213], v[42:43], v[122:123] op_sel_hi:[0,1,1]
	v_pk_fma_f32 v[42:43], v[40:41], v[42:43], v[132:133] op_sel_hi:[0,1,1]
	v_pk_fma_f32 v[142:143], v[218:219], v[232:233], v[204:205] op_sel_hi:[0,1,1]
	v_pk_fma_f32 v[134:135], v[218:219], v[232:233], v[216:217] op_sel:[1,0,0]
	v_pk_fma_f32 v[128:129], v[220:221], v[232:233], v[228:229] op_sel_hi:[0,1,1]
	v_pk_fma_f32 v[204:205], v[206:207], v[44:45], v[124:125] op_sel_hi:[0,1,1]
; __device__ __forceinline__ void dsa_item(const KP& p, int b, int tile, char* smem) {
;     ...
;         for (int i = 0; i < 8; ++i) {
;           const int pos = (g8 * 8 + i) * 8 + rs;
;           const int s = (pos < nsel) ? (int)sel[tk * 256 + pos] : 0;
;           vv[i] = *(const h8*)(ub + (size_t)s * NU + C_BV + dc * 8);
;         }
; #pragma unroll
;         for (int i = 0; i < 8; ++i) {
;           const int pos = (g8 * 8 + i) * 8 + rs;
;           const f32x4 pa = *(const f32x4*)&pbuf[pos * 8];
;           const f32x4 pb = *(const f32x4*)&pbuf[pos * 8 + 4];
;           float vf[8];
; #pragma unroll
;           for (int e = 0; e < 8; ++e) vf[e] = (float)vv[i][e];
; #pragma unroll
;           for (int e = 0; e < 8; ++e) {
;             acc[0][e] += pa[0] * vf[e]; acc[1][e] += pa[1] * vf[e]; acc[2][e] += pa[2] * vf[e]; acc[3][e] += pa[3] * vf[e];
;             acc[4][e] += pb[0] * vf[e]; acc[5][e] += pb[1] * vf[e]; acc[6][e] += pb[2] * vf[e]; acc[7][e] += pb[3] * vf[e];
;           }
	v_pk_fma_f32 v[216:217], v[206:207], v[44:45], v[116:117] op_sel:[1,0,0]
	v_pk_fma_f32 v[228:229], v[208:209], v[44:45], v[110:111] op_sel_hi:[0,1,1]
	v_pk_fma_f32 v[120:121], v[72:73], v[232:233], v[36:37] op_sel_hi:[0,1,1]
	v_pk_fma_f32 v[136:137], v[222:223], v[232:233], v[48:49] op_sel_hi:[0,1,1]
	v_pk_fma_f32 v[130:131], v[222:223], v[232:233], v[52:53] op_sel:[1,0,0]
	v_pk_fma_f32 v[122:123], v[224:225], v[232:233], v[54:55] op_sel_hi:[0,1,1]
	v_pk_fma_f32 v[132:133], v[74:75], v[232:233], v[42:43] op_sel_hi:[0,1,1]
	v_pk_fma_f32 v[232:233], v[38:39], v[44:45], v[104:105] op_sel_hi:[0,1,1]
	v_pk_fma_f32 v[36:37], v[210:211], v[44:45], v[118:119] op_sel_hi:[0,1,1]
	v_pk_fma_f32 v[42:43], v[210:211], v[44:45], v[112:113] op_sel:[1,0,0]
	v_pk_fma_f32 v[48:49], v[212:213], v[44:45], v[106:107] op_sel_hi:[0,1,1]
	v_pk_fma_f32 v[44:45], v[40:41], v[44:45], v[114:115] op_sel_hi:[0,1,1]
	v_pk_fma_f32 v[124:125], v[218:219], v[50:51], v[204:205] op_sel_hi:[0,1,1]
	v_pk_fma_f32 v[116:117], v[218:219], v[50:51], v[216:217] op_sel:[1,0,0]
	v_pk_fma_f32 v[110:111], v[220:221], v[50:51], v[228:229] op_sel_hi:[0,1,1]
	v_pk_fma_f32 v[204:205], v[206:207], v[46:47], v[230:231] op_sel_hi:[0,1,1]
	v_pk_fma_f32 v[206:207], v[206:207], v[46:47], v[58:59] op_sel:[1,0,0]
	v_pk_fma_f32 v[208:209], v[208:209], v[46:47], v[60:61] op_sel_hi:[0,1,1]
	v_pk_fma_f32 v[216:217], v[38:39], v[46:47], v[62:63] op_sel_hi:[0,1,1]
	v_pk_fma_f32 v[228:229], v[210:211], v[46:47], v[64:65] op_sel_hi:[0,1,1]
	v_pk_fma_f32 v[210:211], v[210:211], v[46:47], v[34:35] op_sel:[1,0,0]
	v_pk_fma_f32 v[212:213], v[212:213], v[46:47], v[214:215] op_sel_hi:[0,1,1]
	v_pk_fma_f32 v[214:215], v[40:41], v[46:47], v[226:227] op_sel_hi:[0,1,1]
	v_pk_fma_f32 v[104:105], v[72:73], v[50:51], v[232:233] op_sel_hi:[0,1,1]
	v_pk_fma_f32 v[118:119], v[222:223], v[50:51], v[36:37] op_sel_hi:[0,1,1]
	v_pk_fma_f32 v[112:113], v[222:223], v[50:51], v[42:43] op_sel:[1,0,0]
	v_pk_fma_f32 v[106:107], v[224:225], v[50:51], v[48:49] op_sel_hi:[0,1,1]
	v_pk_fma_f32 v[114:115], v[74:75], v[50:51], v[44:45] op_sel_hi:[0,1,1]
	v_pk_fma_f32 v[108:109], v[218:219], v[234:235], v[204:205] op_sel_hi:[0,1,1]
	v_pk_fma_f32 v[100:101], v[218:219], v[234:235], v[206:207] op_sel:[1,0,0]
	v_pk_fma_f32 v[94:95], v[220:221], v[234:235], v[208:209] op_sel_hi:[0,1,1]
	v_pk_fma_f32 v[90:91], v[72:73], v[234:235], v[216:217] op_sel_hi:[0,1,1]
	v_pk_fma_f32 v[102:103], v[222:223], v[234:235], v[228:229] op_sel_hi:[0,1,1]
	v_pk_fma_f32 v[96:97], v[222:223], v[234:235], v[210:211] op_sel:[1,0,0]
	v_pk_fma_f32 v[92:93], v[224:225], v[234:235], v[212:213] op_sel_hi:[0,1,1]
	v_pk_fma_f32 v[98:99], v[74:75], v[234:235], v[214:215] op_sel_hi:[0,1,1]
	v_add_u32_e32 v172, 0x800, v172
	v_lshlrev_b32_e32 v35, 8, v159
	v_lshl_add_u32 v35, v165, 2, v35
	v_add_u32_e32 v35, 0xcc00, v35
	ds_read_b32 v204, v35 offset:768
	ds_read_b32 v208, v35 offset:800
	ds_read_b32 v212, v35 offset:832
	ds_read_b32 v216, v35 offset:864
	ds_read_b32 v224, v35 offset:896
	ds_read_b32 v228, v35 offset:928
	ds_read_b32 v220, v35 offset:960
	ds_read_b32 v232, v35 offset:992
	s_waitcnt lgkmcnt(7)
	v_add_u32_e32 v204, v204, v0
	global_load_dwordx4 v[204:207], v204, s[2:3]
	s_waitcnt lgkmcnt(6)
	v_add_u32_e32 v208, v208, v0
	global_load_dwordx4 v[208:211], v208, s[2:3]
	s_waitcnt lgkmcnt(5)
	v_add_u32_e32 v212, v212, v0
	global_load_dwordx4 v[212:215], v212, s[2:3]
	s_waitcnt lgkmcnt(4)
	v_add_u32_e32 v216, v216, v0
	global_load_dwordx4 v[216:219], v216, s[2:3]
	s_waitcnt lgkmcnt(3)
	v_add_u32_e32 v224, v224, v0
	global_load_dwordx4 v[224:227], v224, s[2:3]
	s_waitcnt lgkmcnt(2)
	v_add_u32_e32 v228, v228, v0
	global_load_dwordx4 v[228:231], v228, s[2:3]
	s_waitcnt lgkmcnt(1)
	v_add_u32_e32 v220, v220, v0
	global_load_dwordx4 v[220:223], v220, s[2:3]
	s_waitcnt lgkmcnt(0)
	v_add_u32_e32 v232, v232, v0
	global_load_dwordx4 v[232:235], v232, s[2:3]
	s_waitcnt vmcnt(15)
	v_cvt_f32_f16_sdwa v175, v2 dst_sel:DWORD dst_unused:UNUSED_PAD src0_sel:WORD_1
	v_cvt_f32_f16_e32 v174, v2
	s_waitcnt vmcnt(14)
	v_cvt_f32_f16_sdwa v177, v6 dst_sel:DWORD dst_unused:UNUSED_PAD src0_sel:WORD_1
	v_cvt_f32_f16_e32 v176, v6
	ds_read_b128 v[58:61], v172
	ds_read_b128 v[34:37], v172 offset:16
	ds_read_b128 v[62:65], v172 offset:256
	ds_read_b128 v[38:41], v172 offset:272
	ds_read_b128 v[66:69], v172 offset:512
	ds_read_b128 v[42:45], v172 offset:528
	ds_read_b128 v[70:73], v172 offset:768
	ds_read_b128 v[46:49], v172 offset:784
	ds_read_b128 v[74:77], v172 offset:1024
	ds_read_b128 v[50:53], v172 offset:1040
	s_waitcnt vmcnt(13)
	v_cvt_f32_f16_sdwa v179, v10 dst_sel:DWORD dst_unused:UNUSED_PAD src0_sel:WORD_1
	v_cvt_f32_f16_e32 v178, v10
	s_waitcnt lgkmcnt(8)
	v_mov_b32_e32 v156, v37
	s_waitcnt vmcnt(12)
	v_cvt_f32_f16_sdwa v181, v14 dst_sel:DWORD dst_unused:UNUSED_PAD src0_sel:WORD_1
	v_cvt_f32_f16_e32 v180, v14
	v_pk_fma_f32 v[148:149], v[156:157], v[174:175], v[148:149] op_sel_hi:[0,1,1]
	s_waitcnt lgkmcnt(6)
	v_mov_b32_e32 v6, v41
	s_waitcnt vmcnt(11)
	v_cvt_f32_f16_sdwa v189, v22 dst_sel:DWORD dst_unused:UNUSED_PAD src0_sel:WORD_1
	v_cvt_f32_f16_e32 v188, v22
	v_pk_fma_f32 v[148:149], v[6:7], v[176:177], v[148:149] op_sel_hi:[0,1,1]
	s_waitcnt lgkmcnt(4)
	v_mov_b32_e32 v10, v45
	v_pk_fma_f32 v[148:149], v[10:11], v[178:179], v[148:149] op_sel_hi:[0,1,1]
	s_waitcnt lgkmcnt(2)
	v_mov_b32_e32 v22, v49
	v_pk_fma_f32 v[148:149], v[22:23], v[180:181], v[148:149] op_sel_hi:[0,1,1]
	s_waitcnt lgkmcnt(0)
; __device__ __forceinline__ void dsa_item(const KP& p, int b, int tile, char* smem) {
;     ...
; #pragma unroll
;         for (int i = 0; i < 8; ++i) {
;           const int pos = (g8 * 8 + i) * 8 + rs;
;           const f32x4 pa = *(const f32x4*)&pbuf[pos * 8];
;           const f32x4 pb = *(const f32x4*)&pbuf[pos * 8 + 4];
;           float vf[8];
; #pragma unroll
;           for (int e = 0; e < 8; ++e) vf[e] = (float)vv[i][e];
; #pragma unroll
;           for (int e = 0; e < 8; ++e) {
;             acc[0][e] += pa[0] * vf[e]; acc[1][e] += pa[1] * vf[e]; acc[2][e] += pa[2] * vf[e]; acc[3][e] += pa[3] * vf[e];
;             acc[4][e] += pb[0] * vf[e]; acc[5][e] += pb[1] * vf[e]; acc[6][e] += pb[2] * vf[e]; acc[7][e] += pb[3] * vf[e];
;           }
	v_mov_b32_e32 v158, v53
	ds_read_b128 v[78:81], v172 offset:1280
	ds_read_b128 v[54:57], v172 offset:1296
	v_pk_fma_f32 v[190:191], v[158:159], v[188:189], v[148:149] op_sel_hi:[0,1,1]
	v_pk_fma_f32 v[148:149], v[58:59], v[174:175], v[154:155] op_sel_hi:[0,1,1]
	v_mov_b32_e32 v154, v61
	v_pk_fma_f32 v[152:153], v[58:59], v[174:175], v[152:153] op_sel:[1,0,0]
	v_pk_fma_f32 v[146:147], v[60:61], v[174:175], v[146:147] op_sel_hi:[0,1,1]
	v_pk_fma_f32 v[140:141], v[154:155], v[174:175], v[140:141] op_sel_hi:[0,1,1]
	v_mov_b32_e32 v194, v65
	v_pk_fma_f32 v[150:151], v[34:35], v[174:175], v[150:151] op_sel_hi:[0,1,1]
	v_pk_fma_f32 v[144:145], v[34:35], v[174:175], v[144:145] op_sel:[1,0,0]
	v_pk_fma_f32 v[138:139], v[36:37], v[174:175], v[138:139] op_sel_hi:[0,1,1]
	s_waitcnt vmcnt(10)
	v_cvt_f32_f16_sdwa v193, v26 dst_sel:DWORD dst_unused:UNUSED_PAD src0_sel:WORD_1
	v_cvt_f32_f16_e32 v192, v26
	v_pk_fma_f32 v[148:149], v[62:63], v[176:177], v[148:149] op_sel_hi:[0,1,1]
	v_pk_fma_f32 v[152:153], v[62:63], v[176:177], v[152:153] op_sel:[1,0,0]
	v_pk_fma_f32 v[146:147], v[64:65], v[176:177], v[146:147] op_sel_hi:[0,1,1]
	v_pk_fma_f32 v[140:141], v[194:195], v[176:177], v[140:141] op_sel_hi:[0,1,1]
	v_mov_b32_e32 v196, v69
	v_pk_fma_f32 v[150:151], v[38:39], v[176:177], v[150:151] op_sel_hi:[0,1,1]
	v_pk_fma_f32 v[144:145], v[38:39], v[176:177], v[144:145] op_sel:[1,0,0]
	v_pk_fma_f32 v[138:139], v[40:41], v[176:177], v[138:139] op_sel_hi:[0,1,1]
	v_cvt_f32_f16_sdwa v175, v3 dst_sel:DWORD dst_unused:UNUSED_PAD src0_sel:WORD_1
	v_cvt_f32_f16_e32 v174, v3
	v_pk_fma_f32 v[148:149], v[66:67], v[178:179], v[148:149] op_sel_hi:[0,1,1]
	v_pk_fma_f32 v[152:153], v[66:67], v[178:179], v[152:153] op_sel:[1,0,0]
	v_pk_fma_f32 v[146:147], v[68:69], v[178:179], v[146:147] op_sel_hi:[0,1,1]
	v_pk_fma_f32 v[140:141], v[196:197], v[178:179], v[140:141] op_sel_hi:[0,1,1]
	v_mov_b32_e32 v198, v73
	v_pk_fma_f32 v[150:151], v[42:43], v[178:179], v[150:151] op_sel_hi:[0,1,1]
	v_pk_fma_f32 v[144:145], v[42:43], v[178:179], v[144:145] op_sel:[1,0,0]
	v_pk_fma_f32 v[138:139], v[44:45], v[178:179], v[138:139] op_sel_hi:[0,1,1]
	v_cvt_f32_f16_sdwa v179, v7 dst_sel:DWORD dst_unused:UNUSED_PAD src0_sel:WORD_1
	v_cvt_f32_f16_e32 v178, v7
	v_pk_fma_f32 v[148:149], v[70:71], v[180:181], v[148:149] op_sel_hi:[0,1,1]
	v_pk_fma_f32 v[152:153], v[70:71], v[180:181], v[152:153] op_sel:[1,0,0]
	v_pk_fma_f32 v[146:147], v[72:73], v[180:181], v[146:147] op_sel_hi:[0,1,1]
	v_pk_fma_f32 v[140:141], v[198:199], v[180:181], v[140:141] op_sel_hi:[0,1,1]
	v_mov_b32_e32 v200, v77
	v_pk_fma_f32 v[150:151], v[46:47], v[180:181], v[150:151] op_sel_hi:[0,1,1]
	v_pk_fma_f32 v[144:145], v[46:47], v[180:181], v[144:145] op_sel:[1,0,0]
	v_pk_fma_f32 v[138:139], v[48:49], v[180:181], v[138:139] op_sel_hi:[0,1,1]
	v_cvt_f32_f16_sdwa v181, v11 dst_sel:DWORD dst_unused:UNUSED_PAD src0_sel:WORD_1
	v_cvt_f32_f16_e32 v180, v11
	v_pk_fma_f32 v[148:149], v[74:75], v[188:189], v[148:149] op_sel_hi:[0,1,1]
	v_pk_fma_f32 v[152:153], v[74:75], v[188:189], v[152:153] op_sel:[1,0,0]
	v_pk_fma_f32 v[146:147], v[76:77], v[188:189], v[146:147] op_sel_hi:[0,1,1]
	v_pk_fma_f32 v[140:141], v[200:201], v[188:189], v[140:141] op_sel_hi:[0,1,1]
	v_pk_fma_f32 v[150:151], v[50:51], v[188:189], v[150:151] op_sel_hi:[0,1,1]
	v_pk_fma_f32 v[144:145], v[50:51], v[188:189], v[144:145] op_sel:[1,0,0]
	v_pk_fma_f32 v[138:139], v[52:53], v[188:189], v[138:139] op_sel_hi:[0,1,1]
	s_waitcnt lgkmcnt(0)
	v_mov_b32_e32 v176, v57
	v_cvt_f32_f16_sdwa v189, v15 dst_sel:DWORD dst_unused:UNUSED_PAD src0_sel:WORD_1
	v_cvt_f32_f16_e32 v188, v15
	v_pk_fma_f32 v[2:3], v[56:57], v[192:193], v[138:139] op_sel_hi:[0,1,1]
	v_pk_fma_f32 v[138:139], v[176:177], v[192:193], v[190:191] op_sel_hi:[0,1,1]
	v_pk_fma_f32 v[132:133], v[156:157], v[174:175], v[132:133] op_sel_hi:[0,1,1]
	v_cvt_f32_f16_sdwa v191, v23 dst_sel:DWORD dst_unused:UNUSED_PAD src0_sel:WORD_1
	v_cvt_f32_f16_e32 v190, v23
	v_pk_fma_f32 v[14:15], v[6:7], v[178:179], v[132:133] op_sel_hi:[0,1,1]
	v_mov_b32_e32 v202, v81
	v_pk_fma_f32 v[14:15], v[10:11], v[180:181], v[14:15] op_sel_hi:[0,1,1]
	v_pk_fma_f32 v[148:149], v[78:79], v[192:193], v[148:149] op_sel_hi:[0,1,1]
	v_pk_fma_f32 v[152:153], v[78:79], v[192:193], v[152:153] op_sel:[1,0,0]
	v_pk_fma_f32 v[146:147], v[80:81], v[192:193], v[146:147] op_sel_hi:[0,1,1]
	v_pk_fma_f32 v[140:141], v[202:203], v[192:193], v[140:141] op_sel_hi:[0,1,1]
	v_pk_fma_f32 v[150:151], v[54:55], v[192:193], v[150:151] op_sel_hi:[0,1,1]
	v_pk_fma_f32 v[144:145], v[54:55], v[192:193], v[144:145] op_sel:[1,0,0]
	v_pk_fma_f32 v[14:15], v[22:23], v[188:189], v[14:15] op_sel_hi:[0,1,1]
	v_cvt_f32_f16_sdwa v193, v27 dst_sel:DWORD dst_unused:UNUSED_PAD src0_sel:WORD_1
	v_cvt_f32_f16_e32 v192, v27
	v_pk_fma_f32 v[26:27], v[58:59], v[174:175], v[134:135] op_sel:[1,0,0]
	v_pk_fma_f32 v[134:135], v[34:35], v[174:175], v[136:137] op_sel_hi:[0,1,1]
	v_cvt_f32_f16_sdwa v137, v4 dst_sel:DWORD dst_unused:UNUSED_PAD src0_sel:WORD_1
	v_cvt_f32_f16_e32 v136, v4
	v_pk_fma_f32 v[132:133], v[158:159], v[190:191], v[14:15] op_sel_hi:[0,1,1]
	v_pk_fma_f32 v[14:15], v[58:59], v[174:175], v[142:143] op_sel_hi:[0,1,1]
	v_cvt_f32_f16_sdwa v143, v8 dst_sel:DWORD dst_unused:UNUSED_PAD src0_sel:WORD_1
	v_cvt_f32_f16_e32 v142, v8
	v_pk_fma_f32 v[128:129], v[60:61], v[174:175], v[128:129] op_sel_hi:[0,1,1]
	v_pk_fma_f32 v[120:121], v[154:155], v[174:175], v[120:121] op_sel_hi:[0,1,1]
	v_pk_fma_f32 v[130:131], v[34:35], v[174:175], v[130:131] op_sel:[1,0,0]
	v_pk_fma_f32 v[122:123], v[36:37], v[174:175], v[122:123] op_sel_hi:[0,1,1]
	v_cvt_f32_f16_sdwa v175, v12 dst_sel:DWORD dst_unused:UNUSED_PAD src0_sel:WORD_1
; __device__ __forceinline__ void dsa_item(const KP& p, int b, int tile, char* smem) {
;     ...
; #pragma unroll
;         for (int i = 0; i < 8; ++i) {
;           const int pos = (g8 * 8 + i) * 8 + rs;
;           const f32x4 pa = *(const f32x4*)&pbuf[pos * 8];
;           const f32x4 pb = *(const f32x4*)&pbuf[pos * 8 + 4];
;           float vf[8];
; #pragma unroll
;           for (int e = 0; e < 8; ++e) vf[e] = (float)vv[i][e];
; #pragma unroll
;           for (int e = 0; e < 8; ++e) {
;             acc[0][e] += pa[0] * vf[e]; acc[1][e] += pa[1] * vf[e]; acc[2][e] += pa[2] * vf[e]; acc[3][e] += pa[3] * vf[e];
;             acc[4][e] += pb[0] * vf[e]; acc[5][e] += pb[1] * vf[e]; acc[6][e] += pb[2] * vf[e]; acc[7][e] += pb[3] * vf[e];
;           }
	v_cvt_f32_f16_e32 v174, v12
	v_pk_fma_f32 v[14:15], v[62:63], v[178:179], v[14:15] op_sel_hi:[0,1,1]
	v_pk_fma_f32 v[26:27], v[62:63], v[178:179], v[26:27] op_sel:[1,0,0]
	v_pk_fma_f32 v[128:129], v[64:65], v[178:179], v[128:129] op_sel_hi:[0,1,1]
	v_pk_fma_f32 v[120:121], v[194:195], v[178:179], v[120:121] op_sel_hi:[0,1,1]
	v_pk_fma_f32 v[134:135], v[38:39], v[178:179], v[134:135] op_sel_hi:[0,1,1]
	v_pk_fma_f32 v[130:131], v[38:39], v[178:179], v[130:131] op_sel:[1,0,0]
	v_pk_fma_f32 v[122:123], v[40:41], v[178:179], v[122:123] op_sel_hi:[0,1,1]
	v_cvt_f32_f16_sdwa v179, v16 dst_sel:DWORD dst_unused:UNUSED_PAD src0_sel:WORD_1
	v_cvt_f32_f16_e32 v178, v16
	v_pk_fma_f32 v[14:15], v[66:67], v[180:181], v[14:15] op_sel_hi:[0,1,1]
	v_pk_fma_f32 v[26:27], v[66:67], v[180:181], v[26:27] op_sel:[1,0,0]
	v_pk_fma_f32 v[128:129], v[68:69], v[180:181], v[128:129] op_sel_hi:[0,1,1]
	v_pk_fma_f32 v[120:121], v[196:197], v[180:181], v[120:121] op_sel_hi:[0,1,1]
	v_pk_fma_f32 v[134:135], v[42:43], v[180:181], v[134:135] op_sel_hi:[0,1,1]
	v_pk_fma_f32 v[130:131], v[42:43], v[180:181], v[130:131] op_sel:[1,0,0]
	v_pk_fma_f32 v[122:123], v[44:45], v[180:181], v[122:123] op_sel_hi:[0,1,1]
	v_cvt_f32_f16_sdwa v181, v24 dst_sel:DWORD dst_unused:UNUSED_PAD src0_sel:WORD_1
	v_cvt_f32_f16_e32 v180, v24
	v_pk_fma_f32 v[106:107], v[36:37], v[136:137], v[106:107] op_sel_hi:[0,1,1]
	v_pk_fma_f32 v[14:15], v[70:71], v[188:189], v[14:15] op_sel_hi:[0,1,1]
	v_pk_fma_f32 v[26:27], v[70:71], v[188:189], v[26:27] op_sel:[1,0,0]
	v_pk_fma_f32 v[128:129], v[72:73], v[188:189], v[128:129] op_sel_hi:[0,1,1]
	v_pk_fma_f32 v[120:121], v[198:199], v[188:189], v[120:121] op_sel_hi:[0,1,1]
	v_pk_fma_f32 v[134:135], v[46:47], v[188:189], v[134:135] op_sel_hi:[0,1,1]
	v_pk_fma_f32 v[130:131], v[46:47], v[188:189], v[130:131] op_sel:[1,0,0]
	v_pk_fma_f32 v[122:123], v[48:49], v[188:189], v[122:123] op_sel_hi:[0,1,1]
	v_pk_fma_f32 v[114:115], v[156:157], v[136:137], v[114:115] op_sel_hi:[0,1,1]
	v_cvt_f32_f16_sdwa v189, v28 dst_sel:DWORD dst_unused:UNUSED_PAD src0_sel:WORD_1
	v_cvt_f32_f16_e32 v188, v28
	v_pk_fma_f32 v[124:125], v[58:59], v[136:137], v[124:125] op_sel_hi:[0,1,1]
	v_pk_fma_f32 v[116:117], v[58:59], v[136:137], v[116:117] op_sel:[1,0,0]
	v_pk_fma_f32 v[110:111], v[60:61], v[136:137], v[110:111] op_sel_hi:[0,1,1]
	v_pk_fma_f32 v[104:105], v[154:155], v[136:137], v[104:105] op_sel_hi:[0,1,1]
	v_pk_fma_f32 v[118:119], v[34:35], v[136:137], v[118:119] op_sel_hi:[0,1,1]
	v_pk_fma_f32 v[112:113], v[34:35], v[136:137], v[112:113] op_sel:[1,0,0]
	v_pk_fma_f32 v[106:107], v[40:41], v[142:143], v[106:107] op_sel_hi:[0,1,1]
	v_cvt_f32_f16_sdwa v137, v5 dst_sel:DWORD dst_unused:UNUSED_PAD src0_sel:WORD_1
	v_cvt_f32_f16_e32 v136, v5
	v_pk_fma_f32 v[106:107], v[44:45], v[174:175], v[106:107] op_sel_hi:[0,1,1]
	v_pk_fma_f32 v[106:107], v[48:49], v[178:179], v[106:107] op_sel_hi:[0,1,1]
	v_pk_fma_f32 v[4:5], v[52:53], v[180:181], v[106:107] op_sel_hi:[0,1,1]
	v_pk_fma_f32 v[106:107], v[56:57], v[188:189], v[4:5] op_sel_hi:[0,1,1]
	v_pk_fma_f32 v[4:5], v[156:157], v[136:137], v[98:99] op_sel_hi:[0,1,1]
	v_cvt_f32_f16_sdwa v99, v9 dst_sel:DWORD dst_unused:UNUSED_PAD src0_sel:WORD_1
	v_cvt_f32_f16_e32 v98, v9
	v_cvt_f32_f16_sdwa v9, v13 dst_sel:DWORD dst_unused:UNUSED_PAD src0_sel:WORD_1
	v_cvt_f32_f16_e32 v8, v13
	v_cvt_f32_f16_sdwa v13, v17 dst_sel:DWORD dst_unused:UNUSED_PAD src0_sel:WORD_1
	v_cvt_f32_f16_e32 v12, v17
	v_cvt_f32_f16_sdwa v17, v25 dst_sel:DWORD dst_unused:UNUSED_PAD src0_sel:WORD_1
	v_cvt_f32_f16_e32 v16, v25
	v_pk_fma_f32 v[4:5], v[6:7], v[98:99], v[4:5] op_sel_hi:[0,1,1]
	v_pk_fma_f32 v[114:115], v[6:7], v[142:143], v[114:115] op_sel_hi:[0,1,1]
	v_pk_fma_f32 v[4:5], v[10:11], v[8:9], v[4:5] op_sel_hi:[0,1,1]
	v_pk_fma_f32 v[114:115], v[10:11], v[174:175], v[114:115] op_sel_hi:[0,1,1]
	v_pk_fma_f32 v[4:5], v[22:23], v[12:13], v[4:5] op_sel_hi:[0,1,1]
	v_pk_fma_f32 v[114:115], v[22:23], v[178:179], v[114:115] op_sel_hi:[0,1,1]
	v_pk_fma_f32 v[22:23], v[158:159], v[16:17], v[4:5] op_sel_hi:[0,1,1]
	v_pk_fma_f32 v[4:5], v[58:59], v[136:137], v[108:109] op_sel_hi:[0,1,1]
	v_cvt_f32_f16_sdwa v25, v29 dst_sel:DWORD dst_unused:UNUSED_PAD src0_sel:WORD_1
	v_cvt_f32_f16_e32 v24, v29
	v_pk_fma_f32 v[4:5], v[62:63], v[98:99], v[4:5] op_sel_hi:[0,1,1]
	v_pk_fma_f32 v[4:5], v[66:67], v[8:9], v[4:5] op_sel_hi:[0,1,1]
	v_pk_fma_f32 v[4:5], v[70:71], v[12:13], v[4:5] op_sel_hi:[0,1,1]
	v_pk_fma_f32 v[4:5], v[74:75], v[16:17], v[4:5] op_sel_hi:[0,1,1]
	v_pk_fma_f32 v[28:29], v[78:79], v[24:25], v[4:5] op_sel_hi:[0,1,1]
	v_pk_fma_f32 v[4:5], v[58:59], v[136:137], v[100:101] op_sel:[1,0,0]
	v_pk_fma_f32 v[124:125], v[62:63], v[142:143], v[124:125] op_sel_hi:[0,1,1]
	v_pk_fma_f32 v[4:5], v[62:63], v[98:99], v[4:5] op_sel:[1,0,0]
	v_pk_fma_f32 v[116:117], v[62:63], v[142:143], v[116:117] op_sel:[1,0,0]
	v_pk_fma_f32 v[4:5], v[66:67], v[8:9], v[4:5] op_sel:[1,0,0]
	v_pk_fma_f32 v[110:111], v[64:65], v[142:143], v[110:111] op_sel_hi:[0,1,1]
	v_pk_fma_f32 v[4:5], v[70:71], v[12:13], v[4:5] op_sel:[1,0,0]
	v_pk_fma_f32 v[118:119], v[38:39], v[142:143], v[118:119] op_sel_hi:[0,1,1]
	v_pk_fma_f32 v[4:5], v[74:75], v[16:17], v[4:5] op_sel:[1,0,0]
	v_pk_fma_f32 v[112:113], v[38:39], v[142:143], v[112:113] op_sel:[1,0,0]
	v_pk_fma_f32 v[58:59], v[78:79], v[24:25], v[4:5] op_sel:[1,0,0]
	v_pk_fma_f32 v[4:5], v[60:61], v[136:137], v[94:95] op_sel_hi:[0,1,1]
	v_pk_fma_f32 v[4:5], v[64:65], v[98:99], v[4:5] op_sel_hi:[0,1,1]
	v_pk_fma_f32 v[4:5], v[68:69], v[8:9], v[4:5] op_sel_hi:[0,1,1]
	v_pk_fma_f32 v[4:5], v[72:73], v[12:13], v[4:5] op_sel_hi:[0,1,1]
	v_pk_fma_f32 v[4:5], v[76:77], v[16:17], v[4:5] op_sel_hi:[0,1,1]
; __device__ __forceinline__ void dsa_item(const KP& p, int b, int tile, char* smem) {
;     ...
; #pragma unroll
;         for (int i = 0; i < 8; ++i) {
;           const int pos = (g8 * 8 + i) * 8 + rs;
;           const f32x4 pa = *(const f32x4*)&pbuf[pos * 8];
;           const f32x4 pb = *(const f32x4*)&pbuf[pos * 8 + 4];
;           float vf[8];
; #pragma unroll
;           for (int e = 0; e < 8; ++e) vf[e] = (float)vv[i][e];
; #pragma unroll
;           for (int e = 0; e < 8; ++e) {
;             acc[0][e] += pa[0] * vf[e]; acc[1][e] += pa[1] * vf[e]; acc[2][e] += pa[2] * vf[e]; acc[3][e] += pa[3] * vf[e];
;             acc[4][e] += pb[0] * vf[e]; acc[5][e] += pb[1] * vf[e]; acc[6][e] += pb[2] * vf[e]; acc[7][e] += pb[3] * vf[e];
;           }
	v_pk_fma_f32 v[60:61], v[80:81], v[24:25], v[4:5] op_sel_hi:[0,1,1]
	v_pk_fma_f32 v[4:5], v[154:155], v[136:137], v[90:91] op_sel_hi:[0,1,1]
	v_pk_fma_f32 v[4:5], v[194:195], v[98:99], v[4:5] op_sel_hi:[0,1,1]
	v_pk_fma_f32 v[4:5], v[196:197], v[8:9], v[4:5] op_sel_hi:[0,1,1]
	v_pk_fma_f32 v[4:5], v[198:199], v[12:13], v[4:5] op_sel_hi:[0,1,1]
	v_pk_fma_f32 v[4:5], v[200:201], v[16:17], v[4:5] op_sel_hi:[0,1,1]
	v_pk_fma_f32 v[62:63], v[202:203], v[24:25], v[4:5] op_sel_hi:[0,1,1]
	v_pk_fma_f32 v[4:5], v[34:35], v[136:137], v[102:103] op_sel_hi:[0,1,1]
	v_pk_fma_f32 v[4:5], v[38:39], v[98:99], v[4:5] op_sel_hi:[0,1,1]
	v_pk_fma_f32 v[4:5], v[42:43], v[8:9], v[4:5] op_sel_hi:[0,1,1]
	v_pk_fma_f32 v[4:5], v[46:47], v[12:13], v[4:5] op_sel_hi:[0,1,1]
	v_pk_fma_f32 v[4:5], v[50:51], v[16:17], v[4:5] op_sel_hi:[0,1,1]
	v_pk_fma_f32 v[64:65], v[54:55], v[24:25], v[4:5] op_sel_hi:[0,1,1]
	v_pk_fma_f32 v[4:5], v[34:35], v[136:137], v[96:97] op_sel:[1,0,0]
	v_pk_fma_f32 v[118:119], v[42:43], v[174:175], v[118:119] op_sel_hi:[0,1,1]
	v_pk_fma_f32 v[4:5], v[38:39], v[98:99], v[4:5] op_sel:[1,0,0]
	v_pk_fma_f32 v[112:113], v[42:43], v[174:175], v[112:113] op_sel:[1,0,0]
	v_pk_fma_f32 v[4:5], v[42:43], v[8:9], v[4:5] op_sel:[1,0,0]
	v_pk_fma_f32 v[118:119], v[46:47], v[178:179], v[118:119] op_sel_hi:[0,1,1]
	v_pk_fma_f32 v[4:5], v[46:47], v[12:13], v[4:5] op_sel:[1,0,0]
	v_pk_fma_f32 v[112:113], v[46:47], v[178:179], v[112:113] op_sel:[1,0,0]
	v_pk_fma_f32 v[4:5], v[50:51], v[16:17], v[4:5] op_sel:[1,0,0]
	s_waitcnt vmcnt(9)
	v_cvt_f32_f16_sdwa v43, v19 dst_sel:DWORD dst_unused:UNUSED_PAD src0_sel:WORD_1
	v_pk_fma_f32 v[34:35], v[54:55], v[24:25], v[4:5] op_sel:[1,0,0]
	v_pk_fma_f32 v[4:5], v[36:37], v[136:137], v[92:93] op_sel_hi:[0,1,1]
	v_pk_fma_f32 v[4:5], v[40:41], v[98:99], v[4:5] op_sel_hi:[0,1,1]
	v_pk_fma_f32 v[4:5], v[44:45], v[8:9], v[4:5] op_sel_hi:[0,1,1]
	v_pk_fma_f32 v[4:5], v[48:49], v[12:13], v[4:5] op_sel_hi:[0,1,1]
	v_pk_fma_f32 v[4:5], v[52:53], v[16:17], v[4:5] op_sel_hi:[0,1,1]
	v_pk_fma_f32 v[12:13], v[56:57], v[24:25], v[4:5] op_sel_hi:[0,1,1]
	ds_read_b128 v[4:7], v172 offset:1536
	ds_read_b128 v[8:11], v172 offset:1552
	v_pk_fma_f32 v[24:25], v[176:177], v[24:25], v[22:23] op_sel_hi:[0,1,1]
	v_cvt_f32_f16_sdwa v37, v18 dst_sel:DWORD dst_unused:UNUSED_PAD src0_sel:WORD_1
	v_cvt_f32_f16_e32 v36, v18
	v_cvt_f32_f16_e32 v42, v19
	v_cvt_f32_f16_sdwa v45, v20 dst_sel:DWORD dst_unused:UNUSED_PAD src0_sel:WORD_1
	v_cvt_f32_f16_e32 v44, v20
	v_cvt_f32_f16_sdwa v47, v21 dst_sel:DWORD dst_unused:UNUSED_PAD src0_sel:WORD_1
	v_cvt_f32_f16_e32 v46, v21
	ds_read_b128 v[16:19], v172 offset:1792
	ds_read_b128 v[20:23], v172 offset:1808
	s_waitcnt vmcnt(8)
	v_cvt_f32_f16_e32 v48, v30
	v_cvt_f32_f16_sdwa v49, v30 dst_sel:DWORD dst_unused:UNUSED_PAD src0_sel:WORD_1
	v_pk_fma_f32 v[124:125], v[66:67], v[174:175], v[124:125] op_sel_hi:[0,1,1]
	v_pk_fma_f32 v[116:117], v[66:67], v[174:175], v[116:117] op_sel:[1,0,0]
	v_pk_fma_f32 v[110:111], v[68:69], v[174:175], v[110:111] op_sel_hi:[0,1,1]
	v_pk_fma_f32 v[104:105], v[194:195], v[142:143], v[104:105] op_sel_hi:[0,1,1]
	v_cvt_f32_f16_e32 v30, v31
	v_cvt_f32_f16_sdwa v31, v31 dst_sel:DWORD dst_unused:UNUSED_PAD src0_sel:WORD_1
	v_pk_fma_f32 v[14:15], v[74:75], v[190:191], v[14:15] op_sel_hi:[0,1,1]
	v_pk_fma_f32 v[26:27], v[74:75], v[190:191], v[26:27] op_sel:[1,0,0]
	v_pk_fma_f32 v[128:129], v[76:77], v[190:191], v[128:129] op_sel_hi:[0,1,1]
	v_pk_fma_f32 v[134:135], v[50:51], v[190:191], v[134:135] op_sel_hi:[0,1,1]
	v_pk_fma_f32 v[130:131], v[50:51], v[190:191], v[130:131] op_sel:[1,0,0]
	v_pk_fma_f32 v[124:125], v[70:71], v[178:179], v[124:125] op_sel_hi:[0,1,1]
	v_pk_fma_f32 v[116:117], v[70:71], v[178:179], v[116:117] op_sel:[1,0,0]
	v_pk_fma_f32 v[110:111], v[72:73], v[178:179], v[110:111] op_sel_hi:[0,1,1]
	v_pk_fma_f32 v[104:105], v[196:197], v[174:175], v[104:105] op_sel_hi:[0,1,1]
	v_pk_fma_f32 v[118:119], v[50:51], v[180:181], v[118:119] op_sel_hi:[0,1,1]
	v_pk_fma_f32 v[112:113], v[50:51], v[180:181], v[112:113] op_sel:[1,0,0]
	v_cvt_f32_f16_e32 v50, v32
	v_cvt_f32_f16_sdwa v51, v32 dst_sel:DWORD dst_unused:UNUSED_PAD src0_sel:WORD_1
	v_pk_fma_f32 v[14:15], v[78:79], v[192:193], v[14:15] op_sel_hi:[0,1,1]
	v_pk_fma_f32 v[26:27], v[78:79], v[192:193], v[26:27] op_sel:[1,0,0]
	v_pk_fma_f32 v[128:129], v[80:81], v[192:193], v[128:129] op_sel_hi:[0,1,1]
	v_pk_fma_f32 v[120:121], v[200:201], v[190:191], v[120:121] op_sel_hi:[0,1,1]
	v_pk_fma_f32 v[122:123], v[52:53], v[190:191], v[122:123] op_sel_hi:[0,1,1]
	v_pk_fma_f32 v[124:125], v[74:75], v[180:181], v[124:125] op_sel_hi:[0,1,1]
	v_pk_fma_f32 v[116:117], v[74:75], v[180:181], v[116:117] op_sel:[1,0,0]
	v_pk_fma_f32 v[110:111], v[76:77], v[180:181], v[110:111] op_sel_hi:[0,1,1]
	v_pk_fma_f32 v[104:105], v[198:199], v[178:179], v[104:105] op_sel_hi:[0,1,1]
	s_waitcnt lgkmcnt(3)
	v_mov_b32_e32 v38, v7
	s_waitcnt lgkmcnt(2)
; __device__ __forceinline__ void dsa_item(const KP& p, int b, int tile, char* smem) {
;     ...
; #pragma unroll
;         for (int i = 0; i < 8; ++i) {
;           const int pos = (g8 * 8 + i) * 8 + rs;
;           const f32x4 pa = *(const f32x4*)&pbuf[pos * 8];
;           const f32x4 pb = *(const f32x4*)&pbuf[pos * 8 + 4];
;           float vf[8];
; #pragma unroll
;           for (int e = 0; e < 8; ++e) vf[e] = (float)vv[i][e];
; #pragma unroll
;           for (int e = 0; e < 8; ++e) {
;             acc[0][e] += pa[0] * vf[e]; acc[1][e] += pa[1] * vf[e]; acc[2][e] += pa[2] * vf[e]; acc[3][e] += pa[3] * vf[e];
;             acc[4][e] += pb[0] * vf[e]; acc[5][e] += pb[1] * vf[e]; acc[6][e] += pb[2] * vf[e]; acc[7][e] += pb[3] * vf[e];
;           }
	v_mov_b32_e32 v40, v11
	v_cvt_f32_f16_e32 v32, v33
	v_cvt_f32_f16_sdwa v33, v33 dst_sel:DWORD dst_unused:UNUSED_PAD src0_sel:WORD_1
	v_pk_fma_f32 v[2:3], v[10:11], v[36:37], v[2:3] op_sel_hi:[0,1,1]
	v_pk_fma_f32 v[120:121], v[202:203], v[192:193], v[120:121] op_sel_hi:[0,1,1]
	v_pk_fma_f32 v[134:135], v[54:55], v[192:193], v[134:135] op_sel_hi:[0,1,1]
	v_pk_fma_f32 v[130:131], v[54:55], v[192:193], v[130:131] op_sel:[1,0,0]
	v_pk_fma_f32 v[122:123], v[56:57], v[192:193], v[122:123] op_sel_hi:[0,1,1]
	v_pk_fma_f32 v[132:133], v[176:177], v[192:193], v[132:133] op_sel_hi:[0,1,1]
	v_pk_fma_f32 v[114:115], v[158:159], v[180:181], v[114:115] op_sel_hi:[0,1,1]
	v_pk_fma_f32 v[124:125], v[78:79], v[188:189], v[124:125] op_sel_hi:[0,1,1]
	v_pk_fma_f32 v[116:117], v[78:79], v[188:189], v[116:117] op_sel:[1,0,0]
	v_pk_fma_f32 v[110:111], v[80:81], v[188:189], v[110:111] op_sel_hi:[0,1,1]
	v_pk_fma_f32 v[104:105], v[200:201], v[180:181], v[104:105] op_sel_hi:[0,1,1]
	v_pk_fma_f32 v[118:119], v[54:55], v[188:189], v[118:119] op_sel_hi:[0,1,1]
	v_pk_fma_f32 v[112:113], v[54:55], v[188:189], v[112:113] op_sel:[1,0,0]
	v_pk_fma_f32 v[52:53], v[4:5], v[36:37], v[148:149] op_sel_hi:[0,1,1]
	v_pk_fma_f32 v[54:55], v[4:5], v[36:37], v[152:153] op_sel:[1,0,0]
	v_pk_fma_f32 v[56:57], v[6:7], v[36:37], v[146:147] op_sel_hi:[0,1,1]
	v_pk_fma_f32 v[66:67], v[38:39], v[36:37], v[140:141] op_sel_hi:[0,1,1]
	v_pk_fma_f32 v[68:69], v[8:9], v[36:37], v[150:151] op_sel_hi:[0,1,1]
	v_pk_fma_f32 v[70:71], v[8:9], v[36:37], v[144:145] op_sel:[1,0,0]
	v_pk_fma_f32 v[36:37], v[40:41], v[36:37], v[138:139] op_sel_hi:[0,1,1]
	s_waitcnt lgkmcnt(1)
	v_mov_b32_e32 v72, v19
	s_waitcnt lgkmcnt(0)
	v_mov_b32_e32 v74, v23
	v_pk_fma_f32 v[138:139], v[22:23], v[48:49], v[2:3] op_sel_hi:[0,1,1]
	v_pk_fma_f32 v[2:3], v[4:5], v[42:43], v[14:15] op_sel_hi:[0,1,1]
	v_pk_fma_f32 v[14:15], v[4:5], v[42:43], v[26:27] op_sel:[1,0,0]
	v_pk_fma_f32 v[26:27], v[6:7], v[42:43], v[128:129] op_sel_hi:[0,1,1]
	v_pk_fma_f32 v[104:105], v[202:203], v[188:189], v[104:105] op_sel_hi:[0,1,1]
	v_pk_fma_f32 v[114:115], v[176:177], v[188:189], v[114:115] op_sel_hi:[0,1,1]
	v_pk_fma_f32 v[154:155], v[16:17], v[48:49], v[52:53] op_sel_hi:[0,1,1]
	v_pk_fma_f32 v[152:153], v[16:17], v[48:49], v[54:55] op_sel:[1,0,0]
	v_pk_fma_f32 v[146:147], v[18:19], v[48:49], v[56:57] op_sel_hi:[0,1,1]
	v_pk_fma_f32 v[140:141], v[72:73], v[48:49], v[66:67] op_sel_hi:[0,1,1]
	v_pk_fma_f32 v[150:151], v[20:21], v[48:49], v[68:69] op_sel_hi:[0,1,1]
	v_pk_fma_f32 v[144:145], v[20:21], v[48:49], v[70:71] op_sel:[1,0,0]
	v_pk_fma_f32 v[148:149], v[74:75], v[48:49], v[36:37] op_sel_hi:[0,1,1]
	v_pk_fma_f32 v[36:37], v[38:39], v[42:43], v[120:121] op_sel_hi:[0,1,1]
	v_pk_fma_f32 v[48:49], v[8:9], v[42:43], v[134:135] op_sel_hi:[0,1,1]
	v_pk_fma_f32 v[52:53], v[8:9], v[42:43], v[130:131] op_sel:[1,0,0]
	v_pk_fma_f32 v[54:55], v[10:11], v[42:43], v[122:123] op_sel_hi:[0,1,1]
	v_pk_fma_f32 v[42:43], v[40:41], v[42:43], v[132:133] op_sel_hi:[0,1,1]
	v_pk_fma_f32 v[142:143], v[16:17], v[30:31], v[2:3] op_sel_hi:[0,1,1]
	v_pk_fma_f32 v[134:135], v[16:17], v[30:31], v[14:15] op_sel:[1,0,0]
	v_pk_fma_f32 v[128:129], v[18:19], v[30:31], v[26:27] op_sel_hi:[0,1,1]
	v_pk_fma_f32 v[2:3], v[4:5], v[44:45], v[124:125] op_sel_hi:[0,1,1]
	v_pk_fma_f32 v[14:15], v[4:5], v[44:45], v[116:117] op_sel:[1,0,0]
	v_pk_fma_f32 v[26:27], v[6:7], v[44:45], v[110:111] op_sel_hi:[0,1,1]
	v_pk_fma_f32 v[120:121], v[72:73], v[30:31], v[36:37] op_sel_hi:[0,1,1]
	v_pk_fma_f32 v[136:137], v[20:21], v[30:31], v[48:49] op_sel_hi:[0,1,1]
	v_pk_fma_f32 v[130:131], v[20:21], v[30:31], v[52:53] op_sel:[1,0,0]
	v_pk_fma_f32 v[122:123], v[22:23], v[30:31], v[54:55] op_sel_hi:[0,1,1]
	v_pk_fma_f32 v[132:133], v[74:75], v[30:31], v[42:43] op_sel_hi:[0,1,1]
	v_pk_fma_f32 v[30:31], v[38:39], v[44:45], v[104:105] op_sel_hi:[0,1,1]
	v_pk_fma_f32 v[36:37], v[8:9], v[44:45], v[118:119] op_sel_hi:[0,1,1]
	v_pk_fma_f32 v[42:43], v[8:9], v[44:45], v[112:113] op_sel:[1,0,0]
	v_pk_fma_f32 v[48:49], v[10:11], v[44:45], v[106:107] op_sel_hi:[0,1,1]
	v_pk_fma_f32 v[44:45], v[40:41], v[44:45], v[114:115] op_sel_hi:[0,1,1]
	v_pk_fma_f32 v[124:125], v[16:17], v[50:51], v[2:3] op_sel_hi:[0,1,1]
	v_pk_fma_f32 v[116:117], v[16:17], v[50:51], v[14:15] op_sel:[1,0,0]
	v_pk_fma_f32 v[110:111], v[18:19], v[50:51], v[26:27] op_sel_hi:[0,1,1]
	v_pk_fma_f32 v[2:3], v[4:5], v[46:47], v[28:29] op_sel_hi:[0,1,1]
	v_pk_fma_f32 v[4:5], v[4:5], v[46:47], v[58:59] op_sel:[1,0,0]
	v_pk_fma_f32 v[6:7], v[6:7], v[46:47], v[60:61] op_sel_hi:[0,1,1]
	v_pk_fma_f32 v[14:15], v[38:39], v[46:47], v[62:63] op_sel_hi:[0,1,1]
	v_pk_fma_f32 v[26:27], v[8:9], v[46:47], v[64:65] op_sel_hi:[0,1,1]
	v_pk_fma_f32 v[8:9], v[8:9], v[46:47], v[34:35] op_sel:[1,0,0]
	v_pk_fma_f32 v[10:11], v[10:11], v[46:47], v[12:13] op_sel_hi:[0,1,1]
	v_pk_fma_f32 v[12:13], v[40:41], v[46:47], v[24:25] op_sel_hi:[0,1,1]
	v_pk_fma_f32 v[104:105], v[72:73], v[50:51], v[30:31] op_sel_hi:[0,1,1]
	v_pk_fma_f32 v[118:119], v[20:21], v[50:51], v[36:37] op_sel_hi:[0,1,1]
	v_pk_fma_f32 v[112:113], v[20:21], v[50:51], v[42:43] op_sel:[1,0,0]
	v_pk_fma_f32 v[106:107], v[22:23], v[50:51], v[48:49] op_sel_hi:[0,1,1]
	v_pk_fma_f32 v[114:115], v[74:75], v[50:51], v[44:45] op_sel_hi:[0,1,1]
	v_pk_fma_f32 v[108:109], v[16:17], v[32:33], v[2:3] op_sel_hi:[0,1,1]
	v_pk_fma_f32 v[100:101], v[16:17], v[32:33], v[4:5] op_sel:[1,0,0]
	v_pk_fma_f32 v[94:95], v[18:19], v[32:33], v[6:7] op_sel_hi:[0,1,1]
	v_pk_fma_f32 v[90:91], v[72:73], v[32:33], v[14:15] op_sel_hi:[0,1,1]
	v_pk_fma_f32 v[102:103], v[20:21], v[32:33], v[26:27] op_sel_hi:[0,1,1]
	v_pk_fma_f32 v[96:97], v[20:21], v[32:33], v[8:9] op_sel:[1,0,0]
	v_pk_fma_f32 v[92:93], v[22:23], v[32:33], v[10:11] op_sel_hi:[0,1,1]
	v_pk_fma_f32 v[98:99], v[74:75], v[32:33], v[12:13] op_sel_hi:[0,1,1]
	v_add_u32_e32 v172, 0x800, v172
	s_waitcnt vmcnt(7)
; __device__ __forceinline__ void dsa_item(const KP& p, int b, int tile, char* smem) {
;     ...
; #pragma unroll
;         for (int i = 0; i < 8; ++i) {
;           const int pos = (g8 * 8 + i) * 8 + rs;
;           const f32x4 pa = *(const f32x4*)&pbuf[pos * 8];
;           const f32x4 pb = *(const f32x4*)&pbuf[pos * 8 + 4];
;           float vf[8];
; #pragma unroll
;           for (int e = 0; e < 8; ++e) vf[e] = (float)vv[i][e];
; #pragma unroll
;           for (int e = 0; e < 8; ++e) {
;             acc[0][e] += pa[0] * vf[e]; acc[1][e] += pa[1] * vf[e]; acc[2][e] += pa[2] * vf[e]; acc[3][e] += pa[3] * vf[e];
;             acc[4][e] += pb[0] * vf[e]; acc[5][e] += pb[1] * vf[e]; acc[6][e] += pb[2] * vf[e]; acc[7][e] += pb[3] * vf[e];
;           }
	v_cvt_f32_f16_sdwa v175, v204 dst_sel:DWORD dst_unused:UNUSED_PAD src0_sel:WORD_1
	v_cvt_f32_f16_e32 v174, v204
	s_waitcnt vmcnt(6)
	v_cvt_f32_f16_sdwa v177, v208 dst_sel:DWORD dst_unused:UNUSED_PAD src0_sel:WORD_1
	v_cvt_f32_f16_e32 v176, v208
	ds_read_b128 v[58:61], v172
	ds_read_b128 v[34:37], v172 offset:16
	ds_read_b128 v[62:65], v172 offset:256
	ds_read_b128 v[38:41], v172 offset:272
	ds_read_b128 v[66:69], v172 offset:512
	ds_read_b128 v[42:45], v172 offset:528
	ds_read_b128 v[70:73], v172 offset:768
	ds_read_b128 v[46:49], v172 offset:784
	ds_read_b128 v[74:77], v172 offset:1024
	ds_read_b128 v[50:53], v172 offset:1040
	s_waitcnt vmcnt(5)
	v_cvt_f32_f16_sdwa v179, v212 dst_sel:DWORD dst_unused:UNUSED_PAD src0_sel:WORD_1
	v_cvt_f32_f16_e32 v178, v212
	s_waitcnt lgkmcnt(8)
	v_mov_b32_e32 v156, v37
	s_waitcnt vmcnt(4)
	v_cvt_f32_f16_sdwa v181, v216 dst_sel:DWORD dst_unused:UNUSED_PAD src0_sel:WORD_1
	v_cvt_f32_f16_e32 v180, v216
	v_pk_fma_f32 v[148:149], v[156:157], v[174:175], v[148:149] op_sel_hi:[0,1,1]
	s_waitcnt lgkmcnt(6)
	v_mov_b32_e32 v208, v41
	s_waitcnt vmcnt(3)
	v_cvt_f32_f16_sdwa v189, v224 dst_sel:DWORD dst_unused:UNUSED_PAD src0_sel:WORD_1
	v_cvt_f32_f16_e32 v188, v224
	v_pk_fma_f32 v[148:149], v[208:209], v[176:177], v[148:149] op_sel_hi:[0,1,1]
	s_waitcnt lgkmcnt(4)
	v_mov_b32_e32 v212, v45
	v_pk_fma_f32 v[148:149], v[212:213], v[178:179], v[148:149] op_sel_hi:[0,1,1]
	s_waitcnt lgkmcnt(2)
	v_mov_b32_e32 v224, v49
	v_pk_fma_f32 v[148:149], v[224:225], v[180:181], v[148:149] op_sel_hi:[0,1,1]
	s_waitcnt lgkmcnt(0)
	v_mov_b32_e32 v158, v53
	ds_read_b128 v[78:81], v172 offset:1280
	ds_read_b128 v[54:57], v172 offset:1296
	v_pk_fma_f32 v[190:191], v[158:159], v[188:189], v[148:149] op_sel_hi:[0,1,1]
	v_pk_fma_f32 v[148:149], v[58:59], v[174:175], v[154:155] op_sel_hi:[0,1,1]
	v_mov_b32_e32 v154, v61
	v_pk_fma_f32 v[152:153], v[58:59], v[174:175], v[152:153] op_sel:[1,0,0]
	v_pk_fma_f32 v[146:147], v[60:61], v[174:175], v[146:147] op_sel_hi:[0,1,1]
	v_pk_fma_f32 v[140:141], v[154:155], v[174:175], v[140:141] op_sel_hi:[0,1,1]
	v_mov_b32_e32 v194, v65
	v_pk_fma_f32 v[150:151], v[34:35], v[174:175], v[150:151] op_sel_hi:[0,1,1]
	v_pk_fma_f32 v[144:145], v[34:35], v[174:175], v[144:145] op_sel:[1,0,0]
	v_pk_fma_f32 v[138:139], v[36:37], v[174:175], v[138:139] op_sel_hi:[0,1,1]
	s_waitcnt vmcnt(2)
	v_cvt_f32_f16_sdwa v193, v228 dst_sel:DWORD dst_unused:UNUSED_PAD src0_sel:WORD_1
	v_cvt_f32_f16_e32 v192, v228
	v_pk_fma_f32 v[148:149], v[62:63], v[176:177], v[148:149] op_sel_hi:[0,1,1]
	v_pk_fma_f32 v[152:153], v[62:63], v[176:177], v[152:153] op_sel:[1,0,0]
	v_pk_fma_f32 v[146:147], v[64:65], v[176:177], v[146:147] op_sel_hi:[0,1,1]
	v_pk_fma_f32 v[140:141], v[194:195], v[176:177], v[140:141] op_sel_hi:[0,1,1]
	v_mov_b32_e32 v196, v69
	v_pk_fma_f32 v[150:151], v[38:39], v[176:177], v[150:151] op_sel_hi:[0,1,1]
	v_pk_fma_f32 v[144:145], v[38:39], v[176:177], v[144:145] op_sel:[1,0,0]
	v_pk_fma_f32 v[138:139], v[40:41], v[176:177], v[138:139] op_sel_hi:[0,1,1]
	v_cvt_f32_f16_sdwa v175, v205 dst_sel:DWORD dst_unused:UNUSED_PAD src0_sel:WORD_1
	v_cvt_f32_f16_e32 v174, v205
	v_pk_fma_f32 v[148:149], v[66:67], v[178:179], v[148:149] op_sel_hi:[0,1,1]
	v_pk_fma_f32 v[152:153], v[66:67], v[178:179], v[152:153] op_sel:[1,0,0]
	v_pk_fma_f32 v[146:147], v[68:69], v[178:179], v[146:147] op_sel_hi:[0,1,1]
	v_pk_fma_f32 v[140:141], v[196:197], v[178:179], v[140:141] op_sel_hi:[0,1,1]
	v_mov_b32_e32 v198, v73
	v_pk_fma_f32 v[150:151], v[42:43], v[178:179], v[150:151] op_sel_hi:[0,1,1]
	v_pk_fma_f32 v[144:145], v[42:43], v[178:179], v[144:145] op_sel:[1,0,0]
	v_pk_fma_f32 v[138:139], v[44:45], v[178:179], v[138:139] op_sel_hi:[0,1,1]
	v_cvt_f32_f16_sdwa v179, v209 dst_sel:DWORD dst_unused:UNUSED_PAD src0_sel:WORD_1
	v_cvt_f32_f16_e32 v178, v209
	v_pk_fma_f32 v[148:149], v[70:71], v[180:181], v[148:149] op_sel_hi:[0,1,1]
	v_pk_fma_f32 v[152:153], v[70:71], v[180:181], v[152:153] op_sel:[1,0,0]
	v_pk_fma_f32 v[146:147], v[72:73], v[180:181], v[146:147] op_sel_hi:[0,1,1]
	v_pk_fma_f32 v[140:141], v[198:199], v[180:181], v[140:141] op_sel_hi:[0,1,1]
	v_mov_b32_e32 v200, v77
	v_pk_fma_f32 v[150:151], v[46:47], v[180:181], v[150:151] op_sel_hi:[0,1,1]
	v_pk_fma_f32 v[144:145], v[46:47], v[180:181], v[144:145] op_sel:[1,0,0]
	v_pk_fma_f32 v[138:139], v[48:49], v[180:181], v[138:139] op_sel_hi:[0,1,1]
	v_cvt_f32_f16_sdwa v181, v213 dst_sel:DWORD dst_unused:UNUSED_PAD src0_sel:WORD_1
	v_cvt_f32_f16_e32 v180, v213
	v_pk_fma_f32 v[148:149], v[74:75], v[188:189], v[148:149] op_sel_hi:[0,1,1]
	v_pk_fma_f32 v[152:153], v[74:75], v[188:189], v[152:153] op_sel:[1,0,0]
	v_pk_fma_f32 v[146:147], v[76:77], v[188:189], v[146:147] op_sel_hi:[0,1,1]
	v_pk_fma_f32 v[140:141], v[200:201], v[188:189], v[140:141] op_sel_hi:[0,1,1]
	v_pk_fma_f32 v[150:151], v[50:51], v[188:189], v[150:151] op_sel_hi:[0,1,1]
	v_pk_fma_f32 v[144:145], v[50:51], v[188:189], v[144:145] op_sel:[1,0,0]
	v_pk_fma_f32 v[138:139], v[52:53], v[188:189], v[138:139] op_sel_hi:[0,1,1]
	s_waitcnt lgkmcnt(0)
; __device__ __forceinline__ void dsa_item(const KP& p, int b, int tile, char* smem) {
;     ...
;       for (int g8 = 0; g8 < 4; ++g8) {
;         h8 vv[8];
; #pragma unroll
;         for (int i = 0; i < 8; ++i) {
;           const int pos = (g8 * 8 + i) * 8 + rs;
;           const int s = (pos < nsel) ? (int)sel[tk * 256 + pos] : 0;
;           vv[i] = *(const h8*)(ub + (size_t)s * NU + C_BV + dc * 8);
;         }
; #pragma unroll
;         for (int i = 0; i < 8; ++i) {
;           const int pos = (g8 * 8 + i) * 8 + rs;
;           const f32x4 pa = *(const f32x4*)&pbuf[pos * 8];
;           const f32x4 pb = *(const f32x4*)&pbuf[pos * 8 + 4];
;           float vf[8];
; #pragma unroll
;           for (int e = 0; e < 8; ++e) vf[e] = (float)vv[i][e];
; #pragma unroll
;           for (int e = 0; e < 8; ++e) {
;             acc[0][e] += pa[0] * vf[e]; acc[1][e] += pa[1] * vf[e]; acc[2][e] += pa[2] * vf[e]; acc[3][e] += pa[3] * vf[e];
;             acc[4][e] += pb[0] * vf[e]; acc[5][e] += pb[1] * vf[e]; acc[6][e] += pb[2] * vf[e]; acc[7][e] += pb[3] * vf[e];
;           }
;         }
	v_mov_b32_e32 v176, v57
	v_cvt_f32_f16_sdwa v189, v217 dst_sel:DWORD dst_unused:UNUSED_PAD src0_sel:WORD_1
	v_cvt_f32_f16_e32 v188, v217
	v_pk_fma_f32 v[204:205], v[56:57], v[192:193], v[138:139] op_sel_hi:[0,1,1]
	v_pk_fma_f32 v[138:139], v[176:177], v[192:193], v[190:191] op_sel_hi:[0,1,1]
	v_pk_fma_f32 v[132:133], v[156:157], v[174:175], v[132:133] op_sel_hi:[0,1,1]
	v_cvt_f32_f16_sdwa v191, v225 dst_sel:DWORD dst_unused:UNUSED_PAD src0_sel:WORD_1
	v_cvt_f32_f16_e32 v190, v225
	v_pk_fma_f32 v[216:217], v[208:209], v[178:179], v[132:133] op_sel_hi:[0,1,1]
	v_mov_b32_e32 v202, v81
	v_pk_fma_f32 v[216:217], v[212:213], v[180:181], v[216:217] op_sel_hi:[0,1,1]
	v_pk_fma_f32 v[148:149], v[78:79], v[192:193], v[148:149] op_sel_hi:[0,1,1]
	v_pk_fma_f32 v[152:153], v[78:79], v[192:193], v[152:153] op_sel:[1,0,0]
	v_pk_fma_f32 v[146:147], v[80:81], v[192:193], v[146:147] op_sel_hi:[0,1,1]
	v_pk_fma_f32 v[140:141], v[202:203], v[192:193], v[140:141] op_sel_hi:[0,1,1]
	v_pk_fma_f32 v[150:151], v[54:55], v[192:193], v[150:151] op_sel_hi:[0,1,1]
	v_pk_fma_f32 v[144:145], v[54:55], v[192:193], v[144:145] op_sel:[1,0,0]
	v_pk_fma_f32 v[216:217], v[224:225], v[188:189], v[216:217] op_sel_hi:[0,1,1]
	v_cvt_f32_f16_sdwa v193, v229 dst_sel:DWORD dst_unused:UNUSED_PAD src0_sel:WORD_1
	v_cvt_f32_f16_e32 v192, v229
	v_pk_fma_f32 v[228:229], v[58:59], v[174:175], v[134:135] op_sel:[1,0,0]
	v_pk_fma_f32 v[134:135], v[34:35], v[174:175], v[136:137] op_sel_hi:[0,1,1]
	v_cvt_f32_f16_sdwa v137, v206 dst_sel:DWORD dst_unused:UNUSED_PAD src0_sel:WORD_1
	v_cvt_f32_f16_e32 v136, v206
	v_pk_fma_f32 v[132:133], v[158:159], v[190:191], v[216:217] op_sel_hi:[0,1,1]
	v_pk_fma_f32 v[216:217], v[58:59], v[174:175], v[142:143] op_sel_hi:[0,1,1]
	v_cvt_f32_f16_sdwa v143, v210 dst_sel:DWORD dst_unused:UNUSED_PAD src0_sel:WORD_1
	v_cvt_f32_f16_e32 v142, v210
	v_pk_fma_f32 v[128:129], v[60:61], v[174:175], v[128:129] op_sel_hi:[0,1,1]
	v_pk_fma_f32 v[120:121], v[154:155], v[174:175], v[120:121] op_sel_hi:[0,1,1]
	v_pk_fma_f32 v[130:131], v[34:35], v[174:175], v[130:131] op_sel:[1,0,0]
	v_pk_fma_f32 v[122:123], v[36:37], v[174:175], v[122:123] op_sel_hi:[0,1,1]
	v_cvt_f32_f16_sdwa v175, v214 dst_sel:DWORD dst_unused:UNUSED_PAD src0_sel:WORD_1
	v_cvt_f32_f16_e32 v174, v214
	v_pk_fma_f32 v[216:217], v[62:63], v[178:179], v[216:217] op_sel_hi:[0,1,1]
	v_pk_fma_f32 v[228:229], v[62:63], v[178:179], v[228:229] op_sel:[1,0,0]
	v_pk_fma_f32 v[128:129], v[64:65], v[178:179], v[128:129] op_sel_hi:[0,1,1]
	v_pk_fma_f32 v[120:121], v[194:195], v[178:179], v[120:121] op_sel_hi:[0,1,1]
	v_pk_fma_f32 v[134:135], v[38:39], v[178:179], v[134:135] op_sel_hi:[0,1,1]
	v_pk_fma_f32 v[130:131], v[38:39], v[178:179], v[130:131] op_sel:[1,0,0]
	v_pk_fma_f32 v[122:123], v[40:41], v[178:179], v[122:123] op_sel_hi:[0,1,1]
	v_cvt_f32_f16_sdwa v179, v218 dst_sel:DWORD dst_unused:UNUSED_PAD src0_sel:WORD_1
	v_cvt_f32_f16_e32 v178, v218
	v_pk_fma_f32 v[216:217], v[66:67], v[180:181], v[216:217] op_sel_hi:[0,1,1]
	v_pk_fma_f32 v[228:229], v[66:67], v[180:181], v[228:229] op_sel:[1,0,0]
	v_pk_fma_f32 v[128:129], v[68:69], v[180:181], v[128:129] op_sel_hi:[0,1,1]
	v_pk_fma_f32 v[120:121], v[196:197], v[180:181], v[120:121] op_sel_hi:[0,1,1]
	v_pk_fma_f32 v[134:135], v[42:43], v[180:181], v[134:135] op_sel_hi:[0,1,1]
	v_pk_fma_f32 v[130:131], v[42:43], v[180:181], v[130:131] op_sel:[1,0,0]
	v_pk_fma_f32 v[122:123], v[44:45], v[180:181], v[122:123] op_sel_hi:[0,1,1]
	v_cvt_f32_f16_sdwa v181, v226 dst_sel:DWORD dst_unused:UNUSED_PAD src0_sel:WORD_1
	v_cvt_f32_f16_e32 v180, v226
	v_pk_fma_f32 v[106:107], v[36:37], v[136:137], v[106:107] op_sel_hi:[0,1,1]
	v_pk_fma_f32 v[216:217], v[70:71], v[188:189], v[216:217] op_sel_hi:[0,1,1]
	v_pk_fma_f32 v[228:229], v[70:71], v[188:189], v[228:229] op_sel:[1,0,0]
	v_pk_fma_f32 v[128:129], v[72:73], v[188:189], v[128:129] op_sel_hi:[0,1,1]
	v_pk_fma_f32 v[120:121], v[198:199], v[188:189], v[120:121] op_sel_hi:[0,1,1]
	v_pk_fma_f32 v[134:135], v[46:47], v[188:189], v[134:135] op_sel_hi:[0,1,1]
	v_pk_fma_f32 v[130:131], v[46:47], v[188:189], v[130:131] op_sel:[1,0,0]
	v_pk_fma_f32 v[122:123], v[48:49], v[188:189], v[122:123] op_sel_hi:[0,1,1]
	v_pk_fma_f32 v[114:115], v[156:157], v[136:137], v[114:115] op_sel_hi:[0,1,1]
	v_cvt_f32_f16_sdwa v189, v230 dst_sel:DWORD dst_unused:UNUSED_PAD src0_sel:WORD_1
	v_cvt_f32_f16_e32 v188, v230
	v_pk_fma_f32 v[124:125], v[58:59], v[136:137], v[124:125] op_sel_hi:[0,1,1]
	v_pk_fma_f32 v[116:117], v[58:59], v[136:137], v[116:117] op_sel:[1,0,0]
	v_pk_fma_f32 v[110:111], v[60:61], v[136:137], v[110:111] op_sel_hi:[0,1,1]
	v_pk_fma_f32 v[104:105], v[154:155], v[136:137], v[104:105] op_sel_hi:[0,1,1]
	v_pk_fma_f32 v[118:119], v[34:35], v[136:137], v[118:119] op_sel_hi:[0,1,1]
	v_pk_fma_f32 v[112:113], v[34:35], v[136:137], v[112:113] op_sel:[1,0,0]
	v_pk_fma_f32 v[106:107], v[40:41], v[142:143], v[106:107] op_sel_hi:[0,1,1]
	v_cvt_f32_f16_sdwa v137, v207 dst_sel:DWORD dst_unused:UNUSED_PAD src0_sel:WORD_1
	v_cvt_f32_f16_e32 v136, v207
	v_pk_fma_f32 v[106:107], v[44:45], v[174:175], v[106:107] op_sel_hi:[0,1,1]
	v_pk_fma_f32 v[106:107], v[48:49], v[178:179], v[106:107] op_sel_hi:[0,1,1]
	v_pk_fma_f32 v[206:207], v[52:53], v[180:181], v[106:107] op_sel_hi:[0,1,1]
	v_pk_fma_f32 v[106:107], v[56:57], v[188:189], v[206:207] op_sel_hi:[0,1,1]
	v_pk_fma_f32 v[206:207], v[156:157], v[136:137], v[98:99] op_sel_hi:[0,1,1]
	v_cvt_f32_f16_sdwa v99, v211 dst_sel:DWORD dst_unused:UNUSED_PAD src0_sel:WORD_1
	v_cvt_f32_f16_e32 v98, v211
	v_cvt_f32_f16_sdwa v211, v215 dst_sel:DWORD dst_unused:UNUSED_PAD src0_sel:WORD_1
	v_cvt_f32_f16_e32 v210, v215
; __device__ __forceinline__ void dsa_item(const KP& p, int b, int tile, char* smem) {
;     ...
;       for (int g8 = 0; g8 < 4; ++g8) {
;         h8 vv[8];
; #pragma unroll
;         for (int i = 0; i < 8; ++i) {
;           const int pos = (g8 * 8 + i) * 8 + rs;
;           const int s = (pos < nsel) ? (int)sel[tk * 256 + pos] : 0;
;           vv[i] = *(const h8*)(ub + (size_t)s * NU + C_BV + dc * 8);
;         }
; #pragma unroll
;         for (int i = 0; i < 8; ++i) {
;           const int pos = (g8 * 8 + i) * 8 + rs;
;           const f32x4 pa = *(const f32x4*)&pbuf[pos * 8];
;           const f32x4 pb = *(const f32x4*)&pbuf[pos * 8 + 4];
;           float vf[8];
; #pragma unroll
;           for (int e = 0; e < 8; ++e) vf[e] = (float)vv[i][e];
; #pragma unroll
;           for (int e = 0; e < 8; ++e) {
;             acc[0][e] += pa[0] * vf[e]; acc[1][e] += pa[1] * vf[e]; acc[2][e] += pa[2] * vf[e]; acc[3][e] += pa[3] * vf[e];
;             acc[4][e] += pb[0] * vf[e]; acc[5][e] += pb[1] * vf[e]; acc[6][e] += pb[2] * vf[e]; acc[7][e] += pb[3] * vf[e];
;           }
;         }
	v_cvt_f32_f16_sdwa v215, v219 dst_sel:DWORD dst_unused:UNUSED_PAD src0_sel:WORD_1
	v_cvt_f32_f16_e32 v214, v219
	v_cvt_f32_f16_sdwa v219, v227 dst_sel:DWORD dst_unused:UNUSED_PAD src0_sel:WORD_1
	v_cvt_f32_f16_e32 v218, v227
	v_pk_fma_f32 v[206:207], v[208:209], v[98:99], v[206:207] op_sel_hi:[0,1,1]
	v_pk_fma_f32 v[114:115], v[208:209], v[142:143], v[114:115] op_sel_hi:[0,1,1]
	v_pk_fma_f32 v[206:207], v[212:213], v[210:211], v[206:207] op_sel_hi:[0,1,1]
	v_pk_fma_f32 v[114:115], v[212:213], v[174:175], v[114:115] op_sel_hi:[0,1,1]
	v_pk_fma_f32 v[206:207], v[224:225], v[214:215], v[206:207] op_sel_hi:[0,1,1]
	v_pk_fma_f32 v[114:115], v[224:225], v[178:179], v[114:115] op_sel_hi:[0,1,1]
	v_pk_fma_f32 v[224:225], v[158:159], v[218:219], v[206:207] op_sel_hi:[0,1,1]
	v_pk_fma_f32 v[206:207], v[58:59], v[136:137], v[108:109] op_sel_hi:[0,1,1]
	v_cvt_f32_f16_sdwa v227, v231 dst_sel:DWORD dst_unused:UNUSED_PAD src0_sel:WORD_1
	v_cvt_f32_f16_e32 v226, v231
	v_pk_fma_f32 v[206:207], v[62:63], v[98:99], v[206:207] op_sel_hi:[0,1,1]
	v_pk_fma_f32 v[206:207], v[66:67], v[210:211], v[206:207] op_sel_hi:[0,1,1]
	v_pk_fma_f32 v[206:207], v[70:71], v[214:215], v[206:207] op_sel_hi:[0,1,1]
	v_pk_fma_f32 v[206:207], v[74:75], v[218:219], v[206:207] op_sel_hi:[0,1,1]
	v_pk_fma_f32 v[230:231], v[78:79], v[226:227], v[206:207] op_sel_hi:[0,1,1]
	v_pk_fma_f32 v[206:207], v[58:59], v[136:137], v[100:101] op_sel:[1,0,0]
	v_pk_fma_f32 v[124:125], v[62:63], v[142:143], v[124:125] op_sel_hi:[0,1,1]
	v_pk_fma_f32 v[206:207], v[62:63], v[98:99], v[206:207] op_sel:[1,0,0]
	v_pk_fma_f32 v[116:117], v[62:63], v[142:143], v[116:117] op_sel:[1,0,0]
	v_pk_fma_f32 v[206:207], v[66:67], v[210:211], v[206:207] op_sel:[1,0,0]
	v_pk_fma_f32 v[110:111], v[64:65], v[142:143], v[110:111] op_sel_hi:[0,1,1]
	v_pk_fma_f32 v[206:207], v[70:71], v[214:215], v[206:207] op_sel:[1,0,0]
	v_pk_fma_f32 v[118:119], v[38:39], v[142:143], v[118:119] op_sel_hi:[0,1,1]
	v_pk_fma_f32 v[206:207], v[74:75], v[218:219], v[206:207] op_sel:[1,0,0]
	v_pk_fma_f32 v[112:113], v[38:39], v[142:143], v[112:113] op_sel:[1,0,0]
	v_pk_fma_f32 v[58:59], v[78:79], v[226:227], v[206:207] op_sel:[1,0,0]
	v_pk_fma_f32 v[206:207], v[60:61], v[136:137], v[94:95] op_sel_hi:[0,1,1]
	v_pk_fma_f32 v[206:207], v[64:65], v[98:99], v[206:207] op_sel_hi:[0,1,1]
	v_pk_fma_f32 v[206:207], v[68:69], v[210:211], v[206:207] op_sel_hi:[0,1,1]
	v_pk_fma_f32 v[206:207], v[72:73], v[214:215], v[206:207] op_sel_hi:[0,1,1]
	v_pk_fma_f32 v[206:207], v[76:77], v[218:219], v[206:207] op_sel_hi:[0,1,1]
	v_pk_fma_f32 v[60:61], v[80:81], v[226:227], v[206:207] op_sel_hi:[0,1,1]
	v_pk_fma_f32 v[206:207], v[154:155], v[136:137], v[90:91] op_sel_hi:[0,1,1]
	v_pk_fma_f32 v[206:207], v[194:195], v[98:99], v[206:207] op_sel_hi:[0,1,1]
	v_pk_fma_f32 v[206:207], v[196:197], v[210:211], v[206:207] op_sel_hi:[0,1,1]
	v_pk_fma_f32 v[206:207], v[198:199], v[214:215], v[206:207] op_sel_hi:[0,1,1]
	v_pk_fma_f32 v[206:207], v[200:201], v[218:219], v[206:207] op_sel_hi:[0,1,1]
	v_pk_fma_f32 v[62:63], v[202:203], v[226:227], v[206:207] op_sel_hi:[0,1,1]
	v_pk_fma_f32 v[206:207], v[34:35], v[136:137], v[102:103] op_sel_hi:[0,1,1]
	v_pk_fma_f32 v[206:207], v[38:39], v[98:99], v[206:207] op_sel_hi:[0,1,1]
	v_pk_fma_f32 v[206:207], v[42:43], v[210:211], v[206:207] op_sel_hi:[0,1,1]
	v_pk_fma_f32 v[206:207], v[46:47], v[214:215], v[206:207] op_sel_hi:[0,1,1]
	v_pk_fma_f32 v[206:207], v[50:51], v[218:219], v[206:207] op_sel_hi:[0,1,1]
	v_pk_fma_f32 v[64:65], v[54:55], v[226:227], v[206:207] op_sel_hi:[0,1,1]
	v_pk_fma_f32 v[206:207], v[34:35], v[136:137], v[96:97] op_sel:[1,0,0]
	v_pk_fma_f32 v[118:119], v[42:43], v[174:175], v[118:119] op_sel_hi:[0,1,1]
	v_pk_fma_f32 v[206:207], v[38:39], v[98:99], v[206:207] op_sel:[1,0,0]
	v_pk_fma_f32 v[112:113], v[42:43], v[174:175], v[112:113] op_sel:[1,0,0]
	v_pk_fma_f32 v[206:207], v[42:43], v[210:211], v[206:207] op_sel:[1,0,0]
	v_pk_fma_f32 v[118:119], v[46:47], v[178:179], v[118:119] op_sel_hi:[0,1,1]
	v_pk_fma_f32 v[206:207], v[46:47], v[214:215], v[206:207] op_sel:[1,0,0]
	v_pk_fma_f32 v[112:113], v[46:47], v[178:179], v[112:113] op_sel:[1,0,0]
	v_pk_fma_f32 v[206:207], v[50:51], v[218:219], v[206:207] op_sel:[1,0,0]
	s_waitcnt vmcnt(1)
	v_cvt_f32_f16_sdwa v43, v221 dst_sel:DWORD dst_unused:UNUSED_PAD src0_sel:WORD_1
	v_pk_fma_f32 v[34:35], v[54:55], v[226:227], v[206:207] op_sel:[1,0,0]
	v_pk_fma_f32 v[206:207], v[36:37], v[136:137], v[92:93] op_sel_hi:[0,1,1]
	v_pk_fma_f32 v[206:207], v[40:41], v[98:99], v[206:207] op_sel_hi:[0,1,1]
	v_pk_fma_f32 v[206:207], v[44:45], v[210:211], v[206:207] op_sel_hi:[0,1,1]
	v_pk_fma_f32 v[206:207], v[48:49], v[214:215], v[206:207] op_sel_hi:[0,1,1]
	v_pk_fma_f32 v[206:207], v[52:53], v[218:219], v[206:207] op_sel_hi:[0,1,1]
	v_pk_fma_f32 v[214:215], v[56:57], v[226:227], v[206:207] op_sel_hi:[0,1,1]
	ds_read_b128 v[206:209], v172 offset:1536
	ds_read_b128 v[210:213], v172 offset:1552
	v_pk_fma_f32 v[226:227], v[176:177], v[226:227], v[224:225] op_sel_hi:[0,1,1]
	v_cvt_f32_f16_sdwa v37, v220 dst_sel:DWORD dst_unused:UNUSED_PAD src0_sel:WORD_1
	v_cvt_f32_f16_e32 v36, v220
	v_cvt_f32_f16_e32 v42, v221
	v_cvt_f32_f16_sdwa v45, v222 dst_sel:DWORD dst_unused:UNUSED_PAD src0_sel:WORD_1
	v_cvt_f32_f16_e32 v44, v222
	v_cvt_f32_f16_sdwa v47, v223 dst_sel:DWORD dst_unused:UNUSED_PAD src0_sel:WORD_1
	v_cvt_f32_f16_e32 v46, v223
	ds_read_b128 v[218:221], v172 offset:1792
	ds_read_b128 v[222:225], v172 offset:1808
	s_waitcnt vmcnt(0)
; __device__ __forceinline__ void dsa_item(const KP& p, int b, int tile, char* smem) {
;     ...
;       for (int g8 = 0; g8 < 4; ++g8) {
;         h8 vv[8];
; #pragma unroll
;         for (int i = 0; i < 8; ++i) {
;           const int pos = (g8 * 8 + i) * 8 + rs;
;           const int s = (pos < nsel) ? (int)sel[tk * 256 + pos] : 0;
;           vv[i] = *(const h8*)(ub + (size_t)s * NU + C_BV + dc * 8);
;         }
; #pragma unroll
;         for (int i = 0; i < 8; ++i) {
;           const int pos = (g8 * 8 + i) * 8 + rs;
;           const f32x4 pa = *(const f32x4*)&pbuf[pos * 8];
;           const f32x4 pb = *(const f32x4*)&pbuf[pos * 8 + 4];
;           float vf[8];
; #pragma unroll
;           for (int e = 0; e < 8; ++e) vf[e] = (float)vv[i][e];
; #pragma unroll
;           for (int e = 0; e < 8; ++e) {
;             acc[0][e] += pa[0] * vf[e]; acc[1][e] += pa[1] * vf[e]; acc[2][e] += pa[2] * vf[e]; acc[3][e] += pa[3] * vf[e];
;             acc[4][e] += pb[0] * vf[e]; acc[5][e] += pb[1] * vf[e]; acc[6][e] += pb[2] * vf[e]; acc[7][e] += pb[3] * vf[e];
;           }
;         }
	v_cvt_f32_f16_e32 v48, v232
	v_cvt_f32_f16_sdwa v49, v232 dst_sel:DWORD dst_unused:UNUSED_PAD src0_sel:WORD_1
	v_pk_fma_f32 v[124:125], v[66:67], v[174:175], v[124:125] op_sel_hi:[0,1,1]
	v_pk_fma_f32 v[116:117], v[66:67], v[174:175], v[116:117] op_sel:[1,0,0]
	v_pk_fma_f32 v[110:111], v[68:69], v[174:175], v[110:111] op_sel_hi:[0,1,1]
	v_pk_fma_f32 v[104:105], v[194:195], v[142:143], v[104:105] op_sel_hi:[0,1,1]
	v_cvt_f32_f16_e32 v232, v233
	v_cvt_f32_f16_sdwa v233, v233 dst_sel:DWORD dst_unused:UNUSED_PAD src0_sel:WORD_1
	v_pk_fma_f32 v[216:217], v[74:75], v[190:191], v[216:217] op_sel_hi:[0,1,1]
	v_pk_fma_f32 v[228:229], v[74:75], v[190:191], v[228:229] op_sel:[1,0,0]
	v_pk_fma_f32 v[128:129], v[76:77], v[190:191], v[128:129] op_sel_hi:[0,1,1]
	v_pk_fma_f32 v[134:135], v[50:51], v[190:191], v[134:135] op_sel_hi:[0,1,1]
	v_pk_fma_f32 v[130:131], v[50:51], v[190:191], v[130:131] op_sel:[1,0,0]
	v_pk_fma_f32 v[124:125], v[70:71], v[178:179], v[124:125] op_sel_hi:[0,1,1]
	v_pk_fma_f32 v[116:117], v[70:71], v[178:179], v[116:117] op_sel:[1,0,0]
	v_pk_fma_f32 v[110:111], v[72:73], v[178:179], v[110:111] op_sel_hi:[0,1,1]
	v_pk_fma_f32 v[104:105], v[196:197], v[174:175], v[104:105] op_sel_hi:[0,1,1]
	v_pk_fma_f32 v[118:119], v[50:51], v[180:181], v[118:119] op_sel_hi:[0,1,1]
	v_pk_fma_f32 v[112:113], v[50:51], v[180:181], v[112:113] op_sel:[1,0,0]
	v_cvt_f32_f16_e32 v50, v234
	v_cvt_f32_f16_sdwa v51, v234 dst_sel:DWORD dst_unused:UNUSED_PAD src0_sel:WORD_1
	v_pk_fma_f32 v[216:217], v[78:79], v[192:193], v[216:217] op_sel_hi:[0,1,1]
	v_pk_fma_f32 v[228:229], v[78:79], v[192:193], v[228:229] op_sel:[1,0,0]
	v_pk_fma_f32 v[128:129], v[80:81], v[192:193], v[128:129] op_sel_hi:[0,1,1]
	v_pk_fma_f32 v[120:121], v[200:201], v[190:191], v[120:121] op_sel_hi:[0,1,1]
	v_pk_fma_f32 v[122:123], v[52:53], v[190:191], v[122:123] op_sel_hi:[0,1,1]
	v_pk_fma_f32 v[124:125], v[74:75], v[180:181], v[124:125] op_sel_hi:[0,1,1]
	v_pk_fma_f32 v[116:117], v[74:75], v[180:181], v[116:117] op_sel:[1,0,0]
	v_pk_fma_f32 v[110:111], v[76:77], v[180:181], v[110:111] op_sel_hi:[0,1,1]
	v_pk_fma_f32 v[104:105], v[198:199], v[178:179], v[104:105] op_sel_hi:[0,1,1]
	s_waitcnt lgkmcnt(3)
	v_mov_b32_e32 v38, v209
	s_waitcnt lgkmcnt(2)
	v_mov_b32_e32 v40, v213
	v_cvt_f32_f16_e32 v234, v235
	v_cvt_f32_f16_sdwa v235, v235 dst_sel:DWORD dst_unused:UNUSED_PAD src0_sel:WORD_1
	v_pk_fma_f32 v[204:205], v[212:213], v[36:37], v[204:205] op_sel_hi:[0,1,1]
	v_pk_fma_f32 v[120:121], v[202:203], v[192:193], v[120:121] op_sel_hi:[0,1,1]
	v_pk_fma_f32 v[134:135], v[54:55], v[192:193], v[134:135] op_sel_hi:[0,1,1]
	v_pk_fma_f32 v[130:131], v[54:55], v[192:193], v[130:131] op_sel:[1,0,0]
	v_pk_fma_f32 v[122:123], v[56:57], v[192:193], v[122:123] op_sel_hi:[0,1,1]
	v_pk_fma_f32 v[132:133], v[176:177], v[192:193], v[132:133] op_sel_hi:[0,1,1]
	v_pk_fma_f32 v[114:115], v[158:159], v[180:181], v[114:115] op_sel_hi:[0,1,1]
	v_pk_fma_f32 v[124:125], v[78:79], v[188:189], v[124:125] op_sel_hi:[0,1,1]
	v_pk_fma_f32 v[116:117], v[78:79], v[188:189], v[116:117] op_sel:[1,0,0]
	v_pk_fma_f32 v[110:111], v[80:81], v[188:189], v[110:111] op_sel_hi:[0,1,1]
	v_pk_fma_f32 v[104:105], v[200:201], v[180:181], v[104:105] op_sel_hi:[0,1,1]
	v_pk_fma_f32 v[118:119], v[54:55], v[188:189], v[118:119] op_sel_hi:[0,1,1]
	v_pk_fma_f32 v[112:113], v[54:55], v[188:189], v[112:113] op_sel:[1,0,0]
	v_pk_fma_f32 v[52:53], v[206:207], v[36:37], v[148:149] op_sel_hi:[0,1,1]
	v_pk_fma_f32 v[54:55], v[206:207], v[36:37], v[152:153] op_sel:[1,0,0]
	v_pk_fma_f32 v[56:57], v[208:209], v[36:37], v[146:147] op_sel_hi:[0,1,1]
	v_pk_fma_f32 v[66:67], v[38:39], v[36:37], v[140:141] op_sel_hi:[0,1,1]
	v_pk_fma_f32 v[68:69], v[210:211], v[36:37], v[150:151] op_sel_hi:[0,1,1]
	v_pk_fma_f32 v[70:71], v[210:211], v[36:37], v[144:145] op_sel:[1,0,0]
	v_pk_fma_f32 v[36:37], v[40:41], v[36:37], v[138:139] op_sel_hi:[0,1,1]
	s_waitcnt lgkmcnt(1)
	v_mov_b32_e32 v72, v221
	s_waitcnt lgkmcnt(0)
; __device__ __forceinline__ void dsa_item(const KP& p, int b, int tile, char* smem) {
;     ...
;       for (int g8 = 0; g8 < 4; ++g8) {
;         h8 vv[8];
; #pragma unroll
;         for (int i = 0; i < 8; ++i) {
;           const int pos = (g8 * 8 + i) * 8 + rs;
;           const int s = (pos < nsel) ? (int)sel[tk * 256 + pos] : 0;
;           vv[i] = *(const h8*)(ub + (size_t)s * NU + C_BV + dc * 8);
;         }
; #pragma unroll
;         for (int i = 0; i < 8; ++i) {
;           const int pos = (g8 * 8 + i) * 8 + rs;
;           const f32x4 pa = *(const f32x4*)&pbuf[pos * 8];
;           const f32x4 pb = *(const f32x4*)&pbuf[pos * 8 + 4];
;           float vf[8];
; #pragma unroll
;           for (int e = 0; e < 8; ++e) vf[e] = (float)vv[i][e];
; #pragma unroll
;           for (int e = 0; e < 8; ++e) {
;             acc[0][e] += pa[0] * vf[e]; acc[1][e] += pa[1] * vf[e]; acc[2][e] += pa[2] * vf[e]; acc[3][e] += pa[3] * vf[e];
;             acc[4][e] += pb[0] * vf[e]; acc[5][e] += pb[1] * vf[e]; acc[6][e] += pb[2] * vf[e]; acc[7][e] += pb[3] * vf[e];
;           }
;         }
	v_mov_b32_e32 v74, v225
	v_pk_fma_f32 v[138:139], v[224:225], v[48:49], v[204:205] op_sel_hi:[0,1,1]
	v_pk_fma_f32 v[204:205], v[206:207], v[42:43], v[216:217] op_sel_hi:[0,1,1]
	v_pk_fma_f32 v[216:217], v[206:207], v[42:43], v[228:229] op_sel:[1,0,0]
	v_pk_fma_f32 v[228:229], v[208:209], v[42:43], v[128:129] op_sel_hi:[0,1,1]
	v_pk_fma_f32 v[104:105], v[202:203], v[188:189], v[104:105] op_sel_hi:[0,1,1]
	v_pk_fma_f32 v[114:115], v[176:177], v[188:189], v[114:115] op_sel_hi:[0,1,1]
	v_pk_fma_f32 v[154:155], v[218:219], v[48:49], v[52:53] op_sel_hi:[0,1,1]
	v_pk_fma_f32 v[152:153], v[218:219], v[48:49], v[54:55] op_sel:[1,0,0]
	v_pk_fma_f32 v[146:147], v[220:221], v[48:49], v[56:57] op_sel_hi:[0,1,1]
	v_pk_fma_f32 v[140:141], v[72:73], v[48:49], v[66:67] op_sel_hi:[0,1,1]
	v_pk_fma_f32 v[150:151], v[222:223], v[48:49], v[68:69] op_sel_hi:[0,1,1]
	v_pk_fma_f32 v[144:145], v[222:223], v[48:49], v[70:71] op_sel:[1,0,0]
	v_pk_fma_f32 v[148:149], v[74:75], v[48:49], v[36:37] op_sel_hi:[0,1,1]
	v_pk_fma_f32 v[36:37], v[38:39], v[42:43], v[120:121] op_sel_hi:[0,1,1]
	v_pk_fma_f32 v[48:49], v[210:211], v[42:43], v[134:135] op_sel_hi:[0,1,1]
	v_pk_fma_f32 v[52:53], v[210:211], v[42:43], v[130:131] op_sel:[1,0,0]
	v_pk_fma_f32 v[54:55], v[212:213], v[42:43], v[122:123] op_sel_hi:[0,1,1]
	v_pk_fma_f32 v[42:43], v[40:41], v[42:43], v[132:133] op_sel_hi:[0,1,1]
	v_pk_fma_f32 v[142:143], v[218:219], v[232:233], v[204:205] op_sel_hi:[0,1,1]
	v_pk_fma_f32 v[134:135], v[218:219], v[232:233], v[216:217] op_sel:[1,0,0]
	v_pk_fma_f32 v[128:129], v[220:221], v[232:233], v[228:229] op_sel_hi:[0,1,1]
	v_pk_fma_f32 v[204:205], v[206:207], v[44:45], v[124:125] op_sel_hi:[0,1,1]
	v_pk_fma_f32 v[216:217], v[206:207], v[44:45], v[116:117] op_sel:[1,0,0]
	v_pk_fma_f32 v[228:229], v[208:209], v[44:45], v[110:111] op_sel_hi:[0,1,1]
	v_pk_fma_f32 v[120:121], v[72:73], v[232:233], v[36:37] op_sel_hi:[0,1,1]
	v_pk_fma_f32 v[136:137], v[222:223], v[232:233], v[48:49] op_sel_hi:[0,1,1]
	v_pk_fma_f32 v[130:131], v[222:223], v[232:233], v[52:53] op_sel:[1,0,0]
	v_pk_fma_f32 v[122:123], v[224:225], v[232:233], v[54:55] op_sel_hi:[0,1,1]
	v_pk_fma_f32 v[132:133], v[74:75], v[232:233], v[42:43] op_sel_hi:[0,1,1]
	v_pk_fma_f32 v[232:233], v[38:39], v[44:45], v[104:105] op_sel_hi:[0,1,1]
	v_pk_fma_f32 v[36:37], v[210:211], v[44:45], v[118:119] op_sel_hi:[0,1,1]
	v_pk_fma_f32 v[42:43], v[210:211], v[44:45], v[112:113] op_sel:[1,0,0]
	v_pk_fma_f32 v[48:49], v[212:213], v[44:45], v[106:107] op_sel_hi:[0,1,1]
	v_pk_fma_f32 v[44:45], v[40:41], v[44:45], v[114:115] op_sel_hi:[0,1,1]
	v_pk_fma_f32 v[124:125], v[218:219], v[50:51], v[204:205] op_sel_hi:[0,1,1]
	v_pk_fma_f32 v[116:117], v[218:219], v[50:51], v[216:217] op_sel:[1,0,0]
	v_pk_fma_f32 v[110:111], v[220:221], v[50:51], v[228:229] op_sel_hi:[0,1,1]
	v_pk_fma_f32 v[204:205], v[206:207], v[46:47], v[230:231] op_sel_hi:[0,1,1]
	v_pk_fma_f32 v[206:207], v[206:207], v[46:47], v[58:59] op_sel:[1,0,0]
	v_pk_fma_f32 v[208:209], v[208:209], v[46:47], v[60:61] op_sel_hi:[0,1,1]
	v_pk_fma_f32 v[216:217], v[38:39], v[46:47], v[62:63] op_sel_hi:[0,1,1]
	v_pk_fma_f32 v[228:229], v[210:211], v[46:47], v[64:65] op_sel_hi:[0,1,1]
	v_pk_fma_f32 v[210:211], v[210:211], v[46:47], v[34:35] op_sel:[1,0,0]
	v_pk_fma_f32 v[212:213], v[212:213], v[46:47], v[214:215] op_sel_hi:[0,1,1]
	v_pk_fma_f32 v[214:215], v[40:41], v[46:47], v[226:227] op_sel_hi:[0,1,1]
	v_pk_fma_f32 v[104:105], v[72:73], v[50:51], v[232:233] op_sel_hi:[0,1,1]
	v_pk_fma_f32 v[118:119], v[222:223], v[50:51], v[36:37] op_sel_hi:[0,1,1]
	v_pk_fma_f32 v[112:113], v[222:223], v[50:51], v[42:43] op_sel:[1,0,0]
	v_pk_fma_f32 v[106:107], v[224:225], v[50:51], v[48:49] op_sel_hi:[0,1,1]
	v_pk_fma_f32 v[114:115], v[74:75], v[50:51], v[44:45] op_sel_hi:[0,1,1]
	v_pk_fma_f32 v[108:109], v[218:219], v[234:235], v[204:205] op_sel_hi:[0,1,1]
	v_pk_fma_f32 v[100:101], v[218:219], v[234:235], v[206:207] op_sel:[1,0,0]
	v_pk_fma_f32 v[94:95], v[220:221], v[234:235], v[208:209] op_sel_hi:[0,1,1]
	v_pk_fma_f32 v[90:91], v[72:73], v[234:235], v[216:217] op_sel_hi:[0,1,1]
	v_pk_fma_f32 v[102:103], v[222:223], v[234:235], v[228:229] op_sel_hi:[0,1,1]
	v_pk_fma_f32 v[96:97], v[222:223], v[234:235], v[210:211] op_sel:[1,0,0]
	v_pk_fma_f32 v[92:93], v[224:225], v[234:235], v[212:213] op_sel_hi:[0,1,1]
	v_pk_fma_f32 v[98:99], v[74:75], v[234:235], v[214:215] op_sel_hi:[0,1,1]
	v_add_u32_e32 v172, 0x800, v172
	s_branch .LBB0_1424
